# all four GEMM k-loops hand-rescheduled: barrier rotated before last k-slab, fragment reads behind MFMAs with counted lgkmcnt, SGPR-base direct-to-LDS loads issued a full k-step ahead
# speedup vs baseline: 1.0922x; 1.0372x over previous
.LBB0_22:
	s_add_i32 s2, s7, s8
	s_cmpk_gt_i32 s2, 0x1ff
	s_mov_b64 s[0:1], -1
	s_cbranch_scc1 .LBB0_21
	s_ashr_i32 s0, s2, 31
	s_lshr_b32 s0, s0, 27
	s_add_i32 s0, s2, s0
	s_and_b32 s1, s0, 0xffffffe0
	s_sub_i32 s1, s2, s1
	s_ashr_i32 s2, s1, 31
	s_lshr_b32 s2, s2, 29
	s_add_i32 s2, s1, s2
	s_and_b32 s3, s2, 0xfffff8
	s_sub_i32 s1, s1, s3
	s_lshl_b32 s0, s0, 6
	s_and_b32 s0, s0, 0xfffff800
	s_lshl_b32 s1, s1, 8
	s_add_i32 s0, s1, s0
	s_ashr_i32 s1, s0, 31
	s_lshl_b64 s[4:5], s[0:1], 12
	s_lshl_b32 s1, s2, 5
	s_and_b32 s2, s1, 0xffffff00
	s_ashr_i32 s3, s2, 31
	s_lshl_b64 s[10:11], s[2:3], 12
	s_add_u32 s12, s64, s4
	v_mov_b32_e32 v0, v138
	s_addc_u32 s13, s65, s5
	s_barrier
	v_readlane_b32 s14, v251, 22
	v_lshl_add_u64 v[2:3], v[0:1], 1, s[12:13]
	v_add_u32_e32 v0, 32, v139
	v_readlane_b32 s15, v251, 23
	v_readfirstlane_b32 s1, v0
	s_mov_b32 m0, s1
	v_mov_b32_e32 v0, v140
	global_load_lds_dwordx4 v[2:3], off
	s_add_u32 s14, s14, s10
	v_lshl_add_u64 v[2:3], v[0:1], 1, s[12:13]
	v_add_u32_e32 v0, 32, v141
	s_addc_u32 s15, s15, s11
	v_readfirstlane_b32 s1, v0
	s_mov_b32 m0, s1
	v_mov_b32_e32 v0, v142
	global_load_lds_dwordx4 v[2:3], off
	v_readlane_b32 s3, v254, 3
	v_lshl_add_u64 v[2:3], v[0:1], 1, s[12:13]
	v_add_u32_e32 v0, 32, v143
	s_mov_b32 s27, s51
	v_readfirstlane_b32 s1, v0
	s_mov_b32 m0, s1
	v_mov_b32_e32 v0, v144
	global_load_lds_dwordx4 v[2:3], off
	s_nop 0
	v_lshl_add_u64 v[2:3], v[0:1], 1, s[12:13]
	v_add_u32_e32 v0, 32, v145
	s_nop 0
	v_readfirstlane_b32 s1, v0
	s_mov_b32 m0, s1
	v_mov_b32_e32 v0, v138
	global_load_lds_dwordx4 v[2:3], off
	s_nop 0
	v_lshl_add_u64 v[2:3], v[0:1], 1, s[14:15]
	v_add_u32_e32 v0, s3, v139
	s_nop 0
	v_readfirstlane_b32 s1, v0
	s_mov_b32 m0, s1
	v_mov_b32_e32 v0, v140
	global_load_lds_dwordx4 v[2:3], off
	s_nop 0
	v_lshl_add_u64 v[2:3], v[0:1], 1, s[14:15]
	v_add_u32_e32 v0, s3, v141
	s_nop 0
	v_readfirstlane_b32 s1, v0
	s_mov_b32 m0, s1
	v_mov_b32_e32 v0, v142
	global_load_lds_dwordx4 v[2:3], off
	s_nop 0
	v_lshl_add_u64 v[2:3], v[0:1], 1, s[14:15]
	v_add_u32_e32 v0, s3, v143
	s_nop 0
	v_readfirstlane_b32 s1, v0
	s_mov_b32 m0, s1
	v_mov_b32_e32 v0, v144
	global_load_lds_dwordx4 v[2:3], off
	s_nop 0
	v_lshl_add_u64 v[2:3], v[0:1], 1, s[14:15]
	v_add_u32_e32 v0, s3, v145
	v_readlane_b32 s3, v253, 26
	v_readfirstlane_b32 s1, v0
	s_mov_b32 m0, s1
	v_readlane_b32 s1, v253, 25
	global_load_lds_dwordx4 v[2:3], off
	s_add_u32 s1, s1, s4
	s_waitcnt vmcnt(0)
	s_addc_u32 s3, s3, s5
	v_readlane_b32 s4, v253, 27
	s_add_u32 s9, s4, s10
	v_readlane_b32 s4, v253, 28
	v_mov_b32_e32 v2, 0
	s_addc_u32 s10, s4, s11
	s_mov_b64 s[4:5], 0
	s_mov_b32 s11, 0
	v_mov_b32_e32 v3, v2
	v_mov_b32_e32 v4, v2
	v_mov_b32_e32 v5, v2
	v_mov_b32_e32 v6, v2
	v_mov_b32_e32 v7, v2
	v_mov_b32_e32 v8, v2
	v_mov_b32_e32 v9, v2
	v_mov_b32_e32 v10, v2
	v_mov_b32_e32 v11, v2
	v_mov_b32_e32 v12, v2
	v_mov_b32_e32 v13, v2
	s_waitcnt vmcnt(0)
	v_mov_b32_e32 v14, v2
	v_mov_b32_e32 v15, v2
	v_mov_b32_e32 v16, v2
	v_mov_b32_e32 v17, v2
	v_mov_b32_e32 v18, v2
	v_mov_b32_e32 v19, v2
	v_mov_b32_e32 v20, v2
	v_mov_b32_e32 v21, v2
	v_mov_b32_e32 v22, v2
	v_mov_b32_e32 v23, v2
	v_mov_b32_e32 v24, v2
	v_mov_b32_e32 v25, v2
	v_mov_b32_e32 v26, v2
	v_mov_b32_e32 v27, v2
	v_mov_b32_e32 v28, v2
	v_mov_b32_e32 v29, v2
	v_mov_b32_e32 v30, v2
	v_mov_b32_e32 v31, v2
	v_mov_b32_e32 v32, v2
	v_mov_b32_e32 v33, v2
	v_mov_b32_e32 v34, v2
	v_mov_b32_e32 v35, v2
	v_mov_b32_e32 v36, v2
	v_mov_b32_e32 v37, v2
	v_mov_b32_e32 v38, v2
	v_mov_b32_e32 v39, v2
	v_mov_b32_e32 v40, v2
	v_mov_b32_e32 v41, v2
	v_mov_b32_e32 v42, v2
	v_mov_b32_e32 v43, v2
	v_mov_b32_e32 v44, v2
	v_mov_b32_e32 v45, v2
	v_mov_b32_e32 v46, v2
	v_mov_b32_e32 v47, v2
	v_mov_b32_e32 v48, v2
	v_mov_b32_e32 v49, v2
	v_mov_b32_e32 v50, v2
	v_mov_b32_e32 v51, v2
	v_mov_b32_e32 v52, v2
	v_mov_b32_e32 v53, v2
	v_mov_b32_e32 v54, v2
	v_mov_b32_e32 v55, v2
	v_mov_b32_e32 v56, v2
	v_mov_b32_e32 v57, v2
	v_mov_b32_e32 v58, v2
	v_mov_b32_e32 v59, v2
	v_mov_b32_e32 v60, v2
	v_mov_b32_e32 v61, v2
	v_mov_b32_e32 v62, v2
	v_mov_b32_e32 v63, v2
	v_mov_b32_e32 v64, v2
	v_mov_b32_e32 v65, v2
	v_mov_b32_e32 v66, v2
	v_mov_b32_e32 v67, v2
	v_mov_b32_e32 v68, v2
	v_mov_b32_e32 v69, v2
	v_mov_b32_e32 v70, v2
	v_mov_b32_e32 v71, v2
	v_mov_b32_e32 v72, v2
	v_mov_b32_e32 v73, v2
	v_mov_b32_e32 v74, v2
	v_mov_b32_e32 v75, v2
	v_mov_b32_e32 v76, v2
	v_mov_b32_e32 v77, v2
	v_mov_b32_e32 v78, v2
	v_mov_b32_e32 v79, v2
	v_mov_b32_e32 v80, v2
	v_mov_b32_e32 v81, v2
	v_mov_b32_e32 v82, v2
	v_mov_b32_e32 v83, v2
	v_mov_b32_e32 v84, v2
	v_mov_b32_e32 v85, v2
	v_mov_b32_e32 v86, v2
	v_mov_b32_e32 v87, v2
	v_mov_b32_e32 v88, v2
	v_mov_b32_e32 v89, v2
	v_mov_b32_e32 v90, v2
	v_mov_b32_e32 v91, v2
	v_mov_b32_e32 v92, v2
	v_mov_b32_e32 v93, v2
	v_mov_b32_e32 v94, v2
	v_mov_b32_e32 v95, v2
	v_mov_b32_e32 v96, v2
	v_mov_b32_e32 v97, v2
	v_mov_b32_e32 v98, v2
	v_mov_b32_e32 v99, v2
	v_mov_b32_e32 v100, v2
	v_mov_b32_e32 v101, v2
	v_mov_b32_e32 v102, v2
	v_mov_b32_e32 v103, v2
	v_mov_b32_e32 v104, v2
	v_mov_b32_e32 v105, v2
	v_mov_b32_e32 v106, v2
	v_mov_b32_e32 v107, v2
	v_mov_b32_e32 v108, v2
	v_mov_b32_e32 v109, v2
	v_mov_b32_e32 v110, v2
	v_mov_b32_e32 v111, v2
	v_mov_b32_e32 v112, v2
	v_mov_b32_e32 v113, v2
	v_mov_b32_e32 v114, v2
	v_mov_b32_e32 v115, v2
	v_mov_b32_e32 v116, v2
	v_mov_b32_e32 v117, v2
	v_mov_b32_e32 v118, v2
	v_mov_b32_e32 v119, v2
	v_mov_b32_e32 v120, v2
	v_mov_b32_e32 v121, v2
	v_mov_b32_e32 v122, v2
	v_mov_b32_e32 v123, v2
	v_mov_b32_e32 v124, v2
	v_mov_b32_e32 v125, v2
	v_mov_b32_e32 v126, v2
	v_mov_b32_e32 v127, v2
	v_mov_b32_e32 v128, v2
	v_mov_b32_e32 v129, v2
	s_waitcnt vmcnt(0) lgkmcnt(0)
	s_barrier
	v_lshlrev_b32_e32 v155, 1, v138
	v_readfirstlane_b32 s14, v139
	v_add_u32_e32 v177, v146, v148
	v_add_u32_e32 v207, v147, v148
	v_add_u32_e32 v204, v146, v152
	v_add_u32_e32 v208, v147, v152
	v_add_u32_e32 v205, v146, v153
	v_add_u32_e32 v209, v147, v153
	v_add_u32_e32 v206, v146, v154
	v_add_u32_e32 v210, v147, v154
	s_nop 1
	s_add_u32 m0, s14, 0x8020
	s_add_u32 s12, s1, s4
	s_addc_u32 s13, s3, s5
	global_load_lds_dwordx4 v155, s[12:13]
	s_add_u32 m0, s14, 0xa020
	s_add_u32 s12, s12, 0x40000
	s_addc_u32 s13, s13, 0
	global_load_lds_dwordx4 v155, s[12:13]
	s_add_u32 m0, s14, 0xc020
	s_add_u32 s12, s12, 0x40000
	s_addc_u32 s13, s13, 0
	global_load_lds_dwordx4 v155, s[12:13]
	s_add_u32 m0, s14, 0xe020
	s_add_u32 s12, s12, 0x40000
	s_addc_u32 s13, s13, 0
	global_load_lds_dwordx4 v155, s[12:13]
	s_add_u32 m0, s14, 0x18020
	s_add_u32 s12, s9, s4
	s_addc_u32 s13, s10, s5
	global_load_lds_dwordx4 v155, s[12:13]
	s_add_u32 m0, s14, 0x1a020
	s_add_u32 s12, s12, 0x40000
	s_addc_u32 s13, s13, 0
	global_load_lds_dwordx4 v155, s[12:13]
	s_add_u32 m0, s14, 0x1c020
	s_add_u32 s12, s12, 0x40000
	s_addc_u32 s13, s13, 0
	global_load_lds_dwordx4 v155, s[12:13]
	s_add_u32 m0, s14, 0x1e020
	s_add_u32 s12, s12, 0x40000
	s_addc_u32 s13, s13, 0
	global_load_lds_dwordx4 v155, s[12:13]
	s_add_u32 s4, s4, 0x80
	s_addc_u32 s5, s5, 0
	ds_read_b128 v[130:133], v177 offset:0
	ds_read_b128 v[164:167], v207 offset:0
	ds_read_b128 v[168:171], v207 offset:4096
	ds_read_b128 v[134:137], v177 offset:4096
	ds_read_b128 v[156:159], v177 offset:8192
	ds_read_b128 v[160:163], v177 offset:12288
.Lg24_loop:
	s_waitcnt lgkmcnt(4)
	v_mfma_f32_32x32x16_bf16 v[114:129], v[130:133], v[164:167], v[114:129]
	ds_read_b128 v[172:175], v204 offset:0
	s_waitcnt lgkmcnt(4)
	v_mfma_f32_32x32x16_bf16 v[98:113], v[130:133], v[168:171], v[98:113]
	ds_read_b128 v[192:195], v208 offset:0
	s_waitcnt lgkmcnt(4)
	v_mfma_f32_32x32x16_bf16 v[82:97], v[134:137], v[164:167], v[82:97]
	ds_read_b128 v[200:203], v208 offset:4096
	v_mfma_f32_32x32x16_bf16 v[66:81], v[134:137], v[168:171], v[66:81]
	ds_read_b128 v[180:183], v204 offset:4096
	s_waitcnt lgkmcnt(5)
	v_mfma_f32_32x32x16_bf16 v[50:65], v[156:159], v[164:167], v[50:65]
	ds_read_b128 v[184:187], v204 offset:8192
	v_mfma_f32_32x32x16_bf16 v[34:49], v[156:159], v[168:171], v[34:49]
	ds_read_b128 v[188:191], v204 offset:12288
	s_waitcnt lgkmcnt(6)
	v_mfma_f32_32x32x16_bf16 v[18:33], v[160:163], v[164:167], v[18:33]
	v_mfma_f32_32x32x16_bf16 v[2:17], v[160:163], v[168:171], v[2:17]
	s_waitcnt lgkmcnt(4)
	v_mfma_f32_32x32x16_bf16 v[114:129], v[172:175], v[192:195], v[114:129]
	ds_read_b128 v[130:133], v205 offset:0
	s_waitcnt lgkmcnt(4)
	v_mfma_f32_32x32x16_bf16 v[98:113], v[172:175], v[200:203], v[98:113]
	ds_read_b128 v[164:167], v209 offset:0
	s_waitcnt lgkmcnt(4)
	v_mfma_f32_32x32x16_bf16 v[82:97], v[180:183], v[192:195], v[82:97]
	ds_read_b128 v[168:171], v209 offset:4096
	v_mfma_f32_32x32x16_bf16 v[66:81], v[180:183], v[200:203], v[66:81]
	ds_read_b128 v[134:137], v205 offset:4096
	s_waitcnt lgkmcnt(5)
	v_mfma_f32_32x32x16_bf16 v[50:65], v[184:187], v[192:195], v[50:65]
	ds_read_b128 v[156:159], v205 offset:8192
	v_mfma_f32_32x32x16_bf16 v[34:49], v[184:187], v[200:203], v[34:49]
	ds_read_b128 v[160:163], v205 offset:12288
	s_waitcnt lgkmcnt(6)
	v_mfma_f32_32x32x16_bf16 v[18:33], v[188:191], v[192:195], v[18:33]
	v_mfma_f32_32x32x16_bf16 v[2:17], v[188:191], v[200:203], v[2:17]
	s_waitcnt lgkmcnt(4)
	v_mfma_f32_32x32x16_bf16 v[114:129], v[130:133], v[164:167], v[114:129]
	ds_read_b128 v[172:175], v206 offset:0
	ds_read_b128 v[192:195], v210 offset:0
	s_waitcnt lgkmcnt(5)
	v_mfma_f32_32x32x16_bf16 v[98:113], v[130:133], v[168:171], v[98:113]
	ds_read_b128 v[200:203], v210 offset:4096
	ds_read_b128 v[180:183], v206 offset:4096
	s_waitcnt lgkmcnt(6)
	v_mfma_f32_32x32x16_bf16 v[82:97], v[134:137], v[164:167], v[82:97]
	ds_read_b128 v[184:187], v206 offset:8192
	ds_read_b128 v[188:191], v206 offset:12288
	v_mfma_f32_32x32x16_bf16 v[66:81], v[134:137], v[168:171], v[66:81]
	s_waitcnt lgkmcnt(7)
	v_mfma_f32_32x32x16_bf16 v[50:65], v[156:159], v[164:167], v[50:65]
	v_mfma_f32_32x32x16_bf16 v[34:49], v[156:159], v[168:171], v[34:49]
	s_waitcnt lgkmcnt(6)
	v_mfma_f32_32x32x16_bf16 v[18:33], v[160:163], v[164:167], v[18:33]
	v_mfma_f32_32x32x16_bf16 v[2:17], v[160:163], v[168:171], v[2:17]
	s_waitcnt vmcnt(0) lgkmcnt(0)
	s_barrier
	s_cmp_lt_u32 s4, 0xf80
	s_cbranch_scc0 .Lg24_nodma0
	v_mfma_f32_32x32x16_bf16 v[114:129], v[172:175], v[192:195], v[114:129]
	ds_read_b128 v[130:133], v177 offset:32768
	s_add_u32 m0, s14, 0x20
	s_add_u32 s12, s1, s4
	s_addc_u32 s13, s3, s5
	global_load_lds_dwordx4 v155, s[12:13]
	v_mfma_f32_32x32x16_bf16 v[98:113], v[172:175], v[200:203], v[98:113]
	ds_read_b128 v[164:167], v207 offset:32768
	s_add_u32 m0, s14, 0x2020
	s_add_u32 s12, s12, 0x40000
	s_addc_u32 s13, s13, 0
	global_load_lds_dwordx4 v155, s[12:13]
	v_mfma_f32_32x32x16_bf16 v[82:97], v[180:183], v[192:195], v[82:97]
	ds_read_b128 v[168:171], v207 offset:36864
	s_add_u32 m0, s14, 0x4020
	s_add_u32 s12, s12, 0x40000
	s_addc_u32 s13, s13, 0
	global_load_lds_dwordx4 v155, s[12:13]
	v_mfma_f32_32x32x16_bf16 v[66:81], v[180:183], v[200:203], v[66:81]
	ds_read_b128 v[134:137], v177 offset:36864
	s_add_u32 m0, s14, 0x6020
	s_add_u32 s12, s12, 0x40000
	s_addc_u32 s13, s13, 0
	global_load_lds_dwordx4 v155, s[12:13]
	v_mfma_f32_32x32x16_bf16 v[50:65], v[184:187], v[192:195], v[50:65]
	ds_read_b128 v[156:159], v177 offset:40960
	s_add_u32 m0, s14, 0x10020
	s_add_u32 s12, s9, s4
	s_addc_u32 s13, s10, s5
	global_load_lds_dwordx4 v155, s[12:13]
	v_mfma_f32_32x32x16_bf16 v[34:49], v[184:187], v[200:203], v[34:49]
	ds_read_b128 v[160:163], v177 offset:45056
	s_add_u32 m0, s14, 0x12020
	s_add_u32 s12, s12, 0x40000
	s_addc_u32 s13, s13, 0
	global_load_lds_dwordx4 v155, s[12:13]
	v_mfma_f32_32x32x16_bf16 v[18:33], v[188:191], v[192:195], v[18:33]
	s_add_u32 m0, s14, 0x14020
	s_add_u32 s12, s12, 0x40000
	s_addc_u32 s13, s13, 0
	global_load_lds_dwordx4 v155, s[12:13]
	v_mfma_f32_32x32x16_bf16 v[2:17], v[188:191], v[200:203], v[2:17]
	s_add_u32 m0, s14, 0x16020
	s_add_u32 s12, s12, 0x40000
	s_addc_u32 s13, s13, 0
	global_load_lds_dwordx4 v155, s[12:13]
	s_add_u32 s4, s4, 0x80
	s_addc_u32 s5, s5, 0
	s_branch .Lg24_join0
.Lg24_nodma0:
	s_add_u32 s4, s4, 0x80
	s_addc_u32 s5, s5, 0
	v_mfma_f32_32x32x16_bf16 v[114:129], v[172:175], v[192:195], v[114:129]
	ds_read_b128 v[130:133], v177 offset:32768
	v_mfma_f32_32x32x16_bf16 v[98:113], v[172:175], v[200:203], v[98:113]
	ds_read_b128 v[164:167], v207 offset:32768
	v_mfma_f32_32x32x16_bf16 v[82:97], v[180:183], v[192:195], v[82:97]
	ds_read_b128 v[168:171], v207 offset:36864
	v_mfma_f32_32x32x16_bf16 v[66:81], v[180:183], v[200:203], v[66:81]
	ds_read_b128 v[134:137], v177 offset:36864
	v_mfma_f32_32x32x16_bf16 v[50:65], v[184:187], v[192:195], v[50:65]
	ds_read_b128 v[156:159], v177 offset:40960
	v_mfma_f32_32x32x16_bf16 v[34:49], v[184:187], v[200:203], v[34:49]
	ds_read_b128 v[160:163], v177 offset:45056
	v_mfma_f32_32x32x16_bf16 v[18:33], v[188:191], v[192:195], v[18:33]
	v_mfma_f32_32x32x16_bf16 v[2:17], v[188:191], v[200:203], v[2:17]
.Lg24_join0:
	s_waitcnt lgkmcnt(4)
	v_mfma_f32_32x32x16_bf16 v[114:129], v[130:133], v[164:167], v[114:129]
	ds_read_b128 v[172:175], v204 offset:32768
	s_waitcnt lgkmcnt(4)
	v_mfma_f32_32x32x16_bf16 v[98:113], v[130:133], v[168:171], v[98:113]
	ds_read_b128 v[192:195], v208 offset:32768
	s_waitcnt lgkmcnt(4)
	v_mfma_f32_32x32x16_bf16 v[82:97], v[134:137], v[164:167], v[82:97]
	ds_read_b128 v[200:203], v208 offset:36864
	v_mfma_f32_32x32x16_bf16 v[66:81], v[134:137], v[168:171], v[66:81]
	ds_read_b128 v[180:183], v204 offset:36864
	s_waitcnt lgkmcnt(5)
	v_mfma_f32_32x32x16_bf16 v[50:65], v[156:159], v[164:167], v[50:65]
	ds_read_b128 v[184:187], v204 offset:40960
	v_mfma_f32_32x32x16_bf16 v[34:49], v[156:159], v[168:171], v[34:49]
	ds_read_b128 v[188:191], v204 offset:45056
	s_waitcnt lgkmcnt(6)
	v_mfma_f32_32x32x16_bf16 v[18:33], v[160:163], v[164:167], v[18:33]
	v_mfma_f32_32x32x16_bf16 v[2:17], v[160:163], v[168:171], v[2:17]
	s_waitcnt lgkmcnt(4)
	v_mfma_f32_32x32x16_bf16 v[114:129], v[172:175], v[192:195], v[114:129]
	ds_read_b128 v[130:133], v205 offset:32768
	s_waitcnt lgkmcnt(4)
	v_mfma_f32_32x32x16_bf16 v[98:113], v[172:175], v[200:203], v[98:113]
	ds_read_b128 v[164:167], v209 offset:32768
	s_waitcnt lgkmcnt(4)
	v_mfma_f32_32x32x16_bf16 v[82:97], v[180:183], v[192:195], v[82:97]
	ds_read_b128 v[168:171], v209 offset:36864
	v_mfma_f32_32x32x16_bf16 v[66:81], v[180:183], v[200:203], v[66:81]
	ds_read_b128 v[134:137], v205 offset:36864
	s_waitcnt lgkmcnt(5)
	v_mfma_f32_32x32x16_bf16 v[50:65], v[184:187], v[192:195], v[50:65]
	ds_read_b128 v[156:159], v205 offset:40960
	v_mfma_f32_32x32x16_bf16 v[34:49], v[184:187], v[200:203], v[34:49]
	ds_read_b128 v[160:163], v205 offset:45056
	s_waitcnt lgkmcnt(6)
	v_mfma_f32_32x32x16_bf16 v[18:33], v[188:191], v[192:195], v[18:33]
	v_mfma_f32_32x32x16_bf16 v[2:17], v[188:191], v[200:203], v[2:17]
	s_waitcnt lgkmcnt(4)
	v_mfma_f32_32x32x16_bf16 v[114:129], v[130:133], v[164:167], v[114:129]
	ds_read_b128 v[172:175], v206 offset:32768
	ds_read_b128 v[192:195], v210 offset:32768
	s_waitcnt lgkmcnt(5)
	v_mfma_f32_32x32x16_bf16 v[98:113], v[130:133], v[168:171], v[98:113]
	ds_read_b128 v[200:203], v210 offset:36864
	ds_read_b128 v[180:183], v206 offset:36864
	s_waitcnt lgkmcnt(6)
	v_mfma_f32_32x32x16_bf16 v[82:97], v[134:137], v[164:167], v[82:97]
	ds_read_b128 v[184:187], v206 offset:40960
	ds_read_b128 v[188:191], v206 offset:45056
	v_mfma_f32_32x32x16_bf16 v[66:81], v[134:137], v[168:171], v[66:81]
	s_waitcnt lgkmcnt(7)
	v_mfma_f32_32x32x16_bf16 v[50:65], v[156:159], v[164:167], v[50:65]
	v_mfma_f32_32x32x16_bf16 v[34:49], v[156:159], v[168:171], v[34:49]
	s_waitcnt lgkmcnt(6)
	v_mfma_f32_32x32x16_bf16 v[18:33], v[160:163], v[164:167], v[18:33]
	v_mfma_f32_32x32x16_bf16 v[2:17], v[160:163], v[168:171], v[2:17]
	s_waitcnt vmcnt(0) lgkmcnt(0)
	s_barrier
	s_cmp_lt_u32 s4, 0xf80
	s_cbranch_scc0 .Lg24_nodma1
	v_mfma_f32_32x32x16_bf16 v[114:129], v[172:175], v[192:195], v[114:129]
	ds_read_b128 v[130:133], v177 offset:0
	s_add_u32 m0, s14, 0x8020
	s_add_u32 s12, s1, s4
	s_addc_u32 s13, s3, s5
	global_load_lds_dwordx4 v155, s[12:13]
	v_mfma_f32_32x32x16_bf16 v[98:113], v[172:175], v[200:203], v[98:113]
	ds_read_b128 v[164:167], v207 offset:0
	s_add_u32 m0, s14, 0xa020
	s_add_u32 s12, s12, 0x40000
	s_addc_u32 s13, s13, 0
	global_load_lds_dwordx4 v155, s[12:13]
	v_mfma_f32_32x32x16_bf16 v[82:97], v[180:183], v[192:195], v[82:97]
	ds_read_b128 v[168:171], v207 offset:4096
	s_add_u32 m0, s14, 0xc020
	s_add_u32 s12, s12, 0x40000
	s_addc_u32 s13, s13, 0
	global_load_lds_dwordx4 v155, s[12:13]
	v_mfma_f32_32x32x16_bf16 v[66:81], v[180:183], v[200:203], v[66:81]
	ds_read_b128 v[134:137], v177 offset:4096
	s_add_u32 m0, s14, 0xe020
	s_add_u32 s12, s12, 0x40000
	s_addc_u32 s13, s13, 0
	global_load_lds_dwordx4 v155, s[12:13]
	v_mfma_f32_32x32x16_bf16 v[50:65], v[184:187], v[192:195], v[50:65]
	ds_read_b128 v[156:159], v177 offset:8192
	s_add_u32 m0, s14, 0x18020
	s_add_u32 s12, s9, s4
	s_addc_u32 s13, s10, s5
	global_load_lds_dwordx4 v155, s[12:13]
	v_mfma_f32_32x32x16_bf16 v[34:49], v[184:187], v[200:203], v[34:49]
	ds_read_b128 v[160:163], v177 offset:12288
	s_add_u32 m0, s14, 0x1a020
	s_add_u32 s12, s12, 0x40000
	s_addc_u32 s13, s13, 0
	global_load_lds_dwordx4 v155, s[12:13]
	v_mfma_f32_32x32x16_bf16 v[18:33], v[188:191], v[192:195], v[18:33]
	s_add_u32 m0, s14, 0x1c020
	s_add_u32 s12, s12, 0x40000
	s_addc_u32 s13, s13, 0
	global_load_lds_dwordx4 v155, s[12:13]
	v_mfma_f32_32x32x16_bf16 v[2:17], v[188:191], v[200:203], v[2:17]
	s_add_u32 m0, s14, 0x1e020
	s_add_u32 s12, s12, 0x40000
	s_addc_u32 s13, s13, 0
	global_load_lds_dwordx4 v155, s[12:13]
	s_add_u32 s4, s4, 0x80
	s_addc_u32 s5, s5, 0
	s_branch .Lg24_join1
.Lg24_nodma1:
	s_add_u32 s4, s4, 0x80
	s_addc_u32 s5, s5, 0
	v_mfma_f32_32x32x16_bf16 v[114:129], v[172:175], v[192:195], v[114:129]
	ds_read_b128 v[130:133], v177 offset:0
	v_mfma_f32_32x32x16_bf16 v[98:113], v[172:175], v[200:203], v[98:113]
	ds_read_b128 v[164:167], v207 offset:0
	v_mfma_f32_32x32x16_bf16 v[82:97], v[180:183], v[192:195], v[82:97]
	ds_read_b128 v[168:171], v207 offset:4096
	v_mfma_f32_32x32x16_bf16 v[66:81], v[180:183], v[200:203], v[66:81]
	ds_read_b128 v[134:137], v177 offset:4096
	v_mfma_f32_32x32x16_bf16 v[50:65], v[184:187], v[192:195], v[50:65]
	ds_read_b128 v[156:159], v177 offset:8192
	v_mfma_f32_32x32x16_bf16 v[34:49], v[184:187], v[200:203], v[34:49]
	ds_read_b128 v[160:163], v177 offset:12288
	v_mfma_f32_32x32x16_bf16 v[18:33], v[188:191], v[192:195], v[18:33]
	v_mfma_f32_32x32x16_bf16 v[2:17], v[188:191], v[200:203], v[2:17]
.Lg24_join1:
	s_cmp_lt_u32 s4, 0x1080
	s_cbranch_scc1 .Lg24_loop
	s_waitcnt lgkmcnt(0)
	v_add_u32_e32 v130, s0, v149
	v_ashrrev_i32_e32 v131, 31, v130
	v_lshrrev_b32_e32 v155, 18, v131
	v_add_u32_e32 v0, v130, v155
	v_ashrrev_i32_e32 v0, 14, v0
	v_mul_i32_i24_e32 v133, 0x4000, v0
	v_sub_u32_e32 v133, v130, v133
	v_add_u32_e32 v156, 0x100, v133
	v_mul_hi_i32_i24_e32 v137, 0x4100, v0
	v_mul_i32_i24_e32 v136, 0x4100, v0
	v_ashrrev_i32_e32 v157, 31, v156
	v_lshl_add_u64 v[136:137], v[136:137], 0, v[156:157]
	v_mov_b32_e32 v156, v179
	s_waitcnt vmcnt(0)
	s_barrier
	v_mul_i32_i24_e32 v134, 0xc00, v0
	v_readlane_b32 s40, v251, 2
	v_and_b32_e32 v0, 31, v156
	v_bfe_u32 v133, v156, 5, 1
	v_mul_u32_u24_e32 v133, 0x240, v133
	v_lshlrev_b32_e32 v0, 2, v0
	v_add3_u32 v0, v151, v133, v0
	ds_write2_b32 v0, v114, v115 offset1:36
	ds_write2_b32 v0, v116, v117 offset0:72 offset1:108
	v_add_u32_e32 v114, 0x400, v0
	v_or_b32_e32 v132, s2, v150
	ds_write2_b32 v114, v118, v119 offset0:32 offset1:68
	ds_write2_b32 v114, v120, v121 offset0:104 offset1:140
	v_add_u32_e32 v114, 0x800, v0
	v_add_u32_e32 v0, 0xc00, v0
	v_readlane_b32 s41, v251, 3
	v_readlane_b32 s42, v251, 4
	v_readlane_b32 s43, v251, 5
	v_readlane_b32 s44, v251, 6
	v_readlane_b32 s45, v251, 7
	v_readlane_b32 s46, v251, 8
	v_readlane_b32 s47, v251, 9
	v_readlane_b32 s48, v251, 10
	v_readlane_b32 s49, v251, 11
	v_readlane_b32 s50, v251, 12
	v_readlane_b32 s51, v251, 13
	v_readlane_b32 s0, v251, 26
	v_ashrrev_i32_e32 v135, 31, v134
	v_lshlrev_b64 v[136:137], 11, v[136:137]
	ds_write2_b32 v114, v122, v123 offset0:64 offset1:100
	ds_write2_b32 v114, v124, v125 offset0:136 offset1:172
	ds_write2_b32 v0, v126, v127 offset0:96 offset1:132
	ds_write2_b32 v0, v128, v129 offset0:168 offset1:204
	v_readlane_b32 s54, v251, 16
	v_readlane_b32 s55, v251, 17
	v_ashrrev_i32_e32 v133, 31, v132
	v_readlane_b32 s1, v251, 27
	v_readlane_b32 s36, v253, 47
	v_lshlrev_b32_e32 v0, 2, v156
	v_readlane_b32 s52, v251, 14
	v_readlane_b32 s53, v251, 15
	v_lshl_add_u64 v[114:115], v[134:135], 2, s[54:55]
	s_mov_b64 s[2:3], 0x1b0b000
	v_lshl_add_u64 v[118:119], s[0:1], 0, v[136:137]
	v_lshlrev_b64 v[116:117], 1, v[132:133]
	v_lshlrev_b64 v[122:123], 12, v[130:131]
	v_readlane_b32 s37, v253, 48
	v_and_b32_e32 v128, 28, v0
	v_lshl_add_u64 v[120:121], v[114:115], 0, s[2:3]
	v_lshlrev_b64 v[114:115], 2, v[132:133]
	v_lshl_add_u64 v[118:119], v[118:119], 0, v[116:117]
	v_lshl_add_u64 v[124:125], s[36:37], 0, v[122:123]
	v_lshl_add_u64 v[122:123], s[52:53], 0, v[122:123]
	v_lshlrev_b32_e32 v0, 2, v128
	v_lshlrev_b32_e32 v128, 1, v128
	v_mov_b32_e32 v129, v1
	v_bfe_u32 v133, v156, 3, 3
	v_lshl_add_u64 v[126:127], v[120:121], 0, v[114:115]
	v_lshl_add_u64 v[124:125], v[124:125], 0, v[114:115]
	v_lshl_add_u64 v[122:123], v[122:123], 0, v[114:115]
	v_lshl_add_u64 v[134:135], v[118:119], 0, v[128:129]
	v_mul_u32_u24_e32 v131, 0x90, v133
	v_lshlrev_b32_e32 v156, 11, v133
	v_mov_b32_e32 v157, v1
	s_waitcnt lgkmcnt(0)
	v_lshl_add_u64 v[126:127], v[126:127], 0, v[0:1]
	v_lshl_add_u64 v[136:137], v[124:125], 0, v[0:1]
	v_lshl_add_u64 v[128:129], v[122:123], 0, v[0:1]
	v_add3_u32 v131, v151, v0, v131
	v_lshlrev_b32_e32 v0, 12, v133
	v_lshl_add_u64 v[156:157], v[134:135], 0, v[156:157]
	v_lshl_add_u64 v[164:165], v[136:137], 0, v[0:1]
	global_load_dwordx2 v[168:169], v[156:157], off
	ds_read_b128 v[156:159], v131
	global_load_dwordx4 v[160:163], v[126:127], off
	s_nop 0
	global_load_dwordx4 v[164:167], v[164:165], off
	v_lshl_add_u64 v[170:171], v[128:129], 0, v[0:1]
	v_readlane_b32 s38, v253, 49
	v_readlane_b32 s39, v253, 50
	v_readlane_b32 s42, v253, 53
	v_readlane_b32 s43, v253, 54
	v_readlane_b32 s44, v253, 55
	v_readlane_b32 s45, v253, 56
	v_readlane_b32 s46, v253, 57
	v_readlane_b32 s47, v253, 58
	v_readlane_b32 s48, v253, 59
	v_readlane_b32 s49, v253, 60
	v_readlane_b32 s51, v253, 62
	v_readlane_b32 s40, v253, 51
	v_readlane_b32 s41, v253, 52
	v_readlane_b32 s50, v253, 61
	s_waitcnt vmcnt(2)
	v_and_b32_e32 v173, 0xffff0000, v168
	v_lshlrev_b32_e32 v172, 16, v168
	s_waitcnt vmcnt(0)
	v_pk_add_f32 v[164:165], v[164:165], v[172:173]
	s_waitcnt lgkmcnt(0)
	v_pk_fma_f32 v[156:157], v[156:157], v[160:161], v[164:165]
	v_and_b32_e32 v161, 0xffff0000, v169
	v_lshlrev_b32_e32 v160, 16, v169
	v_pk_add_f32 v[160:161], v[166:167], v[160:161]
	s_nop 0
	v_pk_fma_f32 v[158:159], v[158:159], v[162:163], v[160:161]
	global_store_dwordx4 v[170:171], v[156:159], off
	s_nop 1
	v_or_b32_e32 v156, 8, v133
	v_lshlrev_b32_e32 v0, 12, v156
	v_lshlrev_b32_e32 v156, 11, v156
	v_mov_b32_e32 v157, v1
	v_lshl_add_u64 v[156:157], v[134:135], 0, v[156:157]
	v_lshl_add_u64 v[164:165], v[136:137], 0, v[0:1]
	global_load_dwordx2 v[168:169], v[156:157], off
	ds_read_b128 v[156:159], v131 offset:1152
	global_load_dwordx4 v[160:163], v[126:127], off
	s_nop 0
	global_load_dwordx4 v[164:167], v[164:165], off
	v_lshl_add_u64 v[170:171], v[128:129], 0, v[0:1]
	v_or_b32_e32 v0, 16, v133
	s_waitcnt vmcnt(2)
	v_and_b32_e32 v173, 0xffff0000, v168
	v_lshlrev_b32_e32 v172, 16, v168
	s_waitcnt vmcnt(0)
	v_pk_add_f32 v[164:165], v[164:165], v[172:173]
	s_waitcnt lgkmcnt(0)
	v_pk_fma_f32 v[156:157], v[156:157], v[160:161], v[164:165]
	v_and_b32_e32 v161, 0xffff0000, v169
	v_lshlrev_b32_e32 v160, 16, v169
	v_pk_add_f32 v[160:161], v[166:167], v[160:161]
	s_nop 0
	v_pk_fma_f32 v[158:159], v[158:159], v[162:163], v[160:161]
	global_store_dwordx4 v[170:171], v[156:159], off
	s_nop 1
	v_lshlrev_b32_e32 v158, 11, v0
	v_mov_b32_e32 v159, v1
	v_lshlrev_b32_e32 v156, 12, v0
	v_mov_b32_e32 v157, v1
	v_lshl_add_u64 v[158:159], v[134:135], 0, v[158:159]
	v_lshl_add_u64 v[164:165], v[136:137], 0, v[156:157]
	global_load_dwordx2 v[168:169], v[158:159], off
	v_lshl_add_u64 v[170:171], v[128:129], 0, v[156:157]
	ds_read_b128 v[156:159], v131 offset:2304
	global_load_dwordx4 v[160:163], v[126:127], off
	s_nop 0
	global_load_dwordx4 v[164:167], v[164:165], off
	v_or_b32_e32 v0, 24, v133
	s_waitcnt vmcnt(2)
	v_and_b32_e32 v173, 0xffff0000, v168
	v_lshlrev_b32_e32 v172, 16, v168
	s_waitcnt vmcnt(0)
	v_pk_add_f32 v[164:165], v[164:165], v[172:173]
	s_waitcnt lgkmcnt(0)
	v_pk_fma_f32 v[156:157], v[156:157], v[160:161], v[164:165]
	v_and_b32_e32 v161, 0xffff0000, v169
	v_lshlrev_b32_e32 v160, 16, v169
	v_pk_add_f32 v[160:161], v[166:167], v[160:161]
	s_nop 0
	v_pk_fma_f32 v[158:159], v[158:159], v[162:163], v[160:161]
	global_store_dwordx4 v[170:171], v[156:159], off
	s_nop 1
	v_lshlrev_b32_e32 v156, 12, v0
	v_mov_b32_e32 v157, v1
	v_lshl_add_u64 v[158:159], v[136:137], 0, v[156:157]
	v_lshlrev_b32_e32 v136, 11, v0
	v_mov_b32_e32 v137, v1
	v_lshl_add_u64 v[134:135], v[134:135], 0, v[136:137]
	global_load_dwordx2 v[160:161], v[134:135], off
	v_lshl_add_u64 v[162:163], v[128:129], 0, v[156:157]
	ds_read_b128 v[134:137], v131 offset:3456
	global_load_dwordx4 v[126:129], v[126:127], off
	s_nop 0
	global_load_dwordx4 v[156:159], v[158:159], off
	s_waitcnt vmcnt(2)
	v_and_b32_e32 v165, 0xffff0000, v160
	v_lshlrev_b32_e32 v164, 16, v160
	s_waitcnt vmcnt(0)
	v_pk_add_f32 v[156:157], v[156:157], v[164:165]
	s_waitcnt lgkmcnt(0)
	v_pk_fma_f32 v[126:127], v[134:135], v[126:127], v[156:157]
	v_and_b32_e32 v135, 0xffff0000, v161
	v_lshlrev_b32_e32 v134, 16, v161
	v_pk_add_f32 v[134:135], v[158:159], v[134:135]
	s_nop 0
	v_pk_fma_f32 v[128:129], v[136:137], v[128:129], v[134:135]
	global_store_dwordx4 v[162:163], v[126:129], off
	v_mov_b32_e32 v0, v179
	s_nop 0
	v_or_b32_e32 v126, 32, v132
	v_and_b32_e32 v127, 31, v0
	v_bfe_u32 v128, v0, 5, 1
	v_mul_u32_u24_e32 v128, 0x240, v128
	v_lshlrev_b32_e32 v127, 2, v127
	v_add3_u32 v127, v151, v128, v127
	ds_write2_b32 v127, v98, v99 offset1:36
	ds_write2_b32 v127, v100, v101 offset0:72 offset1:108
	v_add_u32_e32 v98, 0x400, v127
	ds_write2_b32 v98, v102, v103 offset0:32 offset1:68
	ds_write2_b32 v98, v104, v105 offset0:104 offset1:140
	v_add_u32_e32 v98, 0x800, v127
	ds_write2_b32 v98, v106, v107 offset0:64 offset1:100
	ds_write2_b32 v98, v108, v109 offset0:136 offset1:172
	v_add_u32_e32 v98, 0xc00, v127
	ds_write2_b32 v98, v110, v111 offset0:96 offset1:132
	ds_write2_b32 v98, v112, v113 offset0:168 offset1:204
	v_lshlrev_b32_e32 v98, 2, v0
	v_and_b32_e32 v102, 28, v98
	v_lshlrev_b32_e32 v108, 2, v102
	v_lshlrev_b32_e32 v102, 1, v102
	v_mov_b32_e32 v103, v1
	v_bfe_u32 v131, v0, 3, 3
	v_ashrrev_i32_e32 v127, 31, v126
	v_mov_b32_e32 v109, v1
	v_lshl_add_u64 v[104:105], v[118:119], 0, v[102:103]
	v_lshlrev_b32_e32 v110, 11, v131
	v_mov_b32_e32 v111, v1
	s_waitcnt lgkmcnt(0)
	v_lshl_add_u64 v[100:101], v[120:121], 0, v[108:109]
	v_lshlrev_b64 v[98:99], 2, v[126:127]
	v_mul_u32_u24_e32 v0, 0x90, v131
	v_lshl_add_u64 v[110:111], v[104:105], 0, v[110:111]
	v_lshl_add_u64 v[100:101], v[100:101], 0, v[98:99]
	v_lshl_add_u64 v[106:107], v[124:125], 0, v[108:109]
	v_lshl_add_u64 v[102:103], v[122:123], 0, v[108:109]
	v_add3_u32 v0, v151, v108, v0
	v_lshlrev_b32_e32 v108, 12, v131
	global_load_dwordx2 v[126:127], v[110:111], off offset:64
	v_lshl_add_u64 v[112:113], v[106:107], 0, v[108:109]
	v_lshl_add_u64 v[128:129], v[102:103], 0, v[108:109]
	ds_read_b128 v[108:111], v0
	global_load_dwordx4 v[118:121], v[100:101], off
	global_load_dwordx4 v[122:125], v[112:113], off offset:128
	s_waitcnt vmcnt(2)
	v_and_b32_e32 v113, 0xffff0000, v126
	v_lshlrev_b32_e32 v112, 16, v126
	s_waitcnt vmcnt(0)
	v_pk_add_f32 v[112:113], v[122:123], v[112:113]
	s_waitcnt lgkmcnt(0)
	v_pk_fma_f32 v[108:109], v[108:109], v[118:119], v[112:113]
	v_and_b32_e32 v113, 0xffff0000, v127
	v_lshlrev_b32_e32 v112, 16, v127
	v_pk_add_f32 v[112:113], v[124:125], v[112:113]
	s_nop 0
	v_pk_fma_f32 v[110:111], v[110:111], v[120:121], v[112:113]
	global_store_dwordx4 v[128:129], v[108:111], off offset:128
	s_nop 1
	v_or_b32_e32 v110, 8, v131
	v_lshlrev_b32_e32 v108, 12, v110
	v_lshlrev_b32_e32 v110, 11, v110
	v_mov_b32_e32 v111, v1
	v_lshl_add_u64 v[110:111], v[104:105], 0, v[110:111]
	v_mov_b32_e32 v109, v1
	global_load_dwordx2 v[126:127], v[110:111], off offset:64
	v_lshl_add_u64 v[112:113], v[106:107], 0, v[108:109]
	v_lshl_add_u64 v[128:129], v[102:103], 0, v[108:109]
	ds_read_b128 v[108:111], v0 offset:1152
	global_load_dwordx4 v[118:121], v[100:101], off
	global_load_dwordx4 v[122:125], v[112:113], off offset:128
	s_waitcnt vmcnt(2)
	v_and_b32_e32 v113, 0xffff0000, v126
	v_lshlrev_b32_e32 v112, 16, v126
	s_waitcnt vmcnt(0)
	v_pk_add_f32 v[112:113], v[122:123], v[112:113]
	s_waitcnt lgkmcnt(0)
	v_pk_fma_f32 v[108:109], v[108:109], v[118:119], v[112:113]
	v_and_b32_e32 v113, 0xffff0000, v127
	v_lshlrev_b32_e32 v112, 16, v127
	v_pk_add_f32 v[112:113], v[124:125], v[112:113]
	s_nop 0
	v_pk_fma_f32 v[110:111], v[110:111], v[120:121], v[112:113]
	global_store_dwordx4 v[128:129], v[108:111], off offset:128
	s_nop 1
	v_or_b32_e32 v110, 16, v131
	v_lshlrev_b32_e32 v108, 12, v110
	v_lshlrev_b32_e32 v110, 11, v110
	v_mov_b32_e32 v111, v1
	v_lshl_add_u64 v[110:111], v[104:105], 0, v[110:111]
	v_mov_b32_e32 v109, v1
	global_load_dwordx2 v[126:127], v[110:111], off offset:64
	v_lshl_add_u64 v[112:113], v[106:107], 0, v[108:109]
	v_lshl_add_u64 v[128:129], v[102:103], 0, v[108:109]
	ds_read_b128 v[108:111], v0 offset:2304
	global_load_dwordx4 v[118:121], v[100:101], off
	global_load_dwordx4 v[122:125], v[112:113], off offset:128
	s_waitcnt vmcnt(2)
	v_and_b32_e32 v113, 0xffff0000, v126
	v_lshlrev_b32_e32 v112, 16, v126
	s_waitcnt vmcnt(0)
	v_pk_add_f32 v[112:113], v[122:123], v[112:113]
	s_waitcnt lgkmcnt(0)
	v_pk_fma_f32 v[108:109], v[108:109], v[118:119], v[112:113]
	v_and_b32_e32 v113, 0xffff0000, v127
	v_lshlrev_b32_e32 v112, 16, v127
	v_pk_add_f32 v[112:113], v[124:125], v[112:113]
	s_nop 0
	v_pk_fma_f32 v[110:111], v[110:111], v[120:121], v[112:113]
	v_or_b32_e32 v112, 24, v131
	global_store_dwordx4 v[128:129], v[108:111], off offset:128
	s_nop 1
	v_lshlrev_b32_e32 v108, 12, v112
	v_mov_b32_e32 v109, v1
	v_lshl_add_u64 v[110:111], v[106:107], 0, v[108:109]
	v_lshlrev_b32_e32 v106, 11, v112
	v_mov_b32_e32 v107, v1
	v_lshl_add_u64 v[104:105], v[104:105], 0, v[106:107]
	global_load_dwordx2 v[118:119], v[104:105], off offset:64
	v_lshl_add_u64 v[120:121], v[102:103], 0, v[108:109]
	ds_read_b128 v[102:105], v0 offset:3456
	global_load_dwordx4 v[106:109], v[100:101], off
	s_nop 0
	global_load_dwordx4 v[110:113], v[110:111], off offset:128
	s_waitcnt vmcnt(2)
	v_and_b32_e32 v101, 0xffff0000, v118
	v_lshlrev_b32_e32 v100, 16, v118
	s_waitcnt vmcnt(0)
	v_pk_add_f32 v[100:101], v[110:111], v[100:101]
	s_waitcnt lgkmcnt(0)
	v_pk_fma_f32 v[100:101], v[102:103], v[106:107], v[100:101]
	v_and_b32_e32 v103, 0xffff0000, v119
	v_lshlrev_b32_e32 v102, 16, v119
	v_pk_add_f32 v[102:103], v[112:113], v[102:103]
	s_nop 0
	v_pk_fma_f32 v[102:103], v[104:105], v[108:109], v[102:103]
	global_store_dwordx4 v[120:121], v[100:103], off offset:128
	s_nop 1
	v_or_b32_e32 v100, 32, v130
	v_add_u32_e32 v0, v100, v155
	v_ashrrev_i32_e32 v0, 14, v0
	v_mul_i32_i24_e32 v101, 0x4000, v0
	v_sub_u32_e32 v101, v100, v101
	v_add_u32_e32 v106, 0x100, v101
	v_mul_i32_i24_e32 v102, 0xc00, v0
	v_mul_hi_i32_i24_e32 v105, 0x4100, v0
	v_mul_i32_i24_e32 v104, 0x4100, v0
	v_ashrrev_i32_e32 v107, 31, v106
	v_mov_b32_e32 v0, v179
	v_lshl_add_u64 v[104:105], v[104:105], 0, v[106:107]
	v_ashrrev_i32_e32 v103, 31, v102
	v_and_b32_e32 v106, 31, v0
	v_bfe_u32 v107, v0, 5, 1
	v_mul_u32_u24_e32 v107, 0x240, v107
	v_lshlrev_b32_e32 v106, 2, v106
	v_add3_u32 v106, v151, v107, v106
	ds_write2_b32 v106, v82, v83 offset1:36
	ds_write2_b32 v106, v84, v85 offset0:72 offset1:108
	v_add_u32_e32 v82, 0x400, v106
	ds_write2_b32 v82, v86, v87 offset0:32 offset1:68
	ds_write2_b32 v82, v88, v89 offset0:104 offset1:140
	v_add_u32_e32 v82, 0x800, v106
	ds_write2_b32 v82, v90, v91 offset0:64 offset1:100
	ds_write2_b32 v82, v92, v93 offset0:136 offset1:172
	v_add_u32_e32 v82, 0xc00, v106
	v_lshlrev_b64 v[104:105], 11, v[104:105]
	v_ashrrev_i32_e32 v101, 31, v100
	ds_write2_b32 v82, v94, v95 offset0:96 offset1:132
	ds_write2_b32 v82, v96, v97 offset0:168 offset1:204
	v_lshl_add_u64 v[82:83], v[102:103], 2, s[54:55]
	v_lshlrev_b32_e32 v92, 2, v0
	v_lshl_add_u64 v[86:87], v[82:83], 0, s[2:3]
	v_lshl_add_u64 v[82:83], s[0:1], 0, v[104:105]
	v_lshlrev_b64 v[84:85], 12, v[100:101]
	v_and_b32_e32 v92, 28, v92
	v_lshl_add_u64 v[82:83], v[82:83], 0, v[116:117]
	v_lshl_add_u64 v[88:89], s[36:37], 0, v[84:85]
	v_lshl_add_u64 v[84:85], s[52:53], 0, v[84:85]
	v_lshlrev_b32_e32 v100, 2, v92
	v_lshlrev_b32_e32 v92, 1, v92
	v_mov_b32_e32 v93, v1
	v_bfe_u32 v122, v0, 3, 3
	v_lshl_add_u64 v[90:91], v[86:87], 0, v[114:115]
	v_lshl_add_u64 v[88:89], v[88:89], 0, v[114:115]
	v_lshl_add_u64 v[84:85], v[84:85], 0, v[114:115]
	v_mov_b32_e32 v101, v1
	v_lshl_add_u64 v[94:95], v[82:83], 0, v[92:93]
	v_mul_u32_u24_e32 v0, 0x90, v122
	v_lshlrev_b32_e32 v102, 11, v122
	v_mov_b32_e32 v103, v1
	s_waitcnt lgkmcnt(0)
	v_lshl_add_u64 v[90:91], v[90:91], 0, v[100:101]
	v_lshl_add_u64 v[96:97], v[88:89], 0, v[100:101]
	v_lshl_add_u64 v[92:93], v[84:85], 0, v[100:101]
	v_add3_u32 v0, v151, v100, v0
	v_lshlrev_b32_e32 v100, 12, v122
	v_lshl_add_u64 v[102:103], v[94:95], 0, v[102:103]
	v_lshl_add_u64 v[108:109], v[96:97], 0, v[100:101]
	global_load_dwordx2 v[112:113], v[102:103], off
	v_lshl_add_u64 v[118:119], v[92:93], 0, v[100:101]
	ds_read_b128 v[100:103], v0
	global_load_dwordx4 v[104:107], v[90:91], off
	s_nop 0
	global_load_dwordx4 v[108:111], v[108:109], off
	s_waitcnt vmcnt(2)
	v_and_b32_e32 v121, 0xffff0000, v112
	v_lshlrev_b32_e32 v120, 16, v112
	s_waitcnt vmcnt(0)
	v_pk_add_f32 v[108:109], v[108:109], v[120:121]
	s_waitcnt lgkmcnt(0)
	v_pk_fma_f32 v[100:101], v[100:101], v[104:105], v[108:109]
	v_and_b32_e32 v105, 0xffff0000, v113
	v_lshlrev_b32_e32 v104, 16, v113
	v_pk_add_f32 v[104:105], v[110:111], v[104:105]
	s_nop 0
	v_pk_fma_f32 v[102:103], v[102:103], v[106:107], v[104:105]
	global_store_dwordx4 v[118:119], v[100:103], off
	s_nop 1
	v_or_b32_e32 v102, 8, v122
	v_lshlrev_b32_e32 v100, 12, v102
	v_lshlrev_b32_e32 v102, 11, v102
	v_mov_b32_e32 v103, v1
	v_mov_b32_e32 v101, v1
	v_lshl_add_u64 v[102:103], v[94:95], 0, v[102:103]
	v_lshl_add_u64 v[108:109], v[96:97], 0, v[100:101]
	global_load_dwordx2 v[112:113], v[102:103], off
	v_lshl_add_u64 v[118:119], v[92:93], 0, v[100:101]
	ds_read_b128 v[100:103], v0 offset:1152
	global_load_dwordx4 v[104:107], v[90:91], off
	s_nop 0
	global_load_dwordx4 v[108:111], v[108:109], off
	s_waitcnt vmcnt(2)
	v_and_b32_e32 v121, 0xffff0000, v112
	v_lshlrev_b32_e32 v120, 16, v112
	s_waitcnt vmcnt(0)
	v_pk_add_f32 v[108:109], v[108:109], v[120:121]
	s_waitcnt lgkmcnt(0)
	v_pk_fma_f32 v[100:101], v[100:101], v[104:105], v[108:109]
	v_and_b32_e32 v105, 0xffff0000, v113
	v_lshlrev_b32_e32 v104, 16, v113
	v_pk_add_f32 v[104:105], v[110:111], v[104:105]
	s_nop 0
	v_pk_fma_f32 v[102:103], v[102:103], v[106:107], v[104:105]
	global_store_dwordx4 v[118:119], v[100:103], off
	s_nop 1
	v_or_b32_e32 v102, 16, v122
	v_lshlrev_b32_e32 v100, 12, v102
	v_lshlrev_b32_e32 v102, 11, v102
	v_mov_b32_e32 v103, v1
	v_mov_b32_e32 v101, v1
	v_lshl_add_u64 v[102:103], v[94:95], 0, v[102:103]
	v_lshl_add_u64 v[108:109], v[96:97], 0, v[100:101]
	global_load_dwordx2 v[112:113], v[102:103], off
	v_lshl_add_u64 v[118:119], v[92:93], 0, v[100:101]
	ds_read_b128 v[100:103], v0 offset:2304
	global_load_dwordx4 v[104:107], v[90:91], off
	s_nop 0
	global_load_dwordx4 v[108:111], v[108:109], off
	s_waitcnt vmcnt(2)
	v_and_b32_e32 v121, 0xffff0000, v112
	v_lshlrev_b32_e32 v120, 16, v112
	s_waitcnt vmcnt(0)
	v_pk_add_f32 v[108:109], v[108:109], v[120:121]
	s_waitcnt lgkmcnt(0)
	v_pk_fma_f32 v[100:101], v[100:101], v[104:105], v[108:109]
	v_and_b32_e32 v105, 0xffff0000, v113
	v_lshlrev_b32_e32 v104, 16, v113
	v_pk_add_f32 v[104:105], v[110:111], v[104:105]
	s_nop 0
	v_pk_fma_f32 v[102:103], v[102:103], v[106:107], v[104:105]
	global_store_dwordx4 v[118:119], v[100:103], off
	s_nop 1
	v_or_b32_e32 v102, 24, v122
	v_lshlrev_b32_e32 v100, 12, v102
	v_lshlrev_b32_e32 v102, 11, v102
	v_mov_b32_e32 v103, v1
	v_lshl_add_u64 v[94:95], v[94:95], 0, v[102:103]
	v_mov_b32_e32 v101, v1
	global_load_dwordx2 v[108:109], v[94:95], off
	v_lshl_add_u64 v[96:97], v[96:97], 0, v[100:101]
	v_lshl_add_u64 v[110:111], v[92:93], 0, v[100:101]
	ds_read_b128 v[92:95], v0 offset:3456
	global_load_dwordx4 v[100:103], v[90:91], off
	global_load_dwordx4 v[104:107], v[96:97], off
	s_waitcnt vmcnt(2)
	v_and_b32_e32 v91, 0xffff0000, v108
	v_lshlrev_b32_e32 v90, 16, v108
	s_waitcnt vmcnt(0)
	v_pk_add_f32 v[90:91], v[104:105], v[90:91]
	s_waitcnt lgkmcnt(0)
	v_pk_fma_f32 v[90:91], v[92:93], v[100:101], v[90:91]
	v_and_b32_e32 v93, 0xffff0000, v109
	v_lshlrev_b32_e32 v92, 16, v109
	v_pk_add_f32 v[92:93], v[106:107], v[92:93]
	s_nop 0
	v_pk_fma_f32 v[92:93], v[94:95], v[102:103], v[92:93]
	global_store_dwordx4 v[110:111], v[90:93], off
	v_mov_b32_e32 v0, v179
	s_nop 0
	v_and_b32_e32 v90, 31, v0
	v_bfe_u32 v91, v0, 5, 1
	v_mul_u32_u24_e32 v91, 0x240, v91
	v_lshlrev_b32_e32 v90, 2, v90
	v_add3_u32 v90, v151, v91, v90
	ds_write2_b32 v90, v66, v67 offset1:36
	ds_write2_b32 v90, v68, v69 offset0:72 offset1:108
	v_add_u32_e32 v66, 0x400, v90
	ds_write2_b32 v66, v70, v71 offset0:32 offset1:68
	ds_write2_b32 v66, v72, v73 offset0:104 offset1:140
	v_add_u32_e32 v66, 0x800, v90
	ds_write2_b32 v66, v74, v75 offset0:64 offset1:100
	ds_write2_b32 v66, v76, v77 offset0:136 offset1:172
	v_add_u32_e32 v66, 0xc00, v90
	ds_write2_b32 v66, v78, v79 offset0:96 offset1:132
	ds_write2_b32 v66, v80, v81 offset0:168 offset1:204
	v_lshlrev_b32_e32 v66, 2, v0
	v_and_b32_e32 v68, 28, v66
	v_lshlrev_b32_e32 v74, 2, v68
	v_lshlrev_b32_e32 v68, 1, v68
	v_mov_b32_e32 v69, v1
	v_bfe_u32 v92, v0, 3, 3
	v_mov_b32_e32 v75, v1
	v_lshl_add_u64 v[70:71], v[82:83], 0, v[68:69]
	v_mul_u32_u24_e32 v0, 0x90, v92
	v_lshlrev_b32_e32 v76, 11, v92
	v_mov_b32_e32 v77, v1
	s_waitcnt lgkmcnt(0)
	v_lshl_add_u64 v[66:67], v[86:87], 0, v[74:75]
	v_lshl_add_u64 v[72:73], v[88:89], 0, v[74:75]
	v_lshl_add_u64 v[68:69], v[84:85], 0, v[74:75]
	v_add3_u32 v0, v151, v74, v0
	v_lshlrev_b32_e32 v74, 12, v92
	v_lshl_add_u64 v[76:77], v[70:71], 0, v[76:77]
	v_lshl_add_u64 v[66:67], v[66:67], 0, v[98:99]
	v_lshl_add_u64 v[82:83], v[72:73], 0, v[74:75]
	global_load_dwordx2 v[86:87], v[76:77], off offset:64
	v_lshl_add_u64 v[88:89], v[68:69], 0, v[74:75]
	ds_read_b128 v[74:77], v0
	global_load_dwordx4 v[78:81], v[66:67], off
	s_nop 0
	global_load_dwordx4 v[82:85], v[82:83], off offset:128
	s_waitcnt vmcnt(2)
	v_and_b32_e32 v91, 0xffff0000, v86
	v_lshlrev_b32_e32 v90, 16, v86
	s_waitcnt vmcnt(0)
	v_pk_add_f32 v[82:83], v[82:83], v[90:91]
	s_waitcnt lgkmcnt(0)
	v_pk_fma_f32 v[74:75], v[74:75], v[78:79], v[82:83]
	v_and_b32_e32 v79, 0xffff0000, v87
	v_lshlrev_b32_e32 v78, 16, v87
	v_pk_add_f32 v[78:79], v[84:85], v[78:79]
	s_nop 0
	v_pk_fma_f32 v[76:77], v[76:77], v[80:81], v[78:79]
	global_store_dwordx4 v[88:89], v[74:77], off offset:128
	s_nop 1
	v_or_b32_e32 v76, 8, v92
	v_lshlrev_b32_e32 v74, 12, v76
	v_lshlrev_b32_e32 v76, 11, v76
	v_mov_b32_e32 v77, v1
	v_mov_b32_e32 v75, v1
	v_lshl_add_u64 v[76:77], v[70:71], 0, v[76:77]
	v_lshl_add_u64 v[82:83], v[72:73], 0, v[74:75]
	global_load_dwordx2 v[86:87], v[76:77], off offset:64
	v_lshl_add_u64 v[88:89], v[68:69], 0, v[74:75]
	ds_read_b128 v[74:77], v0 offset:1152
	global_load_dwordx4 v[78:81], v[66:67], off
	s_nop 0
	global_load_dwordx4 v[82:85], v[82:83], off offset:128
	s_waitcnt vmcnt(2)
	v_and_b32_e32 v91, 0xffff0000, v86
	v_lshlrev_b32_e32 v90, 16, v86
	s_waitcnt vmcnt(0)
	v_pk_add_f32 v[82:83], v[82:83], v[90:91]
	s_waitcnt lgkmcnt(0)
	v_pk_fma_f32 v[74:75], v[74:75], v[78:79], v[82:83]
	v_and_b32_e32 v79, 0xffff0000, v87
	v_lshlrev_b32_e32 v78, 16, v87
	v_pk_add_f32 v[78:79], v[84:85], v[78:79]
	s_nop 0
	v_pk_fma_f32 v[76:77], v[76:77], v[80:81], v[78:79]
	global_store_dwordx4 v[88:89], v[74:77], off offset:128
	s_nop 1
	v_or_b32_e32 v76, 16, v92
	v_lshlrev_b32_e32 v74, 12, v76
	v_lshlrev_b32_e32 v76, 11, v76
	v_mov_b32_e32 v77, v1
	v_mov_b32_e32 v75, v1
	v_lshl_add_u64 v[76:77], v[70:71], 0, v[76:77]
	v_lshl_add_u64 v[82:83], v[72:73], 0, v[74:75]
	global_load_dwordx2 v[86:87], v[76:77], off offset:64
	v_lshl_add_u64 v[88:89], v[68:69], 0, v[74:75]
	ds_read_b128 v[74:77], v0 offset:2304
	global_load_dwordx4 v[78:81], v[66:67], off
	s_nop 0
	global_load_dwordx4 v[82:85], v[82:83], off offset:128
	s_waitcnt vmcnt(2)
	v_and_b32_e32 v91, 0xffff0000, v86
	v_lshlrev_b32_e32 v90, 16, v86
	s_waitcnt vmcnt(0)
	v_pk_add_f32 v[82:83], v[82:83], v[90:91]
	s_waitcnt lgkmcnt(0)
	v_pk_fma_f32 v[74:75], v[74:75], v[78:79], v[82:83]
	v_and_b32_e32 v79, 0xffff0000, v87
	v_lshlrev_b32_e32 v78, 16, v87
	v_pk_add_f32 v[78:79], v[84:85], v[78:79]
	s_nop 0
	v_pk_fma_f32 v[76:77], v[76:77], v[80:81], v[78:79]
	v_or_b32_e32 v78, 24, v92
	global_store_dwordx4 v[88:89], v[74:77], off offset:128
	s_nop 1
	v_lshlrev_b32_e32 v74, 12, v78
	v_mov_b32_e32 v75, v1
	v_lshl_add_u64 v[76:77], v[72:73], 0, v[74:75]
	v_lshlrev_b32_e32 v72, 11, v78
	v_mov_b32_e32 v73, v1
	v_lshl_add_u64 v[70:71], v[70:71], 0, v[72:73]
	global_load_dwordx2 v[80:81], v[70:71], off offset:64
	v_lshl_add_u64 v[82:83], v[68:69], 0, v[74:75]
	ds_read_b128 v[68:71], v0 offset:3456
	global_load_dwordx4 v[72:75], v[66:67], off
	s_nop 0
	global_load_dwordx4 v[76:79], v[76:77], off offset:128
	s_waitcnt vmcnt(2)
	v_and_b32_e32 v67, 0xffff0000, v80
	v_lshlrev_b32_e32 v66, 16, v80
	s_waitcnt vmcnt(0)
	v_pk_add_f32 v[66:67], v[76:77], v[66:67]
	s_waitcnt lgkmcnt(0)
	v_pk_fma_f32 v[66:67], v[68:69], v[72:73], v[66:67]
	v_and_b32_e32 v69, 0xffff0000, v81
	v_lshlrev_b32_e32 v68, 16, v81
	v_pk_add_f32 v[68:69], v[78:79], v[68:69]
	s_nop 0
	v_pk_fma_f32 v[68:69], v[70:71], v[74:75], v[68:69]
	global_store_dwordx4 v[82:83], v[66:69], off offset:128
	s_nop 1
	v_or_b32_e32 v66, 64, v130
	v_add_u32_e32 v0, v66, v155
	v_ashrrev_i32_e32 v0, 14, v0
	v_mul_i32_i24_e32 v67, 0x4000, v0
	v_sub_u32_e32 v67, v66, v67
	v_add_u32_e32 v72, 0x100, v67
	v_mul_i32_i24_e32 v68, 0xc00, v0
	v_mul_hi_i32_i24_e32 v71, 0x4100, v0
	v_mul_i32_i24_e32 v70, 0x4100, v0
	v_ashrrev_i32_e32 v73, 31, v72
	v_mov_b32_e32 v0, v179
	v_lshl_add_u64 v[70:71], v[70:71], 0, v[72:73]
	v_ashrrev_i32_e32 v69, 31, v68
	v_and_b32_e32 v72, 31, v0
	v_bfe_u32 v73, v0, 5, 1
	v_mul_u32_u24_e32 v73, 0x240, v73
	v_lshlrev_b32_e32 v72, 2, v72
	v_add3_u32 v72, v151, v73, v72
	ds_write2_b32 v72, v50, v51 offset1:36
	ds_write2_b32 v72, v52, v53 offset0:72 offset1:108
	v_add_u32_e32 v50, 0x400, v72
	ds_write2_b32 v50, v54, v55 offset0:32 offset1:68
	ds_write2_b32 v50, v56, v57 offset0:104 offset1:140
	v_add_u32_e32 v50, 0x800, v72
	ds_write2_b32 v50, v58, v59 offset0:64 offset1:100
	ds_write2_b32 v50, v60, v61 offset0:136 offset1:172
	v_add_u32_e32 v50, 0xc00, v72
	v_lshlrev_b64 v[70:71], 11, v[70:71]
	v_ashrrev_i32_e32 v67, 31, v66
	ds_write2_b32 v50, v62, v63 offset0:96 offset1:132
	ds_write2_b32 v50, v64, v65 offset0:168 offset1:204
	v_lshl_add_u64 v[50:51], v[68:69], 2, s[54:55]
	v_lshlrev_b32_e32 v60, 2, v0
	v_lshl_add_u64 v[54:55], v[50:51], 0, s[2:3]
	v_lshl_add_u64 v[50:51], s[0:1], 0, v[70:71]
	v_lshlrev_b64 v[52:53], 12, v[66:67]
	v_and_b32_e32 v60, 28, v60
	v_lshl_add_u64 v[50:51], v[50:51], 0, v[116:117]
	v_lshl_add_u64 v[56:57], s[36:37], 0, v[52:53]
	v_lshl_add_u64 v[52:53], s[52:53], 0, v[52:53]
	v_lshlrev_b32_e32 v66, 2, v60
	v_lshlrev_b32_e32 v60, 1, v60
	v_mov_b32_e32 v61, v1
	v_bfe_u32 v84, v0, 3, 3
	v_lshl_add_u64 v[58:59], v[54:55], 0, v[114:115]
	v_lshl_add_u64 v[56:57], v[56:57], 0, v[114:115]
	v_lshl_add_u64 v[52:53], v[52:53], 0, v[114:115]
	v_mov_b32_e32 v67, v1
	v_lshl_add_u64 v[62:63], v[50:51], 0, v[60:61]
	v_mul_u32_u24_e32 v0, 0x90, v84
	v_lshlrev_b32_e32 v68, 11, v84
	v_mov_b32_e32 v69, v1
	s_waitcnt lgkmcnt(0)
	v_lshl_add_u64 v[58:59], v[58:59], 0, v[66:67]
	v_lshl_add_u64 v[64:65], v[56:57], 0, v[66:67]
	v_lshl_add_u64 v[60:61], v[52:53], 0, v[66:67]
	v_add3_u32 v0, v151, v66, v0
	v_lshlrev_b32_e32 v66, 12, v84
	v_lshl_add_u64 v[68:69], v[62:63], 0, v[68:69]
	v_lshl_add_u64 v[74:75], v[64:65], 0, v[66:67]
	global_load_dwordx2 v[78:79], v[68:69], off
	v_lshl_add_u64 v[80:81], v[60:61], 0, v[66:67]
	ds_read_b128 v[66:69], v0
	global_load_dwordx4 v[70:73], v[58:59], off
	s_nop 0
	global_load_dwordx4 v[74:77], v[74:75], off
	s_waitcnt vmcnt(2)
	v_and_b32_e32 v83, 0xffff0000, v78
	v_lshlrev_b32_e32 v82, 16, v78
	s_waitcnt vmcnt(0)
	v_pk_add_f32 v[74:75], v[74:75], v[82:83]
	s_waitcnt lgkmcnt(0)
	v_pk_fma_f32 v[66:67], v[66:67], v[70:71], v[74:75]
	v_and_b32_e32 v71, 0xffff0000, v79
	v_lshlrev_b32_e32 v70, 16, v79
	v_pk_add_f32 v[70:71], v[76:77], v[70:71]
	s_nop 0
	v_pk_fma_f32 v[68:69], v[68:69], v[72:73], v[70:71]
	global_store_dwordx4 v[80:81], v[66:69], off
	s_nop 1
	v_or_b32_e32 v68, 8, v84
	v_lshlrev_b32_e32 v66, 12, v68
	v_lshlrev_b32_e32 v68, 11, v68
	v_mov_b32_e32 v69, v1
	v_mov_b32_e32 v67, v1
	v_lshl_add_u64 v[68:69], v[62:63], 0, v[68:69]
	v_lshl_add_u64 v[74:75], v[64:65], 0, v[66:67]
	global_load_dwordx2 v[78:79], v[68:69], off
	v_lshl_add_u64 v[80:81], v[60:61], 0, v[66:67]
	ds_read_b128 v[66:69], v0 offset:1152
	global_load_dwordx4 v[70:73], v[58:59], off
	s_nop 0
	global_load_dwordx4 v[74:77], v[74:75], off
	s_waitcnt vmcnt(2)
	v_and_b32_e32 v83, 0xffff0000, v78
	v_lshlrev_b32_e32 v82, 16, v78
	s_waitcnt vmcnt(0)
	v_pk_add_f32 v[74:75], v[74:75], v[82:83]
	s_waitcnt lgkmcnt(0)
	v_pk_fma_f32 v[66:67], v[66:67], v[70:71], v[74:75]
	v_and_b32_e32 v71, 0xffff0000, v79
	v_lshlrev_b32_e32 v70, 16, v79
	v_pk_add_f32 v[70:71], v[76:77], v[70:71]
	s_nop 0
	v_pk_fma_f32 v[68:69], v[68:69], v[72:73], v[70:71]
	global_store_dwordx4 v[80:81], v[66:69], off
	s_nop 1
	v_or_b32_e32 v68, 16, v84
	v_lshlrev_b32_e32 v66, 12, v68
	v_lshlrev_b32_e32 v68, 11, v68
	v_mov_b32_e32 v69, v1
	v_mov_b32_e32 v67, v1
	v_lshl_add_u64 v[68:69], v[62:63], 0, v[68:69]
	v_lshl_add_u64 v[74:75], v[64:65], 0, v[66:67]
	global_load_dwordx2 v[78:79], v[68:69], off
	v_lshl_add_u64 v[80:81], v[60:61], 0, v[66:67]
	ds_read_b128 v[66:69], v0 offset:2304
	global_load_dwordx4 v[70:73], v[58:59], off
	s_nop 0
	global_load_dwordx4 v[74:77], v[74:75], off
	s_waitcnt vmcnt(2)
	v_and_b32_e32 v83, 0xffff0000, v78
	v_lshlrev_b32_e32 v82, 16, v78
	s_waitcnt vmcnt(0)
	v_pk_add_f32 v[74:75], v[74:75], v[82:83]
	s_waitcnt lgkmcnt(0)
	v_pk_fma_f32 v[66:67], v[66:67], v[70:71], v[74:75]
	v_and_b32_e32 v71, 0xffff0000, v79
	v_lshlrev_b32_e32 v70, 16, v79
	v_pk_add_f32 v[70:71], v[76:77], v[70:71]
	s_nop 0
	v_pk_fma_f32 v[68:69], v[68:69], v[72:73], v[70:71]
	v_or_b32_e32 v70, 24, v84
	global_store_dwordx4 v[80:81], v[66:69], off
	s_nop 1
	v_lshlrev_b32_e32 v66, 12, v70
	v_mov_b32_e32 v67, v1
	v_lshl_add_u64 v[68:69], v[64:65], 0, v[66:67]
	v_lshlrev_b32_e32 v64, 11, v70
	v_mov_b32_e32 v65, v1
	v_lshl_add_u64 v[62:63], v[62:63], 0, v[64:65]
	global_load_dwordx2 v[72:73], v[62:63], off
	v_lshl_add_u64 v[74:75], v[60:61], 0, v[66:67]
	ds_read_b128 v[60:63], v0 offset:3456
	global_load_dwordx4 v[64:67], v[58:59], off
	s_nop 0
	global_load_dwordx4 v[68:71], v[68:69], off
	s_waitcnt vmcnt(2)
	v_and_b32_e32 v59, 0xffff0000, v72
	v_lshlrev_b32_e32 v58, 16, v72
	s_waitcnt vmcnt(0)
	v_pk_add_f32 v[58:59], v[68:69], v[58:59]
	s_waitcnt lgkmcnt(0)
	v_pk_fma_f32 v[58:59], v[60:61], v[64:65], v[58:59]
	v_and_b32_e32 v61, 0xffff0000, v73
	v_lshlrev_b32_e32 v60, 16, v73
	v_pk_add_f32 v[60:61], v[70:71], v[60:61]
	s_nop 0
	v_pk_fma_f32 v[60:61], v[62:63], v[66:67], v[60:61]
	global_store_dwordx4 v[74:75], v[58:61], off
	v_mov_b32_e32 v0, v179
	s_nop 0
	v_and_b32_e32 v58, 31, v0
	v_bfe_u32 v59, v0, 5, 1
	v_mul_u32_u24_e32 v59, 0x240, v59
	v_lshlrev_b32_e32 v58, 2, v58
	v_add3_u32 v58, v151, v59, v58
	ds_write2_b32 v58, v34, v35 offset1:36
	ds_write2_b32 v58, v36, v37 offset0:72 offset1:108
	v_add_u32_e32 v34, 0x400, v58
	ds_write2_b32 v34, v38, v39 offset0:32 offset1:68
	ds_write2_b32 v34, v40, v41 offset0:104 offset1:140
	v_add_u32_e32 v34, 0x800, v58
	ds_write2_b32 v34, v42, v43 offset0:64 offset1:100
	ds_write2_b32 v34, v44, v45 offset0:136 offset1:172
	v_add_u32_e32 v34, 0xc00, v58
	ds_write2_b32 v34, v46, v47 offset0:96 offset1:132
	ds_write2_b32 v34, v48, v49 offset0:168 offset1:204
	v_lshlrev_b32_e32 v34, 2, v0
	v_and_b32_e32 v36, 28, v34
	v_lshlrev_b32_e32 v42, 2, v36
	v_lshlrev_b32_e32 v36, 1, v36
	v_mov_b32_e32 v37, v1
	v_bfe_u32 v60, v0, 3, 3
	v_mov_b32_e32 v43, v1
	v_lshl_add_u64 v[38:39], v[50:51], 0, v[36:37]
	v_mul_u32_u24_e32 v0, 0x90, v60
	v_lshlrev_b32_e32 v44, 11, v60
	v_mov_b32_e32 v45, v1
	s_waitcnt lgkmcnt(0)
	v_lshl_add_u64 v[34:35], v[54:55], 0, v[42:43]
	v_lshl_add_u64 v[40:41], v[56:57], 0, v[42:43]
	v_lshl_add_u64 v[36:37], v[52:53], 0, v[42:43]
	v_add3_u32 v0, v151, v42, v0
	v_lshlrev_b32_e32 v42, 12, v60
	v_lshl_add_u64 v[44:45], v[38:39], 0, v[44:45]
	v_lshl_add_u64 v[34:35], v[34:35], 0, v[98:99]
	v_lshl_add_u64 v[50:51], v[40:41], 0, v[42:43]
	global_load_dwordx2 v[54:55], v[44:45], off offset:64
	v_lshl_add_u64 v[56:57], v[36:37], 0, v[42:43]
	ds_read_b128 v[42:45], v0
	global_load_dwordx4 v[46:49], v[34:35], off
	s_nop 0
	global_load_dwordx4 v[50:53], v[50:51], off offset:128
	s_waitcnt vmcnt(2)
	v_and_b32_e32 v59, 0xffff0000, v54
	v_lshlrev_b32_e32 v58, 16, v54
	s_waitcnt vmcnt(0)
	v_pk_add_f32 v[50:51], v[50:51], v[58:59]
	s_waitcnt lgkmcnt(0)
	v_pk_fma_f32 v[42:43], v[42:43], v[46:47], v[50:51]
	v_and_b32_e32 v47, 0xffff0000, v55
	v_lshlrev_b32_e32 v46, 16, v55
	v_pk_add_f32 v[46:47], v[52:53], v[46:47]
	s_nop 0
	v_pk_fma_f32 v[44:45], v[44:45], v[48:49], v[46:47]
	global_store_dwordx4 v[56:57], v[42:45], off offset:128
	s_nop 1
	v_or_b32_e32 v44, 8, v60
	v_lshlrev_b32_e32 v42, 12, v44
	v_lshlrev_b32_e32 v44, 11, v44
	v_mov_b32_e32 v45, v1
	v_mov_b32_e32 v43, v1
	v_lshl_add_u64 v[44:45], v[38:39], 0, v[44:45]
	v_lshl_add_u64 v[50:51], v[40:41], 0, v[42:43]
	global_load_dwordx2 v[54:55], v[44:45], off offset:64
	v_lshl_add_u64 v[56:57], v[36:37], 0, v[42:43]
	ds_read_b128 v[42:45], v0 offset:1152
	global_load_dwordx4 v[46:49], v[34:35], off
	s_nop 0
	global_load_dwordx4 v[50:53], v[50:51], off offset:128
	s_waitcnt vmcnt(2)
	v_and_b32_e32 v59, 0xffff0000, v54
	v_lshlrev_b32_e32 v58, 16, v54
	s_waitcnt vmcnt(0)
	v_pk_add_f32 v[50:51], v[50:51], v[58:59]
	s_waitcnt lgkmcnt(0)
	v_pk_fma_f32 v[42:43], v[42:43], v[46:47], v[50:51]
	v_and_b32_e32 v47, 0xffff0000, v55
	v_lshlrev_b32_e32 v46, 16, v55
	v_pk_add_f32 v[46:47], v[52:53], v[46:47]
	s_nop 0
	v_pk_fma_f32 v[44:45], v[44:45], v[48:49], v[46:47]
	global_store_dwordx4 v[56:57], v[42:45], off offset:128
	s_nop 1
	v_or_b32_e32 v44, 16, v60
	v_lshlrev_b32_e32 v42, 12, v44
	v_lshlrev_b32_e32 v44, 11, v44
	v_mov_b32_e32 v45, v1
	v_mov_b32_e32 v43, v1
	v_lshl_add_u64 v[44:45], v[38:39], 0, v[44:45]
	v_lshl_add_u64 v[50:51], v[40:41], 0, v[42:43]
	global_load_dwordx2 v[54:55], v[44:45], off offset:64
	v_lshl_add_u64 v[56:57], v[36:37], 0, v[42:43]
	ds_read_b128 v[42:45], v0 offset:2304
	global_load_dwordx4 v[46:49], v[34:35], off
	s_nop 0
	global_load_dwordx4 v[50:53], v[50:51], off offset:128
	s_waitcnt vmcnt(2)
	v_and_b32_e32 v59, 0xffff0000, v54
	v_lshlrev_b32_e32 v58, 16, v54
	s_waitcnt vmcnt(0)
	v_pk_add_f32 v[50:51], v[50:51], v[58:59]
	s_waitcnt lgkmcnt(0)
	v_pk_fma_f32 v[42:43], v[42:43], v[46:47], v[50:51]
	v_and_b32_e32 v47, 0xffff0000, v55
	v_lshlrev_b32_e32 v46, 16, v55
	v_pk_add_f32 v[46:47], v[52:53], v[46:47]
	s_nop 0
	v_pk_fma_f32 v[44:45], v[44:45], v[48:49], v[46:47]
	v_or_b32_e32 v46, 24, v60
	global_store_dwordx4 v[56:57], v[42:45], off offset:128
	s_nop 1
	v_lshlrev_b32_e32 v42, 12, v46
	v_mov_b32_e32 v43, v1
	v_lshl_add_u64 v[44:45], v[40:41], 0, v[42:43]
	v_lshlrev_b32_e32 v40, 11, v46
	v_mov_b32_e32 v41, v1
	v_lshl_add_u64 v[38:39], v[38:39], 0, v[40:41]
	global_load_dwordx2 v[48:49], v[38:39], off offset:64
	v_lshl_add_u64 v[50:51], v[36:37], 0, v[42:43]
	ds_read_b128 v[36:39], v0 offset:3456
	global_load_dwordx4 v[40:43], v[34:35], off
	s_nop 0
	global_load_dwordx4 v[44:47], v[44:45], off offset:128
	s_waitcnt vmcnt(2)
	v_and_b32_e32 v35, 0xffff0000, v48
	v_lshlrev_b32_e32 v34, 16, v48
	s_waitcnt vmcnt(0)
	v_pk_add_f32 v[34:35], v[44:45], v[34:35]
	s_waitcnt lgkmcnt(0)
	v_pk_fma_f32 v[34:35], v[36:37], v[40:41], v[34:35]
	v_and_b32_e32 v37, 0xffff0000, v49
	v_lshlrev_b32_e32 v36, 16, v49
	v_pk_add_f32 v[36:37], v[46:47], v[36:37]
	s_nop 0
	v_pk_fma_f32 v[36:37], v[38:39], v[42:43], v[36:37]
	global_store_dwordx4 v[50:51], v[34:37], off offset:128
	s_nop 1
	v_or_b32_e32 v34, 0x60, v130
	v_add_u32_e32 v0, v34, v155
	v_ashrrev_i32_e32 v0, 14, v0
	v_mul_i32_i24_e32 v35, 0x4000, v0
	v_sub_u32_e32 v35, v34, v35
	v_add_u32_e32 v40, 0x100, v35
	v_mul_i32_i24_e32 v36, 0xc00, v0
	v_mul_hi_i32_i24_e32 v39, 0x4100, v0
	v_mul_i32_i24_e32 v38, 0x4100, v0
	v_ashrrev_i32_e32 v41, 31, v40
	v_mov_b32_e32 v0, v179
	v_lshl_add_u64 v[38:39], v[38:39], 0, v[40:41]
	v_ashrrev_i32_e32 v37, 31, v36
	v_and_b32_e32 v40, 31, v0
	v_bfe_u32 v41, v0, 5, 1
	v_mul_u32_u24_e32 v41, 0x240, v41
	v_lshlrev_b32_e32 v40, 2, v40
	v_add3_u32 v40, v151, v41, v40
	ds_write2_b32 v40, v18, v19 offset1:36
	ds_write2_b32 v40, v20, v21 offset0:72 offset1:108
	v_add_u32_e32 v18, 0x400, v40
	ds_write2_b32 v18, v22, v23 offset0:32 offset1:68
	ds_write2_b32 v18, v24, v25 offset0:104 offset1:140
	v_add_u32_e32 v18, 0x800, v40
	ds_write2_b32 v18, v26, v27 offset0:64 offset1:100
	ds_write2_b32 v18, v28, v29 offset0:136 offset1:172
	v_add_u32_e32 v18, 0xc00, v40
	v_lshlrev_b64 v[38:39], 11, v[38:39]
	v_ashrrev_i32_e32 v35, 31, v34
	ds_write2_b32 v18, v30, v31 offset0:96 offset1:132
	ds_write2_b32 v18, v32, v33 offset0:168 offset1:204
	v_lshl_add_u64 v[18:19], v[36:37], 2, s[54:55]
	v_lshlrev_b32_e32 v28, 2, v0
	v_lshl_add_u64 v[20:21], v[18:19], 0, s[2:3]
	v_lshl_add_u64 v[18:19], s[0:1], 0, v[38:39]
	v_lshlrev_b64 v[22:23], 12, v[34:35]
	v_and_b32_e32 v28, 28, v28
	v_lshl_add_u64 v[18:19], v[18:19], 0, v[116:117]
	v_lshl_add_u64 v[24:25], s[36:37], 0, v[22:23]
	v_lshl_add_u64 v[22:23], s[52:53], 0, v[22:23]
	v_lshlrev_b32_e32 v34, 2, v28
	v_lshlrev_b32_e32 v28, 1, v28
	v_mov_b32_e32 v29, v1
	v_bfe_u32 v52, v0, 3, 3
	v_lshl_add_u64 v[26:27], v[20:21], 0, v[114:115]
	v_lshl_add_u64 v[24:25], v[24:25], 0, v[114:115]
	v_lshl_add_u64 v[22:23], v[22:23], 0, v[114:115]
	v_mov_b32_e32 v35, v1
	v_lshl_add_u64 v[30:31], v[18:19], 0, v[28:29]
	v_mul_u32_u24_e32 v0, 0x90, v52
	v_lshlrev_b32_e32 v36, 11, v52
	v_mov_b32_e32 v37, v1
	s_waitcnt lgkmcnt(0)
	v_lshl_add_u64 v[26:27], v[26:27], 0, v[34:35]
	v_lshl_add_u64 v[32:33], v[24:25], 0, v[34:35]
	v_lshl_add_u64 v[28:29], v[22:23], 0, v[34:35]
	v_add3_u32 v0, v151, v34, v0
	v_lshlrev_b32_e32 v34, 12, v52
	v_lshl_add_u64 v[36:37], v[30:31], 0, v[36:37]
	v_lshl_add_u64 v[42:43], v[32:33], 0, v[34:35]
	global_load_dwordx2 v[46:47], v[36:37], off
	v_lshl_add_u64 v[48:49], v[28:29], 0, v[34:35]
	ds_read_b128 v[34:37], v0
	global_load_dwordx4 v[38:41], v[26:27], off
	s_nop 0
	global_load_dwordx4 v[42:45], v[42:43], off
	s_waitcnt vmcnt(2)
	v_and_b32_e32 v51, 0xffff0000, v46
	v_lshlrev_b32_e32 v50, 16, v46
	s_waitcnt vmcnt(0)
	v_pk_add_f32 v[42:43], v[42:43], v[50:51]
	s_waitcnt lgkmcnt(0)
	v_pk_fma_f32 v[34:35], v[34:35], v[38:39], v[42:43]
	v_and_b32_e32 v39, 0xffff0000, v47
	v_lshlrev_b32_e32 v38, 16, v47
	v_pk_add_f32 v[38:39], v[44:45], v[38:39]
	s_nop 0
	v_pk_fma_f32 v[36:37], v[36:37], v[40:41], v[38:39]
	global_store_dwordx4 v[48:49], v[34:37], off
	s_nop 1
	v_or_b32_e32 v36, 8, v52
	v_lshlrev_b32_e32 v34, 12, v36
	v_lshlrev_b32_e32 v36, 11, v36
	v_mov_b32_e32 v37, v1
	v_mov_b32_e32 v35, v1
	v_lshl_add_u64 v[36:37], v[30:31], 0, v[36:37]
	v_lshl_add_u64 v[42:43], v[32:33], 0, v[34:35]
	global_load_dwordx2 v[46:47], v[36:37], off
	v_lshl_add_u64 v[48:49], v[28:29], 0, v[34:35]
	ds_read_b128 v[34:37], v0 offset:1152
	global_load_dwordx4 v[38:41], v[26:27], off
	s_nop 0
	global_load_dwordx4 v[42:45], v[42:43], off
	s_waitcnt vmcnt(2)
	v_and_b32_e32 v51, 0xffff0000, v46
	v_lshlrev_b32_e32 v50, 16, v46
	s_waitcnt vmcnt(0)
	v_pk_add_f32 v[42:43], v[42:43], v[50:51]
	s_waitcnt lgkmcnt(0)
	v_pk_fma_f32 v[34:35], v[34:35], v[38:39], v[42:43]
	v_and_b32_e32 v39, 0xffff0000, v47
	v_lshlrev_b32_e32 v38, 16, v47
	v_pk_add_f32 v[38:39], v[44:45], v[38:39]
	s_nop 0
	v_pk_fma_f32 v[36:37], v[36:37], v[40:41], v[38:39]
	global_store_dwordx4 v[48:49], v[34:37], off
	s_nop 1
	v_or_b32_e32 v36, 16, v52
	v_lshlrev_b32_e32 v34, 12, v36
	v_lshlrev_b32_e32 v36, 11, v36
	v_mov_b32_e32 v37, v1
	v_mov_b32_e32 v35, v1
	v_lshl_add_u64 v[36:37], v[30:31], 0, v[36:37]
	v_lshl_add_u64 v[42:43], v[32:33], 0, v[34:35]
	global_load_dwordx2 v[46:47], v[36:37], off
	v_lshl_add_u64 v[48:49], v[28:29], 0, v[34:35]
	ds_read_b128 v[34:37], v0 offset:2304
	global_load_dwordx4 v[38:41], v[26:27], off
	s_nop 0
	global_load_dwordx4 v[42:45], v[42:43], off
	s_waitcnt vmcnt(2)
	v_and_b32_e32 v51, 0xffff0000, v46
	v_lshlrev_b32_e32 v50, 16, v46
	s_waitcnt vmcnt(0)
	v_pk_add_f32 v[42:43], v[42:43], v[50:51]
	s_waitcnt lgkmcnt(0)
	v_pk_fma_f32 v[34:35], v[34:35], v[38:39], v[42:43]
	v_and_b32_e32 v39, 0xffff0000, v47
	v_lshlrev_b32_e32 v38, 16, v47
	v_pk_add_f32 v[38:39], v[44:45], v[38:39]
	s_nop 0
	v_pk_fma_f32 v[36:37], v[36:37], v[40:41], v[38:39]
	v_or_b32_e32 v38, 24, v52
	global_store_dwordx4 v[48:49], v[34:37], off
	s_nop 1
	v_lshlrev_b32_e32 v34, 12, v38
	v_mov_b32_e32 v35, v1
	v_lshl_add_u64 v[36:37], v[32:33], 0, v[34:35]
	v_lshlrev_b32_e32 v32, 11, v38
	v_mov_b32_e32 v33, v1
	v_lshl_add_u64 v[30:31], v[30:31], 0, v[32:33]
	global_load_dwordx2 v[40:41], v[30:31], off
	v_lshl_add_u64 v[42:43], v[28:29], 0, v[34:35]
	ds_read_b128 v[28:31], v0 offset:3456
	global_load_dwordx4 v[32:35], v[26:27], off
	s_nop 0
	global_load_dwordx4 v[36:39], v[36:37], off
	s_waitcnt vmcnt(2)
	v_and_b32_e32 v27, 0xffff0000, v40
	v_lshlrev_b32_e32 v26, 16, v40
	s_waitcnt vmcnt(0)
	v_pk_add_f32 v[26:27], v[36:37], v[26:27]
	s_waitcnt lgkmcnt(0)
	v_pk_fma_f32 v[26:27], v[28:29], v[32:33], v[26:27]
	v_and_b32_e32 v29, 0xffff0000, v41
	v_lshlrev_b32_e32 v28, 16, v41
	v_pk_add_f32 v[28:29], v[38:39], v[28:29]
	s_nop 0
	v_pk_fma_f32 v[28:29], v[30:31], v[34:35], v[28:29]
	global_store_dwordx4 v[42:43], v[26:29], off
	v_mov_b32_e32 v0, v179
	s_nop 0
	v_and_b32_e32 v26, 31, v0
	v_bfe_u32 v27, v0, 5, 1
	v_mul_u32_u24_e32 v27, 0x240, v27
	v_lshlrev_b32_e32 v26, 2, v26
	v_add3_u32 v26, v151, v27, v26
	ds_write2_b32 v26, v2, v3 offset1:36
	ds_write2_b32 v26, v4, v5 offset0:72 offset1:108
	v_add_u32_e32 v2, 0x400, v26
	ds_write2_b32 v2, v6, v7 offset0:32 offset1:68
	ds_write2_b32 v2, v8, v9 offset0:104 offset1:140
	v_add_u32_e32 v2, 0x800, v26
	ds_write2_b32 v2, v10, v11 offset0:64 offset1:100
	ds_write2_b32 v2, v12, v13 offset0:136 offset1:172
	v_add_u32_e32 v2, 0xc00, v26
	ds_write2_b32 v2, v14, v15 offset0:96 offset1:132
	ds_write2_b32 v2, v16, v17 offset0:168 offset1:204
	v_lshlrev_b32_e32 v2, 2, v0
	v_and_b32_e32 v4, 28, v2
	v_lshlrev_b32_e32 v10, 2, v4
	v_lshlrev_b32_e32 v4, 1, v4
	v_mov_b32_e32 v5, v1
	v_bfe_u32 v28, v0, 3, 3
	v_mov_b32_e32 v11, v1
	v_lshl_add_u64 v[6:7], v[18:19], 0, v[4:5]
	v_mul_u32_u24_e32 v0, 0x90, v28
	v_lshlrev_b32_e32 v12, 11, v28
	v_mov_b32_e32 v13, v1
	s_waitcnt lgkmcnt(0)
	v_lshl_add_u64 v[2:3], v[20:21], 0, v[10:11]
	v_lshl_add_u64 v[8:9], v[24:25], 0, v[10:11]
	v_lshl_add_u64 v[4:5], v[22:23], 0, v[10:11]
	v_add3_u32 v0, v151, v10, v0
	v_lshlrev_b32_e32 v10, 12, v28
	v_lshl_add_u64 v[12:13], v[6:7], 0, v[12:13]
	v_lshl_add_u64 v[2:3], v[2:3], 0, v[98:99]
	v_lshl_add_u64 v[18:19], v[8:9], 0, v[10:11]
	global_load_dwordx2 v[22:23], v[12:13], off offset:64
	v_lshl_add_u64 v[24:25], v[4:5], 0, v[10:11]
	ds_read_b128 v[10:13], v0
	global_load_dwordx4 v[14:17], v[2:3], off
	s_nop 0
	global_load_dwordx4 v[18:21], v[18:19], off offset:128
	s_waitcnt vmcnt(2)
	v_and_b32_e32 v27, 0xffff0000, v22
	v_lshlrev_b32_e32 v26, 16, v22
	s_waitcnt vmcnt(0)
	v_pk_add_f32 v[18:19], v[18:19], v[26:27]
	s_waitcnt lgkmcnt(0)
	v_pk_fma_f32 v[10:11], v[10:11], v[14:15], v[18:19]
	v_and_b32_e32 v15, 0xffff0000, v23
	v_lshlrev_b32_e32 v14, 16, v23
	v_pk_add_f32 v[14:15], v[20:21], v[14:15]
	s_nop 0
	v_pk_fma_f32 v[12:13], v[12:13], v[16:17], v[14:15]
	global_store_dwordx4 v[24:25], v[10:13], off offset:128
	s_nop 1
	v_or_b32_e32 v12, 8, v28
	v_lshlrev_b32_e32 v10, 12, v12
	v_lshlrev_b32_e32 v12, 11, v12
	v_mov_b32_e32 v13, v1
	v_mov_b32_e32 v11, v1
	v_lshl_add_u64 v[12:13], v[6:7], 0, v[12:13]
	v_lshl_add_u64 v[18:19], v[8:9], 0, v[10:11]
	global_load_dwordx2 v[22:23], v[12:13], off offset:64
	v_lshl_add_u64 v[24:25], v[4:5], 0, v[10:11]
	ds_read_b128 v[10:13], v0 offset:1152
	global_load_dwordx4 v[14:17], v[2:3], off
	s_nop 0
	global_load_dwordx4 v[18:21], v[18:19], off offset:128
	s_waitcnt vmcnt(2)
	v_and_b32_e32 v27, 0xffff0000, v22
	v_lshlrev_b32_e32 v26, 16, v22
	s_waitcnt vmcnt(0)
	v_pk_add_f32 v[18:19], v[18:19], v[26:27]
	s_waitcnt lgkmcnt(0)
	v_pk_fma_f32 v[10:11], v[10:11], v[14:15], v[18:19]
	v_and_b32_e32 v15, 0xffff0000, v23
	v_lshlrev_b32_e32 v14, 16, v23
	v_pk_add_f32 v[14:15], v[20:21], v[14:15]
	s_nop 0
	v_pk_fma_f32 v[12:13], v[12:13], v[16:17], v[14:15]
	global_store_dwordx4 v[24:25], v[10:13], off offset:128
	s_nop 1
	v_or_b32_e32 v12, 16, v28
	v_lshlrev_b32_e32 v10, 12, v12
	v_lshlrev_b32_e32 v12, 11, v12
	v_mov_b32_e32 v13, v1
	v_mov_b32_e32 v11, v1
	v_lshl_add_u64 v[12:13], v[6:7], 0, v[12:13]
	v_lshl_add_u64 v[18:19], v[8:9], 0, v[10:11]
	global_load_dwordx2 v[22:23], v[12:13], off offset:64
	v_lshl_add_u64 v[24:25], v[4:5], 0, v[10:11]
	ds_read_b128 v[10:13], v0 offset:2304
	global_load_dwordx4 v[14:17], v[2:3], off
	s_nop 0
	global_load_dwordx4 v[18:21], v[18:19], off offset:128
	s_waitcnt vmcnt(2)
	v_and_b32_e32 v27, 0xffff0000, v22
	v_lshlrev_b32_e32 v26, 16, v22
	s_waitcnt vmcnt(0)
	v_pk_add_f32 v[18:19], v[18:19], v[26:27]
	s_waitcnt lgkmcnt(0)
	v_pk_fma_f32 v[10:11], v[10:11], v[14:15], v[18:19]
	v_and_b32_e32 v15, 0xffff0000, v23
	v_lshlrev_b32_e32 v14, 16, v23
	v_pk_add_f32 v[14:15], v[20:21], v[14:15]
	s_nop 0
	v_pk_fma_f32 v[12:13], v[12:13], v[16:17], v[14:15]
	v_or_b32_e32 v14, 24, v28
	global_store_dwordx4 v[24:25], v[10:13], off offset:128
	s_nop 1
	v_lshlrev_b32_e32 v10, 12, v14
	v_mov_b32_e32 v11, v1
	v_lshl_add_u64 v[12:13], v[8:9], 0, v[10:11]
	v_lshlrev_b32_e32 v8, 11, v14
	v_mov_b32_e32 v9, v1
	v_lshl_add_u64 v[6:7], v[6:7], 0, v[8:9]
	global_load_dwordx2 v[16:17], v[6:7], off offset:64
	v_lshl_add_u64 v[18:19], v[4:5], 0, v[10:11]
	ds_read_b128 v[4:7], v0 offset:3456
	global_load_dwordx4 v[8:11], v[2:3], off
	s_nop 0
	global_load_dwordx4 v[12:15], v[12:13], off offset:128
	s_waitcnt vmcnt(2)
	v_and_b32_e32 v3, 0xffff0000, v16
	v_lshlrev_b32_e32 v2, 16, v16
	s_waitcnt vmcnt(0)
	v_pk_add_f32 v[2:3], v[12:13], v[2:3]
	s_waitcnt lgkmcnt(0)
	v_pk_fma_f32 v[2:3], v[4:5], v[8:9], v[2:3]
	v_and_b32_e32 v5, 0xffff0000, v17
	v_lshlrev_b32_e32 v4, 16, v17
	v_pk_add_f32 v[4:5], v[14:15], v[4:5]
	s_nop 0
	v_pk_fma_f32 v[4:5], v[6:7], v[10:11], v[4:5]
	global_store_dwordx4 v[18:19], v[2:5], off offset:128
	s_add_i32 s7, s7, s6
	s_cmpk_gt_i32 s7, 0x1ff
	v_readlane_b32 s64, v254, 55
	v_readlane_b32 s38, v254, 57
	v_readlane_b32 s42, v254, 59
	s_cselect_b64 s[0:1], -1, 0
	v_readlane_b32 s65, v254, 56
	v_readlane_b32 s39, v254, 58
	v_readlane_b32 s43, v254, 60
	s_mov_b32 s51, s27
	s_movk_i32 s37, 0x1000
	s_movk_i32 s36, 0x1ff
	s_mov_b32 s47, 0x7f800000
	s_mov_b32 s49, 0x20000
	s_mov_b32 s46, 0x4081e0d3
	s_mov_b32 s48, 0xc09de9e6
	s_mov_b64 s[44:45], 0x800
	s_branch .LBB0_21

.LBB0_293:
	s_add_i32 s2, s11, s12
	s_cmpk_gt_i32 s2, 0xcb1
	s_mov_b64 s[0:1], -1
	s_cbranch_scc1 .LBB0_292
	s_mul_hi_i32 s0, s2, 0x51eb851f
	s_lshr_b32 s1, s0, 31
	s_ashr_i32 s0, s0, 6
	s_add_i32 s0, s0, s1
	s_lshl_b32 s1, s0, 3
	s_sub_i32 s3, 0x82, s1
	s_min_u32 s3, s3, 8
	v_cvt_f32_ubyte0_e32 v0, s3
	v_rcp_iflag_f32_e32 v0, v0
	s_sub_i32 s5, 0, s3
	s_mulk_i32 s0, 0xff38
	s_add_i32 s0, s0, s2
	v_mul_f32_e32 v0, 0x4f7ffffe, v0
	v_cvt_u32_f32_e32 v0, v0
	s_abs_i32 s4, s0
	s_ashr_i32 s2, s0, 31
	v_readlane_b32 s16, v251, 2
	v_readfirstlane_b32 s7, v0
	s_mul_i32 s5, s5, s7
	s_mul_hi_u32 s5, s7, s5
	s_add_i32 s7, s7, s5
	s_mul_hi_u32 s5, s4, s7
	s_mul_i32 s7, s5, s3
	s_sub_i32 s4, s4, s7
	s_add_i32 s7, s5, 1
	s_sub_i32 s8, s4, s3
	s_cmp_ge_u32 s4, s3
	s_cselect_b32 s5, s7, s5
	s_cselect_b32 s4, s8, s4
	s_add_i32 s7, s5, 1
	s_cmp_ge_u32 s4, s3
	s_cselect_b32 s4, s7, s5
	s_xor_b32 s4, s4, s2
	s_sub_i32 s4, s4, s2
	s_mul_i32 s2, s4, s3
	s_sub_i32 s0, s0, s2
	s_add_i32 s0, s0, s1
	s_lshl_b32 s0, s0, 8
	s_lshl_b32 s4, s4, 8
	s_ashr_i32 s1, s0, 31
	s_ashr_i32 s5, s4, 31
	s_lshl_b64 s[2:3], s[0:1], 11
	s_lshl_b64 s[8:9], s[4:5], 11
	v_readlane_b32 s28, v251, 14
	v_readlane_b32 s29, v251, 15
	s_add_u32 s14, s28, s2
	v_mov_b32_e32 v0, v142
	s_addc_u32 s15, s29, s3
	s_waitcnt vmcnt(63) expcnt(7) lgkmcnt(15)
	s_barrier
	v_readlane_b32 s17, v251, 3
	v_lshl_add_u64 v[2:3], v[0:1], 1, s[14:15]
	v_add_u32_e32 v0, 32, v143
	v_readlane_b32 s16, v251, 42
	v_readfirstlane_b32 s1, v0
	s_mov_b32 m0, s1
	v_mov_b32_e32 v0, v144
	global_load_lds_dwordx4 v[2:3], off
	v_readlane_b32 s17, v251, 43
	v_lshl_add_u64 v[2:3], v[0:1], 1, s[14:15]
	v_add_u32_e32 v0, 32, v145
	s_add_u32 s16, s16, s8
	v_readfirstlane_b32 s1, v0
	s_mov_b32 m0, s1
	v_mov_b32_e32 v0, v146
	global_load_lds_dwordx4 v[2:3], off
	s_addc_u32 s17, s17, s9
	v_lshl_add_u64 v[2:3], v[0:1], 1, s[14:15]
	v_add_u32_e32 v0, 32, v147
	v_readlane_b32 s5, v254, 3
	v_readfirstlane_b32 s1, v0
	s_mov_b32 m0, s1
	v_mov_b32_e32 v0, v148
	global_load_lds_dwordx4 v[2:3], off
	s_mov_b32 s6, 0
	v_lshl_add_u64 v[2:3], v[0:1], 1, s[14:15]
	v_add_u32_e32 v0, 32, v149
	v_readlane_b32 s18, v251, 4
	v_readfirstlane_b32 s1, v0
	s_mov_b32 m0, s1
	v_mov_b32_e32 v0, v142
	global_load_lds_dwordx4 v[2:3], off
	v_readlane_b32 s19, v251, 5
	v_lshl_add_u64 v[2:3], v[0:1], 1, s[16:17]
	v_add_u32_e32 v0, s5, v143
	v_readlane_b32 s20, v251, 6
	v_readfirstlane_b32 s1, v0
	s_mov_b32 m0, s1
	v_mov_b32_e32 v0, v144
	global_load_lds_dwordx4 v[2:3], off
	v_readlane_b32 s21, v251, 7
	v_lshl_add_u64 v[2:3], v[0:1], 1, s[16:17]
	v_add_u32_e32 v0, s5, v145
	v_readlane_b32 s22, v251, 8
	v_readfirstlane_b32 s1, v0
	s_mov_b32 m0, s1
	v_mov_b32_e32 v0, v146
	global_load_lds_dwordx4 v[2:3], off
	v_readlane_b32 s23, v251, 9
	v_lshl_add_u64 v[2:3], v[0:1], 1, s[16:17]
	v_add_u32_e32 v0, s5, v147
	v_readlane_b32 s24, v251, 10
	v_readfirstlane_b32 s1, v0
	s_mov_b32 m0, s1
	v_mov_b32_e32 v0, v148
	global_load_lds_dwordx4 v[2:3], off
	v_readlane_b32 s25, v251, 11
	v_lshl_add_u64 v[2:3], v[0:1], 1, s[16:17]
	v_add_u32_e32 v0, s5, v149
	v_readlane_b32 s26, v251, 12
	v_readfirstlane_b32 s1, v0
	s_mov_b32 m0, s1
	v_readlane_b32 s1, v253, 29
	global_load_lds_dwordx4 v[2:3], off
	s_add_u32 s1, s1, s2
	v_readlane_b32 s2, v253, 30
	s_waitcnt vmcnt(0)
	s_addc_u32 s5, s2, s3
	v_readlane_b32 s2, v253, 31
	s_add_u32 s7, s2, s8
	v_readlane_b32 s2, v253, 32
	v_mov_b32_e32 v2, 0
	s_addc_u32 s8, s2, s9
	s_mov_b64 s[2:3], 0
	v_mov_b32_e32 v3, v2
	v_mov_b32_e32 v4, v2
	v_mov_b32_e32 v5, v2
	v_mov_b32_e32 v6, v2
	v_mov_b32_e32 v7, v2
	v_mov_b32_e32 v8, v2
	v_mov_b32_e32 v9, v2
	v_mov_b32_e32 v10, v2
	v_mov_b32_e32 v11, v2
	v_mov_b32_e32 v12, v2
	v_mov_b32_e32 v13, v2
	s_waitcnt vmcnt(0)
	v_mov_b32_e32 v14, v2
	v_mov_b32_e32 v15, v2
	v_mov_b32_e32 v16, v2
	v_mov_b32_e32 v17, v2
	v_mov_b32_e32 v18, v2
	v_mov_b32_e32 v19, v2
	v_mov_b32_e32 v20, v2
	v_mov_b32_e32 v21, v2
	v_mov_b32_e32 v22, v2
	v_mov_b32_e32 v23, v2
	v_mov_b32_e32 v24, v2
	v_mov_b32_e32 v25, v2
	v_mov_b32_e32 v26, v2
	v_mov_b32_e32 v27, v2
	v_mov_b32_e32 v28, v2
	v_mov_b32_e32 v29, v2
	v_mov_b32_e32 v30, v2
	v_mov_b32_e32 v31, v2
	v_mov_b32_e32 v32, v2
	v_mov_b32_e32 v33, v2
	v_mov_b32_e32 v34, v2
	v_mov_b32_e32 v35, v2
	v_mov_b32_e32 v36, v2
	v_mov_b32_e32 v37, v2
	v_mov_b32_e32 v38, v2
	v_mov_b32_e32 v39, v2
	v_mov_b32_e32 v40, v2
	v_mov_b32_e32 v41, v2
	v_mov_b32_e32 v42, v2
	v_mov_b32_e32 v43, v2
	v_mov_b32_e32 v44, v2
	v_mov_b32_e32 v45, v2
	v_mov_b32_e32 v46, v2
	v_mov_b32_e32 v47, v2
	v_mov_b32_e32 v48, v2
	v_mov_b32_e32 v49, v2
	v_mov_b32_e32 v50, v2
	v_mov_b32_e32 v51, v2
	v_mov_b32_e32 v52, v2
	v_mov_b32_e32 v53, v2
	v_mov_b32_e32 v54, v2
	v_mov_b32_e32 v55, v2
	v_mov_b32_e32 v56, v2
	v_mov_b32_e32 v57, v2
	v_mov_b32_e32 v58, v2
	v_mov_b32_e32 v59, v2
	v_mov_b32_e32 v60, v2
	v_mov_b32_e32 v61, v2
	v_mov_b32_e32 v62, v2
	v_mov_b32_e32 v63, v2
	v_mov_b32_e32 v64, v2
	v_mov_b32_e32 v65, v2
	v_mov_b32_e32 v66, v2
	v_mov_b32_e32 v67, v2
	v_mov_b32_e32 v68, v2
	v_mov_b32_e32 v69, v2
	v_mov_b32_e32 v70, v2
	v_mov_b32_e32 v71, v2
	v_mov_b32_e32 v72, v2
	v_mov_b32_e32 v73, v2
	v_mov_b32_e32 v74, v2
	v_mov_b32_e32 v75, v2
	v_mov_b32_e32 v76, v2
	v_mov_b32_e32 v77, v2
	v_mov_b32_e32 v78, v2
	v_mov_b32_e32 v79, v2
	v_mov_b32_e32 v80, v2
	v_mov_b32_e32 v81, v2
	v_mov_b32_e32 v82, v2
	v_mov_b32_e32 v83, v2
	v_mov_b32_e32 v84, v2
	v_mov_b32_e32 v85, v2
	v_mov_b32_e32 v86, v2
	v_mov_b32_e32 v87, v2
	v_mov_b32_e32 v88, v2
	v_mov_b32_e32 v89, v2
	v_mov_b32_e32 v90, v2
	v_mov_b32_e32 v91, v2
	v_mov_b32_e32 v92, v2
	v_mov_b32_e32 v93, v2
	v_mov_b32_e32 v94, v2
	v_mov_b32_e32 v95, v2
	v_mov_b32_e32 v96, v2
	v_mov_b32_e32 v97, v2
	v_mov_b32_e32 v98, v2
	v_mov_b32_e32 v99, v2
	v_mov_b32_e32 v100, v2
	v_mov_b32_e32 v101, v2
	v_mov_b32_e32 v102, v2
	v_mov_b32_e32 v103, v2
	v_mov_b32_e32 v104, v2
	v_mov_b32_e32 v105, v2
	v_mov_b32_e32 v106, v2
	v_mov_b32_e32 v107, v2
	v_mov_b32_e32 v108, v2
	v_mov_b32_e32 v109, v2
	v_mov_b32_e32 v110, v2
	v_mov_b32_e32 v111, v2
	v_mov_b32_e32 v112, v2
	v_mov_b32_e32 v113, v2
	v_mov_b32_e32 v114, v2
	v_mov_b32_e32 v115, v2
	v_mov_b32_e32 v116, v2
	v_mov_b32_e32 v117, v2
	v_mov_b32_e32 v118, v2
	v_mov_b32_e32 v119, v2
	v_mov_b32_e32 v120, v2
	v_mov_b32_e32 v121, v2
	v_mov_b32_e32 v122, v2
	v_mov_b32_e32 v123, v2
	v_mov_b32_e32 v124, v2
	v_mov_b32_e32 v125, v2
	v_mov_b32_e32 v126, v2
	v_mov_b32_e32 v127, v2
	v_mov_b32_e32 v128, v2
	v_mov_b32_e32 v129, v2
	v_readlane_b32 s27, v251, 13
	v_readlane_b32 s30, v251, 16
	v_readlane_b32 s31, v251, 17
	s_waitcnt lgkmcnt(0)
	s_barrier
	v_lshlrev_b32_e32 v159, 1, v142
	v_readfirstlane_b32 s9, v143
	v_add_u32_e32 v177, v150, v152
	v_add_u32_e32 v207, v151, v152
	v_add_u32_e32 v204, v150, v156
	v_add_u32_e32 v208, v151, v156
	v_add_u32_e32 v205, v150, v157
	v_add_u32_e32 v209, v151, v157
	v_add_u32_e32 v206, v150, v158
	v_add_u32_e32 v210, v151, v158
	s_nop 1
	s_add_u32 m0, s9, 0x8020
	s_add_u32 s14, s1, s2
	s_addc_u32 s15, s5, s3
	global_load_lds_dwordx4 v159, s[14:15]
	s_add_u32 m0, s9, 0xa020
	s_add_u32 s14, s14, 0x20000
	s_addc_u32 s15, s15, 0
	global_load_lds_dwordx4 v159, s[14:15]
	s_add_u32 m0, s9, 0xc020
	s_add_u32 s14, s14, 0x20000
	s_addc_u32 s15, s15, 0
	global_load_lds_dwordx4 v159, s[14:15]
	s_add_u32 m0, s9, 0xe020
	s_add_u32 s14, s14, 0x20000
	s_addc_u32 s15, s15, 0
	global_load_lds_dwordx4 v159, s[14:15]
	s_add_u32 m0, s9, 0x18020
	s_add_u32 s14, s7, s2
	s_addc_u32 s15, s8, s3
	global_load_lds_dwordx4 v159, s[14:15]
	s_add_u32 m0, s9, 0x1a020
	s_add_u32 s14, s14, 0x20000
	s_addc_u32 s15, s15, 0
	global_load_lds_dwordx4 v159, s[14:15]
	s_add_u32 m0, s9, 0x1c020
	s_add_u32 s14, s14, 0x20000
	s_addc_u32 s15, s15, 0
	global_load_lds_dwordx4 v159, s[14:15]
	s_add_u32 m0, s9, 0x1e020
	s_add_u32 s14, s14, 0x20000
	s_addc_u32 s15, s15, 0
	global_load_lds_dwordx4 v159, s[14:15]
	s_add_u32 s2, s2, 0x80
	s_addc_u32 s3, s3, 0
	ds_read_b128 v[130:133], v177 offset:0
	ds_read_b128 v[164:167], v207 offset:0
	ds_read_b128 v[168:171], v207 offset:4096
	ds_read_b128 v[134:137], v177 offset:4096
	ds_read_b128 v[138:141], v177 offset:8192
	ds_read_b128 v[160:163], v177 offset:12288
.Lg295_loop:
	s_waitcnt lgkmcnt(4)
	v_mfma_f32_32x32x16_bf16 v[114:129], v[130:133], v[164:167], v[114:129]
	ds_read_b128 v[172:175], v204 offset:0
	s_waitcnt lgkmcnt(4)
	v_mfma_f32_32x32x16_bf16 v[98:113], v[130:133], v[168:171], v[98:113]
	ds_read_b128 v[192:195], v208 offset:0
	s_waitcnt lgkmcnt(4)
	v_mfma_f32_32x32x16_bf16 v[82:97], v[134:137], v[164:167], v[82:97]
	ds_read_b128 v[200:203], v208 offset:4096
	v_mfma_f32_32x32x16_bf16 v[66:81], v[134:137], v[168:171], v[66:81]
	ds_read_b128 v[180:183], v204 offset:4096
	s_waitcnt lgkmcnt(5)
	v_mfma_f32_32x32x16_bf16 v[50:65], v[138:141], v[164:167], v[50:65]
	ds_read_b128 v[184:187], v204 offset:8192
	v_mfma_f32_32x32x16_bf16 v[34:49], v[138:141], v[168:171], v[34:49]
	ds_read_b128 v[188:191], v204 offset:12288
	s_waitcnt lgkmcnt(6)
	v_mfma_f32_32x32x16_bf16 v[18:33], v[160:163], v[164:167], v[18:33]
	v_mfma_f32_32x32x16_bf16 v[2:17], v[160:163], v[168:171], v[2:17]
	s_waitcnt lgkmcnt(4)
	v_mfma_f32_32x32x16_bf16 v[114:129], v[172:175], v[192:195], v[114:129]
	ds_read_b128 v[130:133], v205 offset:0
	s_waitcnt lgkmcnt(4)
	v_mfma_f32_32x32x16_bf16 v[98:113], v[172:175], v[200:203], v[98:113]
	ds_read_b128 v[164:167], v209 offset:0
	s_waitcnt lgkmcnt(4)
	v_mfma_f32_32x32x16_bf16 v[82:97], v[180:183], v[192:195], v[82:97]
	ds_read_b128 v[168:171], v209 offset:4096
	v_mfma_f32_32x32x16_bf16 v[66:81], v[180:183], v[200:203], v[66:81]
	ds_read_b128 v[134:137], v205 offset:4096
	s_waitcnt lgkmcnt(5)
	v_mfma_f32_32x32x16_bf16 v[50:65], v[184:187], v[192:195], v[50:65]
	ds_read_b128 v[138:141], v205 offset:8192
	v_mfma_f32_32x32x16_bf16 v[34:49], v[184:187], v[200:203], v[34:49]
	ds_read_b128 v[160:163], v205 offset:12288
	s_waitcnt lgkmcnt(6)
	v_mfma_f32_32x32x16_bf16 v[18:33], v[188:191], v[192:195], v[18:33]
	v_mfma_f32_32x32x16_bf16 v[2:17], v[188:191], v[200:203], v[2:17]
	s_waitcnt lgkmcnt(4)
	v_mfma_f32_32x32x16_bf16 v[114:129], v[130:133], v[164:167], v[114:129]
	ds_read_b128 v[172:175], v206 offset:0
	ds_read_b128 v[192:195], v210 offset:0
	s_waitcnt lgkmcnt(5)
	v_mfma_f32_32x32x16_bf16 v[98:113], v[130:133], v[168:171], v[98:113]
	ds_read_b128 v[200:203], v210 offset:4096
	ds_read_b128 v[180:183], v206 offset:4096
	s_waitcnt lgkmcnt(6)
	v_mfma_f32_32x32x16_bf16 v[82:97], v[134:137], v[164:167], v[82:97]
	ds_read_b128 v[184:187], v206 offset:8192
	ds_read_b128 v[188:191], v206 offset:12288
	v_mfma_f32_32x32x16_bf16 v[66:81], v[134:137], v[168:171], v[66:81]
	s_waitcnt lgkmcnt(7)
	v_mfma_f32_32x32x16_bf16 v[50:65], v[138:141], v[164:167], v[50:65]
	v_mfma_f32_32x32x16_bf16 v[34:49], v[138:141], v[168:171], v[34:49]
	s_waitcnt lgkmcnt(6)
	v_mfma_f32_32x32x16_bf16 v[18:33], v[160:163], v[164:167], v[18:33]
	v_mfma_f32_32x32x16_bf16 v[2:17], v[160:163], v[168:171], v[2:17]
	s_waitcnt vmcnt(0) lgkmcnt(0)
	s_barrier
	s_cmp_lt_u32 s2, 0x780
	s_cbranch_scc0 .Lg295_nodma0
	v_mfma_f32_32x32x16_bf16 v[114:129], v[172:175], v[192:195], v[114:129]
	ds_read_b128 v[130:133], v177 offset:32768
	s_add_u32 m0, s9, 0x20
	s_add_u32 s14, s1, s2
	s_addc_u32 s15, s5, s3
	global_load_lds_dwordx4 v159, s[14:15]
	v_mfma_f32_32x32x16_bf16 v[98:113], v[172:175], v[200:203], v[98:113]
	ds_read_b128 v[164:167], v207 offset:32768
	s_add_u32 m0, s9, 0x2020
	s_add_u32 s14, s14, 0x20000
	s_addc_u32 s15, s15, 0
	global_load_lds_dwordx4 v159, s[14:15]
	v_mfma_f32_32x32x16_bf16 v[82:97], v[180:183], v[192:195], v[82:97]
	ds_read_b128 v[168:171], v207 offset:36864
	s_add_u32 m0, s9, 0x4020
	s_add_u32 s14, s14, 0x20000
	s_addc_u32 s15, s15, 0
	global_load_lds_dwordx4 v159, s[14:15]
	v_mfma_f32_32x32x16_bf16 v[66:81], v[180:183], v[200:203], v[66:81]
	ds_read_b128 v[134:137], v177 offset:36864
	s_add_u32 m0, s9, 0x6020
	s_add_u32 s14, s14, 0x20000
	s_addc_u32 s15, s15, 0
	global_load_lds_dwordx4 v159, s[14:15]
	v_mfma_f32_32x32x16_bf16 v[50:65], v[184:187], v[192:195], v[50:65]
	ds_read_b128 v[138:141], v177 offset:40960
	s_add_u32 m0, s9, 0x10020
	s_add_u32 s14, s7, s2
	s_addc_u32 s15, s8, s3
	global_load_lds_dwordx4 v159, s[14:15]
	v_mfma_f32_32x32x16_bf16 v[34:49], v[184:187], v[200:203], v[34:49]
	ds_read_b128 v[160:163], v177 offset:45056
	s_add_u32 m0, s9, 0x12020
	s_add_u32 s14, s14, 0x20000
	s_addc_u32 s15, s15, 0
	global_load_lds_dwordx4 v159, s[14:15]
	v_mfma_f32_32x32x16_bf16 v[18:33], v[188:191], v[192:195], v[18:33]
	s_add_u32 m0, s9, 0x14020
	s_add_u32 s14, s14, 0x20000
	s_addc_u32 s15, s15, 0
	global_load_lds_dwordx4 v159, s[14:15]
	v_mfma_f32_32x32x16_bf16 v[2:17], v[188:191], v[200:203], v[2:17]
	s_add_u32 m0, s9, 0x16020
	s_add_u32 s14, s14, 0x20000
	s_addc_u32 s15, s15, 0
	global_load_lds_dwordx4 v159, s[14:15]
	s_add_u32 s2, s2, 0x80
	s_addc_u32 s3, s3, 0
	s_branch .Lg295_join0
.Lg295_nodma0:
	s_add_u32 s2, s2, 0x80
	s_addc_u32 s3, s3, 0
	v_mfma_f32_32x32x16_bf16 v[114:129], v[172:175], v[192:195], v[114:129]
	ds_read_b128 v[130:133], v177 offset:32768
	v_mfma_f32_32x32x16_bf16 v[98:113], v[172:175], v[200:203], v[98:113]
	ds_read_b128 v[164:167], v207 offset:32768
	v_mfma_f32_32x32x16_bf16 v[82:97], v[180:183], v[192:195], v[82:97]
	ds_read_b128 v[168:171], v207 offset:36864
	v_mfma_f32_32x32x16_bf16 v[66:81], v[180:183], v[200:203], v[66:81]
	ds_read_b128 v[134:137], v177 offset:36864
	v_mfma_f32_32x32x16_bf16 v[50:65], v[184:187], v[192:195], v[50:65]
	ds_read_b128 v[138:141], v177 offset:40960
	v_mfma_f32_32x32x16_bf16 v[34:49], v[184:187], v[200:203], v[34:49]
	ds_read_b128 v[160:163], v177 offset:45056
	v_mfma_f32_32x32x16_bf16 v[18:33], v[188:191], v[192:195], v[18:33]
	v_mfma_f32_32x32x16_bf16 v[2:17], v[188:191], v[200:203], v[2:17]
.Lg295_join0:
	s_waitcnt lgkmcnt(4)
	v_mfma_f32_32x32x16_bf16 v[114:129], v[130:133], v[164:167], v[114:129]
	ds_read_b128 v[172:175], v204 offset:32768
	s_waitcnt lgkmcnt(4)
	v_mfma_f32_32x32x16_bf16 v[98:113], v[130:133], v[168:171], v[98:113]
	ds_read_b128 v[192:195], v208 offset:32768
	s_waitcnt lgkmcnt(4)
	v_mfma_f32_32x32x16_bf16 v[82:97], v[134:137], v[164:167], v[82:97]
	ds_read_b128 v[200:203], v208 offset:36864
	v_mfma_f32_32x32x16_bf16 v[66:81], v[134:137], v[168:171], v[66:81]
	ds_read_b128 v[180:183], v204 offset:36864
	s_waitcnt lgkmcnt(5)
	v_mfma_f32_32x32x16_bf16 v[50:65], v[138:141], v[164:167], v[50:65]
	ds_read_b128 v[184:187], v204 offset:40960
	v_mfma_f32_32x32x16_bf16 v[34:49], v[138:141], v[168:171], v[34:49]
	ds_read_b128 v[188:191], v204 offset:45056
	s_waitcnt lgkmcnt(6)
	v_mfma_f32_32x32x16_bf16 v[18:33], v[160:163], v[164:167], v[18:33]
	v_mfma_f32_32x32x16_bf16 v[2:17], v[160:163], v[168:171], v[2:17]
	s_waitcnt lgkmcnt(4)
	v_mfma_f32_32x32x16_bf16 v[114:129], v[172:175], v[192:195], v[114:129]
	ds_read_b128 v[130:133], v205 offset:32768
	s_waitcnt lgkmcnt(4)
	v_mfma_f32_32x32x16_bf16 v[98:113], v[172:175], v[200:203], v[98:113]
	ds_read_b128 v[164:167], v209 offset:32768
	s_waitcnt lgkmcnt(4)
	v_mfma_f32_32x32x16_bf16 v[82:97], v[180:183], v[192:195], v[82:97]
	ds_read_b128 v[168:171], v209 offset:36864
	v_mfma_f32_32x32x16_bf16 v[66:81], v[180:183], v[200:203], v[66:81]
	ds_read_b128 v[134:137], v205 offset:36864
	s_waitcnt lgkmcnt(5)
	v_mfma_f32_32x32x16_bf16 v[50:65], v[184:187], v[192:195], v[50:65]
	ds_read_b128 v[138:141], v205 offset:40960
	v_mfma_f32_32x32x16_bf16 v[34:49], v[184:187], v[200:203], v[34:49]
	ds_read_b128 v[160:163], v205 offset:45056
	s_waitcnt lgkmcnt(6)
	v_mfma_f32_32x32x16_bf16 v[18:33], v[188:191], v[192:195], v[18:33]
	v_mfma_f32_32x32x16_bf16 v[2:17], v[188:191], v[200:203], v[2:17]
	s_waitcnt lgkmcnt(4)
	v_mfma_f32_32x32x16_bf16 v[114:129], v[130:133], v[164:167], v[114:129]
	ds_read_b128 v[172:175], v206 offset:32768
	ds_read_b128 v[192:195], v210 offset:32768
	s_waitcnt lgkmcnt(5)
	v_mfma_f32_32x32x16_bf16 v[98:113], v[130:133], v[168:171], v[98:113]
	ds_read_b128 v[200:203], v210 offset:36864
	ds_read_b128 v[180:183], v206 offset:36864
	s_waitcnt lgkmcnt(6)
	v_mfma_f32_32x32x16_bf16 v[82:97], v[134:137], v[164:167], v[82:97]
	ds_read_b128 v[184:187], v206 offset:40960
	ds_read_b128 v[188:191], v206 offset:45056
	v_mfma_f32_32x32x16_bf16 v[66:81], v[134:137], v[168:171], v[66:81]
	s_waitcnt lgkmcnt(7)
	v_mfma_f32_32x32x16_bf16 v[50:65], v[138:141], v[164:167], v[50:65]
	v_mfma_f32_32x32x16_bf16 v[34:49], v[138:141], v[168:171], v[34:49]
	s_waitcnt lgkmcnt(6)
	v_mfma_f32_32x32x16_bf16 v[18:33], v[160:163], v[164:167], v[18:33]
	v_mfma_f32_32x32x16_bf16 v[2:17], v[160:163], v[168:171], v[2:17]
	s_waitcnt vmcnt(0) lgkmcnt(0)
	s_barrier
	s_cmp_lt_u32 s2, 0x780
	s_cbranch_scc0 .Lg295_nodma1
	v_mfma_f32_32x32x16_bf16 v[114:129], v[172:175], v[192:195], v[114:129]
	ds_read_b128 v[130:133], v177 offset:0
	s_add_u32 m0, s9, 0x8020
	s_add_u32 s14, s1, s2
	s_addc_u32 s15, s5, s3
	global_load_lds_dwordx4 v159, s[14:15]
	v_mfma_f32_32x32x16_bf16 v[98:113], v[172:175], v[200:203], v[98:113]
	ds_read_b128 v[164:167], v207 offset:0
	s_add_u32 m0, s9, 0xa020
	s_add_u32 s14, s14, 0x20000
	s_addc_u32 s15, s15, 0
	global_load_lds_dwordx4 v159, s[14:15]
	v_mfma_f32_32x32x16_bf16 v[82:97], v[180:183], v[192:195], v[82:97]
	ds_read_b128 v[168:171], v207 offset:4096
	s_add_u32 m0, s9, 0xc020
	s_add_u32 s14, s14, 0x20000
	s_addc_u32 s15, s15, 0
	global_load_lds_dwordx4 v159, s[14:15]
	v_mfma_f32_32x32x16_bf16 v[66:81], v[180:183], v[200:203], v[66:81]
	ds_read_b128 v[134:137], v177 offset:4096
	s_add_u32 m0, s9, 0xe020
	s_add_u32 s14, s14, 0x20000
	s_addc_u32 s15, s15, 0
	global_load_lds_dwordx4 v159, s[14:15]
	v_mfma_f32_32x32x16_bf16 v[50:65], v[184:187], v[192:195], v[50:65]
	ds_read_b128 v[138:141], v177 offset:8192
	s_add_u32 m0, s9, 0x18020
	s_add_u32 s14, s7, s2
	s_addc_u32 s15, s8, s3
	global_load_lds_dwordx4 v159, s[14:15]
	v_mfma_f32_32x32x16_bf16 v[34:49], v[184:187], v[200:203], v[34:49]
	ds_read_b128 v[160:163], v177 offset:12288
	s_add_u32 m0, s9, 0x1a020
	s_add_u32 s14, s14, 0x20000
	s_addc_u32 s15, s15, 0
	global_load_lds_dwordx4 v159, s[14:15]
	v_mfma_f32_32x32x16_bf16 v[18:33], v[188:191], v[192:195], v[18:33]
	s_add_u32 m0, s9, 0x1c020
	s_add_u32 s14, s14, 0x20000
	s_addc_u32 s15, s15, 0
	global_load_lds_dwordx4 v159, s[14:15]
	v_mfma_f32_32x32x16_bf16 v[2:17], v[188:191], v[200:203], v[2:17]
	s_add_u32 m0, s9, 0x1e020
	s_add_u32 s14, s14, 0x20000
	s_addc_u32 s15, s15, 0
	global_load_lds_dwordx4 v159, s[14:15]
	s_add_u32 s2, s2, 0x80
	s_addc_u32 s3, s3, 0
	s_branch .Lg295_join1
.Lg295_nodma1:
	s_add_u32 s2, s2, 0x80
	s_addc_u32 s3, s3, 0
	v_mfma_f32_32x32x16_bf16 v[114:129], v[172:175], v[192:195], v[114:129]
	ds_read_b128 v[130:133], v177 offset:0
	v_mfma_f32_32x32x16_bf16 v[98:113], v[172:175], v[200:203], v[98:113]
	ds_read_b128 v[164:167], v207 offset:0
	v_mfma_f32_32x32x16_bf16 v[82:97], v[180:183], v[192:195], v[82:97]
	ds_read_b128 v[168:171], v207 offset:4096
	v_mfma_f32_32x32x16_bf16 v[66:81], v[180:183], v[200:203], v[66:81]
	ds_read_b128 v[134:137], v177 offset:4096
	v_mfma_f32_32x32x16_bf16 v[50:65], v[184:187], v[192:195], v[50:65]
	ds_read_b128 v[138:141], v177 offset:8192
	v_mfma_f32_32x32x16_bf16 v[34:49], v[184:187], v[200:203], v[34:49]
	ds_read_b128 v[160:163], v177 offset:12288
	v_mfma_f32_32x32x16_bf16 v[18:33], v[188:191], v[192:195], v[18:33]
	v_mfma_f32_32x32x16_bf16 v[2:17], v[188:191], v[200:203], v[2:17]
.Lg295_join1:
	s_cmp_lt_u32 s2, 0x880
	s_cbranch_scc1 .Lg295_loop
	s_waitcnt lgkmcnt(0)
	v_add_u32_e32 v159, s0, v153
	s_mov_b32 s0, 0x7e07e07f
	v_mul_hi_i32 v0, v159, s0
	v_lshrrev_b32_e32 v133, 31, v0
	v_ashrrev_i32_e32 v0, 13, v0
	v_add_u32_e32 v134, v0, v133
	v_mul_i32_i24_e32 v0, 0x4100, v134
	v_sub_u32_e32 v136, v159, v0
	s_movk_i32 s0, 0x100
	v_cmp_gt_i32_e64 s[56:57], s0, v136
	v_ashrrev_i32_e32 v137, 31, v136
	s_mov_b32 s0, 0xfff00000
	s_waitcnt vmcnt(0)
	v_ashrrev_i32_e32 v130, 7, v159
	v_lshlrev_b64 v[136:137], 12, v[136:137]
	s_mov_b32 s1, -1
	v_or_b32_e32 v132, s4, v154
	v_ashrrev_i32_e32 v131, 31, v130
	v_ashrrev_i32_e32 v135, 31, v134
	v_lshl_add_u64 v[136:137], v[136:137], 0, s[0:1]
	s_movk_i32 s0, 0x1840
	v_lshlrev_b64 v[130:131], 14, v[130:131]
	v_lshlrev_b64 v[134:135], 26, v[134:135]
	v_mov_b32_e32 v161, v179
	v_cmp_gt_i32_e64 s[54:55], s0, v132
	s_barrier
	s_and_saveexec_b64 s[2:3], s[54:55]
	s_cbranch_execz .LBB0_371
	s_movk_i32 s0, 0x7ff
	v_cmp_lt_i32_e32 vcc, s0, v132
	s_xor_b64 s[0:1], s[56:57], -1
	s_or_b64 s[0:1], vcc, s[0:1]
	s_and_b64 exec, exec, s[0:1]
	s_cbranch_execz .LBB0_371
	v_bfe_u32 v0, v161, 5, 1
	v_mul_u32_u24_e32 v0, 0x90, v0
	v_lshlrev_b32_e32 v133, 2, v161
	v_lshlrev_b32_e32 v0, 2, v0
	v_and_b32_e32 v133, 0x7c, v133
	v_add3_u32 v138, v155, v0, v133
	v_add3_u32 v0, v155, v133, v0
	ds_write_b32 v138, v114
	v_add_u32_e32 v114, 0x100, v0
	ds_write2_b32 v114, v117, v118 offset0:44 offset1:224
	v_add_u32_e32 v114, 0x400, v0
	ds_write2_b32 v114, v119, v120 offset0:68 offset1:104
	v_add_u32_e32 v114, 0x600, v0
	ds_write2_b32 v114, v121, v122 offset0:12 offset1:192
	v_add_u32_e32 v114, 0x800, v0
	ds_write2_b32 v114, v123, v124 offset0:100 offset1:136
	v_add_u32_e32 v114, 0xa00, v0
	ds_write2_b32 v114, v125, v126 offset0:44 offset1:224
	v_add_u32_e32 v114, 0xc00, v0
	ds_write2_b32 v0, v115, v116 offset0:36 offset1:72
	ds_write2_b32 v114, v127, v128 offset0:132 offset1:168
	ds_write_b32 v0, v129 offset:3888
	s_waitcnt lgkmcnt(0)
	v_and_b32_e32 v160, 63, v161
	s_and_saveexec_b64 s[0:1], vcc
	s_xor_b64 s[6:7], exec, s[0:1]
	s_cbranch_execz .LBB0_369
	s_cmpk_gt_u32 s4, 0x17ff
	s_mov_b64 s[0:1], -1
	s_cbranch_scc0 .LBB0_365
	v_readlane_b32 s16, v251, 2
	v_lshlrev_b32_e32 v116, 3, v161
	v_add_u32_e32 v0, 0xffffe800, v132
	v_readlane_b32 s17, v251, 3
	v_and_b32_e32 v116, 24, v116
	v_lshlrev_b32_e32 v140, 2, v116
	v_lshl_add_u64 v[114:115], v[0:1], 2, s[16:17]
	v_mov_b32_e32 v141, v1
	v_lshl_add_u64 v[138:139], v[114:115], 0, v[140:141]
	global_load_dwordx4 v[122:125], v[138:139], off
	global_load_dwordx4 v[114:117], v[138:139], off offset:16
	v_add_u32_e32 v162, v155, v140
	v_lshrrev_b32_e32 v133, 2, v160
	s_movk_i32 s0, 0x90
	v_mad_u32_u24 v118, v133, s0, v162
	ds_read_b128 v[126:129], v118
	ds_read_b128 v[118:121], v118 offset:16
	s_mov_b32 s0, 0xbfb8aa3b
	v_readlane_b32 s18, v251, 4
	v_readlane_b32 s19, v251, 5
	v_readlane_b32 s20, v251, 6
	v_readlane_b32 s21, v251, 7
	v_readlane_b32 s22, v251, 8
	v_readlane_b32 s23, v251, 9
	v_readlane_b32 s24, v251, 10
	v_readlane_b32 s25, v251, 11
	v_readlane_b32 s26, v251, 12
	v_readlane_b32 s27, v251, 13
	v_readlane_b32 s28, v251, 14
	v_readlane_b32 s29, v251, 15
	v_readlane_b32 s30, v251, 16
	v_readlane_b32 s31, v251, 17
	s_waitcnt vmcnt(1) lgkmcnt(1)
	v_add_f32_e32 v122, v126, v122
	v_mul_f32_e64 v126, |v122|, s0
	v_exp_f32_e32 v141, v126
	s_mov_b32 s0, 0x3c23d70a
	v_cmp_ngt_f32_e32 vcc, s0, v141
	s_and_saveexec_b64 s[0:1], vcc
	s_xor_b64 s[8:9], exec, s[0:1]
	s_cbranch_execz .LBB0_302
	v_add_f32_e32 v126, 1.0, v141
	s_mov_b32 s0, 0x800000
	v_cmp_gt_f32_e32 vcc, s0, v126
	s_mov_b32 s0, 0x3f317217
	s_nop 0
	v_cndmask_b32_e64 v141, 0, 32, vcc
	v_ldexp_f32 v126, v126, v141
	v_log_f32_e32 v126, v126
	s_nop 0
	v_mul_f32_e32 v141, 0x3f317217, v126
	v_fma_f32 v141, v126, s0, -v141
	v_fmac_f32_e32 v141, 0x3377d1cf, v126
	v_fmac_f32_e32 v141, 0x3f317217, v126
	v_cmp_lt_f32_e64 s[0:1], |v126|, s47
	s_nop 1
	v_cndmask_b32_e64 v126, v126, v141, s[0:1]
	v_cndmask_b32_e32 v141, 0, v238, vcc
	v_sub_f32_e32 v126, v126, v141

.LBB0_908:
	s_add_i32 s2, s7, s8
	s_cmpk_gt_i32 s2, 0x207
	s_mov_b64 s[0:1], -1
	s_cbranch_scc1 .LBB0_907
	s_ashr_i32 s0, s2, 31
	s_lshr_b32 s0, s0, 27
	s_add_i32 s0, s2, s0
	s_ashr_i32 s1, s0, 5
	s_lshl_b32 s1, s1, 3
	s_sub_i32 s3, 0x82, s1
	s_min_u32 s3, s3, 8
	v_cvt_f32_ubyte0_e32 v0, s3
	v_rcp_iflag_f32_e32 v0, v0
	s_sub_i32 s5, 0, s3
	s_andn2_b32 s0, s0, 31
	s_sub_i32 s0, s2, s0
	v_mul_f32_e32 v0, 0x4f7ffffe, v0
	v_cvt_u32_f32_e32 v0, v0
	s_abs_i32 s4, s0
	s_ashr_i32 s2, s0, 31
	s_waitcnt vmcnt(63) expcnt(7) lgkmcnt(15)
	v_readfirstlane_b32 s10, v0
	s_mul_i32 s5, s5, s10
	s_mul_hi_u32 s5, s10, s5
	s_add_i32 s10, s10, s5
	s_mul_hi_u32 s5, s4, s10
	s_mul_i32 s10, s5, s3
	s_sub_i32 s4, s4, s10
	s_add_i32 s10, s5, 1
	s_sub_i32 s11, s4, s3
	s_cmp_ge_u32 s4, s3
	s_cselect_b32 s5, s10, s5
	s_cselect_b32 s4, s11, s4
	s_add_i32 s10, s5, 1
	s_cmp_ge_u32 s4, s3
	s_cselect_b32 s4, s10, s5
	s_xor_b32 s4, s4, s2
	s_sub_i32 s2, s4, s2
	s_mul_i32 s3, s2, s3
	s_sub_i32 s0, s0, s3
	s_add_i32 s0, s0, s1
	s_lshl_b32 s0, s0, 8
	s_lshl_b32 s2, s2, 8
	s_ashr_i32 s1, s0, 31
	s_ashr_i32 s3, s2, 31
	s_lshl_b64 s[4:5], s[0:1], 11
	s_lshl_b64 s[10:11], s[2:3], 11
	s_add_u32 s12, s64, s4
	v_mov_b32_e32 v0, v132
	s_addc_u32 s13, s65, s5
	s_barrier
	v_readlane_b32 s14, v251, 50
	v_lshl_add_u64 v[2:3], v[0:1], 1, s[12:13]
	v_add_u32_e32 v0, 32, v133
	v_readlane_b32 s15, v251, 51
	v_readfirstlane_b32 s1, v0
	s_mov_b32 m0, s1
	v_mov_b32_e32 v0, v134
	global_load_lds_dwordx4 v[2:3], off
	s_add_u32 s14, s14, s10
	v_lshl_add_u64 v[2:3], v[0:1], 1, s[12:13]
	v_add_u32_e32 v0, 32, v135
	s_addc_u32 s15, s15, s11
	v_readfirstlane_b32 s1, v0
	s_mov_b32 m0, s1
	v_mov_b32_e32 v0, v136
	global_load_lds_dwordx4 v[2:3], off
	v_readlane_b32 s3, v254, 3
	v_lshl_add_u64 v[2:3], v[0:1], 1, s[12:13]
	v_add_u32_e32 v0, 32, v137
	s_mov_b32 s9, 0
	v_readfirstlane_b32 s1, v0
	s_mov_b32 m0, s1
	v_mov_b32_e32 v0, v138
	global_load_lds_dwordx4 v[2:3], off
	s_nop 0
	v_lshl_add_u64 v[2:3], v[0:1], 1, s[12:13]
	v_add_u32_e32 v0, 32, v139
	s_nop 0
	v_readfirstlane_b32 s1, v0
	s_mov_b32 m0, s1
	v_mov_b32_e32 v0, v132
	global_load_lds_dwordx4 v[2:3], off
	s_nop 0
	v_lshl_add_u64 v[2:3], v[0:1], 1, s[14:15]
	v_add_u32_e32 v0, s3, v133
	s_nop 0
	v_readfirstlane_b32 s1, v0
	s_mov_b32 m0, s1
	v_mov_b32_e32 v0, v134
	global_load_lds_dwordx4 v[2:3], off
	s_nop 0
	v_lshl_add_u64 v[2:3], v[0:1], 1, s[14:15]
	v_add_u32_e32 v0, s3, v135
	s_nop 0
	v_readfirstlane_b32 s1, v0
	s_mov_b32 m0, s1
	v_mov_b32_e32 v0, v136
	global_load_lds_dwordx4 v[2:3], off
	s_nop 0
	v_lshl_add_u64 v[2:3], v[0:1], 1, s[14:15]
	v_add_u32_e32 v0, s3, v137
	s_nop 0
	v_readfirstlane_b32 s1, v0
	s_mov_b32 m0, s1
	v_mov_b32_e32 v0, v138
	global_load_lds_dwordx4 v[2:3], off
	s_nop 0
	v_lshl_add_u64 v[2:3], v[0:1], 1, s[14:15]
	v_add_u32_e32 v0, s3, v139
	v_readlane_b32 s3, v253, 26
	v_readfirstlane_b32 s1, v0
	s_mov_b32 m0, s1
	v_readlane_b32 s1, v253, 25
	global_load_lds_dwordx4 v[2:3], off
	s_add_u32 s1, s1, s4
	s_waitcnt vmcnt(0)
	s_addc_u32 s3, s3, s5
	v_readlane_b32 s4, v253, 34
	s_add_u32 s10, s4, s10
	v_readlane_b32 s4, v253, 35
	v_mov_b32_e32 v2, 0
	s_addc_u32 s11, s4, s11
	s_mov_b64 s[4:5], 0
	v_mov_b32_e32 v3, v2
	v_mov_b32_e32 v4, v2
	v_mov_b32_e32 v5, v2
	v_mov_b32_e32 v6, v2
	v_mov_b32_e32 v7, v2
	v_mov_b32_e32 v8, v2
	v_mov_b32_e32 v9, v2
	v_mov_b32_e32 v10, v2
	v_mov_b32_e32 v11, v2
	v_mov_b32_e32 v12, v2
	v_mov_b32_e32 v13, v2
	s_waitcnt vmcnt(0)
	v_mov_b32_e32 v14, v2
	v_mov_b32_e32 v15, v2
	v_mov_b32_e32 v16, v2
	v_mov_b32_e32 v17, v2
	v_mov_b32_e32 v18, v2
	v_mov_b32_e32 v19, v2
	v_mov_b32_e32 v20, v2
	v_mov_b32_e32 v21, v2
	v_mov_b32_e32 v22, v2
	v_mov_b32_e32 v23, v2
	v_mov_b32_e32 v24, v2
	v_mov_b32_e32 v25, v2
	v_mov_b32_e32 v26, v2
	v_mov_b32_e32 v27, v2
	v_mov_b32_e32 v28, v2
	v_mov_b32_e32 v29, v2
	v_mov_b32_e32 v30, v2
	v_mov_b32_e32 v31, v2
	v_mov_b32_e32 v32, v2
	v_mov_b32_e32 v33, v2
	v_mov_b32_e32 v34, v2
	v_mov_b32_e32 v35, v2
	v_mov_b32_e32 v36, v2
	v_mov_b32_e32 v37, v2
	v_mov_b32_e32 v38, v2
	v_mov_b32_e32 v39, v2
	v_mov_b32_e32 v40, v2
	v_mov_b32_e32 v41, v2
	v_mov_b32_e32 v42, v2
	v_mov_b32_e32 v43, v2
	v_mov_b32_e32 v44, v2
	v_mov_b32_e32 v45, v2
	v_mov_b32_e32 v46, v2
	v_mov_b32_e32 v47, v2
	v_mov_b32_e32 v48, v2
	v_mov_b32_e32 v49, v2
	v_mov_b32_e32 v50, v2
	v_mov_b32_e32 v51, v2
	v_mov_b32_e32 v52, v2
	v_mov_b32_e32 v53, v2
	v_mov_b32_e32 v54, v2
	v_mov_b32_e32 v55, v2
	v_mov_b32_e32 v56, v2
	v_mov_b32_e32 v57, v2
	v_mov_b32_e32 v58, v2
	v_mov_b32_e32 v59, v2
	v_mov_b32_e32 v60, v2
	v_mov_b32_e32 v61, v2
	v_mov_b32_e32 v62, v2
	v_mov_b32_e32 v63, v2
	v_mov_b32_e32 v64, v2
	v_mov_b32_e32 v65, v2
	v_mov_b32_e32 v66, v2
	v_mov_b32_e32 v67, v2
	v_mov_b32_e32 v68, v2
	v_mov_b32_e32 v69, v2
	v_mov_b32_e32 v70, v2
	v_mov_b32_e32 v71, v2
	v_mov_b32_e32 v72, v2
	v_mov_b32_e32 v73, v2
	v_mov_b32_e32 v74, v2
	v_mov_b32_e32 v75, v2
	v_mov_b32_e32 v76, v2
	v_mov_b32_e32 v77, v2
	v_mov_b32_e32 v78, v2
	v_mov_b32_e32 v79, v2
	v_mov_b32_e32 v80, v2
	v_mov_b32_e32 v81, v2
	v_mov_b32_e32 v82, v2
	v_mov_b32_e32 v83, v2
	v_mov_b32_e32 v84, v2
	v_mov_b32_e32 v85, v2
	v_mov_b32_e32 v86, v2
	v_mov_b32_e32 v87, v2
	v_mov_b32_e32 v88, v2
	v_mov_b32_e32 v89, v2
	v_mov_b32_e32 v90, v2
	v_mov_b32_e32 v91, v2
	v_mov_b32_e32 v92, v2
	v_mov_b32_e32 v93, v2
	v_mov_b32_e32 v94, v2
	v_mov_b32_e32 v95, v2
	v_mov_b32_e32 v96, v2
	v_mov_b32_e32 v97, v2
	v_mov_b32_e32 v98, v2
	v_mov_b32_e32 v99, v2
	v_mov_b32_e32 v100, v2
	v_mov_b32_e32 v101, v2
	v_mov_b32_e32 v102, v2
	v_mov_b32_e32 v103, v2
	v_mov_b32_e32 v104, v2
	v_mov_b32_e32 v105, v2
	v_mov_b32_e32 v106, v2
	v_mov_b32_e32 v107, v2
	v_mov_b32_e32 v108, v2
	v_mov_b32_e32 v109, v2
	v_mov_b32_e32 v110, v2
	v_mov_b32_e32 v111, v2
	v_mov_b32_e32 v112, v2
	v_mov_b32_e32 v113, v2
	v_mov_b32_e32 v114, v2
	v_mov_b32_e32 v115, v2
	v_mov_b32_e32 v116, v2
	v_mov_b32_e32 v117, v2
	v_mov_b32_e32 v118, v2
	v_mov_b32_e32 v119, v2
	v_mov_b32_e32 v120, v2
	v_mov_b32_e32 v121, v2
	v_mov_b32_e32 v122, v2
	v_mov_b32_e32 v123, v2
	v_mov_b32_e32 v124, v2
	v_mov_b32_e32 v125, v2
	v_mov_b32_e32 v126, v2
	v_mov_b32_e32 v127, v2
	v_mov_b32_e32 v128, v2
	v_mov_b32_e32 v129, v2
	s_waitcnt lgkmcnt(0)
	s_barrier
	v_lshlrev_b32_e32 v149, 1, v132
	v_readfirstlane_b32 s14, v133
	v_add_u32_e32 v205, v140, v142
	v_add_u32_e32 v209, v141, v142
	v_add_u32_e32 v206, v140, v146
	v_add_u32_e32 v210, v141, v146
	v_add_u32_e32 v207, v140, v147
	v_add_u32_e32 v211, v141, v147
	v_add_u32_e32 v208, v140, v148
	v_add_u32_e32 v212, v141, v148
	s_nop 1
	s_add_u32 m0, s14, 0x8020
	s_add_u32 s12, s1, s4
	s_addc_u32 s13, s3, s5
	global_load_lds_dwordx4 v149, s[12:13]
	s_add_u32 m0, s14, 0xa020
	s_add_u32 s12, s12, 0x20000
	s_addc_u32 s13, s13, 0
	global_load_lds_dwordx4 v149, s[12:13]
	s_add_u32 m0, s14, 0xc020
	s_add_u32 s12, s12, 0x20000
	s_addc_u32 s13, s13, 0
	global_load_lds_dwordx4 v149, s[12:13]
	s_add_u32 m0, s14, 0xe020
	s_add_u32 s12, s12, 0x20000
	s_addc_u32 s13, s13, 0
	global_load_lds_dwordx4 v149, s[12:13]
	s_add_u32 m0, s14, 0x18020
	s_add_u32 s12, s10, s4
	s_addc_u32 s13, s11, s5
	global_load_lds_dwordx4 v149, s[12:13]
	s_add_u32 m0, s14, 0x1a020
	s_add_u32 s12, s12, 0x20000
	s_addc_u32 s13, s13, 0
	global_load_lds_dwordx4 v149, s[12:13]
	s_add_u32 m0, s14, 0x1c020
	s_add_u32 s12, s12, 0x20000
	s_addc_u32 s13, s13, 0
	global_load_lds_dwordx4 v149, s[12:13]
	s_add_u32 m0, s14, 0x1e020
	s_add_u32 s12, s12, 0x20000
	s_addc_u32 s13, s13, 0
	global_load_lds_dwordx4 v149, s[12:13]
	s_add_u32 s4, s4, 0x80
	s_addc_u32 s5, s5, 0
	ds_read_b128 v[150:153], v205 offset:0
	ds_read_b128 v[166:169], v209 offset:0
	ds_read_b128 v[170:173], v209 offset:4096
	ds_read_b128 v[154:157], v205 offset:4096
	ds_read_b128 v[158:161], v205 offset:8192
	ds_read_b128 v[162:165], v205 offset:12288
.Lg910_loop:
	s_waitcnt lgkmcnt(4)
	v_mfma_f32_32x32x16_bf16 v[114:129], v[150:153], v[166:169], v[114:129]
	ds_read_b128 v[174:177], v206 offset:0
	s_waitcnt lgkmcnt(4)
	v_mfma_f32_32x32x16_bf16 v[98:113], v[150:153], v[170:173], v[98:113]
	ds_read_b128 v[192:195], v210 offset:0
	s_waitcnt lgkmcnt(4)
	v_mfma_f32_32x32x16_bf16 v[82:97], v[154:157], v[166:169], v[82:97]
	ds_read_b128 v[200:203], v210 offset:4096
	v_mfma_f32_32x32x16_bf16 v[66:81], v[154:157], v[170:173], v[66:81]
	ds_read_b128 v[180:183], v206 offset:4096
	s_waitcnt lgkmcnt(5)
	v_mfma_f32_32x32x16_bf16 v[50:65], v[158:161], v[166:169], v[50:65]
	ds_read_b128 v[184:187], v206 offset:8192
	v_mfma_f32_32x32x16_bf16 v[34:49], v[158:161], v[170:173], v[34:49]
	ds_read_b128 v[188:191], v206 offset:12288
	s_waitcnt lgkmcnt(6)
	v_mfma_f32_32x32x16_bf16 v[18:33], v[162:165], v[166:169], v[18:33]
	v_mfma_f32_32x32x16_bf16 v[2:17], v[162:165], v[170:173], v[2:17]
	s_waitcnt lgkmcnt(4)
	v_mfma_f32_32x32x16_bf16 v[114:129], v[174:177], v[192:195], v[114:129]
	ds_read_b128 v[150:153], v207 offset:0
	s_waitcnt lgkmcnt(4)
	v_mfma_f32_32x32x16_bf16 v[98:113], v[174:177], v[200:203], v[98:113]
	ds_read_b128 v[166:169], v211 offset:0
	s_waitcnt lgkmcnt(4)
	v_mfma_f32_32x32x16_bf16 v[82:97], v[180:183], v[192:195], v[82:97]
	ds_read_b128 v[170:173], v211 offset:4096
	v_mfma_f32_32x32x16_bf16 v[66:81], v[180:183], v[200:203], v[66:81]
	ds_read_b128 v[154:157], v207 offset:4096
	s_waitcnt lgkmcnt(5)
	v_mfma_f32_32x32x16_bf16 v[50:65], v[184:187], v[192:195], v[50:65]
	ds_read_b128 v[158:161], v207 offset:8192
	v_mfma_f32_32x32x16_bf16 v[34:49], v[184:187], v[200:203], v[34:49]
	ds_read_b128 v[162:165], v207 offset:12288
	s_waitcnt lgkmcnt(6)
	v_mfma_f32_32x32x16_bf16 v[18:33], v[188:191], v[192:195], v[18:33]
	v_mfma_f32_32x32x16_bf16 v[2:17], v[188:191], v[200:203], v[2:17]
	s_waitcnt lgkmcnt(4)
	v_mfma_f32_32x32x16_bf16 v[114:129], v[150:153], v[166:169], v[114:129]
	ds_read_b128 v[174:177], v208 offset:0
	ds_read_b128 v[192:195], v212 offset:0
	s_waitcnt lgkmcnt(5)
	v_mfma_f32_32x32x16_bf16 v[98:113], v[150:153], v[170:173], v[98:113]
	ds_read_b128 v[200:203], v212 offset:4096
	ds_read_b128 v[180:183], v208 offset:4096
	s_waitcnt lgkmcnt(6)
	v_mfma_f32_32x32x16_bf16 v[82:97], v[154:157], v[166:169], v[82:97]
	ds_read_b128 v[184:187], v208 offset:8192
	ds_read_b128 v[188:191], v208 offset:12288
	v_mfma_f32_32x32x16_bf16 v[66:81], v[154:157], v[170:173], v[66:81]
	s_waitcnt lgkmcnt(7)
	v_mfma_f32_32x32x16_bf16 v[50:65], v[158:161], v[166:169], v[50:65]
	v_mfma_f32_32x32x16_bf16 v[34:49], v[158:161], v[170:173], v[34:49]
	s_waitcnt lgkmcnt(6)
	v_mfma_f32_32x32x16_bf16 v[18:33], v[162:165], v[166:169], v[18:33]
	v_mfma_f32_32x32x16_bf16 v[2:17], v[162:165], v[170:173], v[2:17]
	s_waitcnt vmcnt(0) lgkmcnt(0)
	s_barrier
	s_cmp_lt_u32 s4, 0x780
	s_cbranch_scc0 .Lg910_nodma0
	v_mfma_f32_32x32x16_bf16 v[114:129], v[174:177], v[192:195], v[114:129]
	ds_read_b128 v[150:153], v205 offset:32768
	s_add_u32 m0, s14, 0x20
	s_add_u32 s12, s1, s4
	s_addc_u32 s13, s3, s5
	global_load_lds_dwordx4 v149, s[12:13]
	v_mfma_f32_32x32x16_bf16 v[98:113], v[174:177], v[200:203], v[98:113]
	ds_read_b128 v[166:169], v209 offset:32768
	s_add_u32 m0, s14, 0x2020
	s_add_u32 s12, s12, 0x20000
	s_addc_u32 s13, s13, 0
	global_load_lds_dwordx4 v149, s[12:13]
	v_mfma_f32_32x32x16_bf16 v[82:97], v[180:183], v[192:195], v[82:97]
	ds_read_b128 v[170:173], v209 offset:36864
	s_add_u32 m0, s14, 0x4020
	s_add_u32 s12, s12, 0x20000
	s_addc_u32 s13, s13, 0
	global_load_lds_dwordx4 v149, s[12:13]
	v_mfma_f32_32x32x16_bf16 v[66:81], v[180:183], v[200:203], v[66:81]
	ds_read_b128 v[154:157], v205 offset:36864
	s_add_u32 m0, s14, 0x6020
	s_add_u32 s12, s12, 0x20000
	s_addc_u32 s13, s13, 0
	global_load_lds_dwordx4 v149, s[12:13]
	v_mfma_f32_32x32x16_bf16 v[50:65], v[184:187], v[192:195], v[50:65]
	ds_read_b128 v[158:161], v205 offset:40960
	s_add_u32 m0, s14, 0x10020
	s_add_u32 s12, s10, s4
	s_addc_u32 s13, s11, s5
	global_load_lds_dwordx4 v149, s[12:13]
	v_mfma_f32_32x32x16_bf16 v[34:49], v[184:187], v[200:203], v[34:49]
	ds_read_b128 v[162:165], v205 offset:45056
	s_add_u32 m0, s14, 0x12020
	s_add_u32 s12, s12, 0x20000
	s_addc_u32 s13, s13, 0
	global_load_lds_dwordx4 v149, s[12:13]
	v_mfma_f32_32x32x16_bf16 v[18:33], v[188:191], v[192:195], v[18:33]
	s_add_u32 m0, s14, 0x14020
	s_add_u32 s12, s12, 0x20000
	s_addc_u32 s13, s13, 0
	global_load_lds_dwordx4 v149, s[12:13]
	v_mfma_f32_32x32x16_bf16 v[2:17], v[188:191], v[200:203], v[2:17]
	s_add_u32 m0, s14, 0x16020
	s_add_u32 s12, s12, 0x20000
	s_addc_u32 s13, s13, 0
	global_load_lds_dwordx4 v149, s[12:13]
	s_add_u32 s4, s4, 0x80
	s_addc_u32 s5, s5, 0
	s_branch .Lg910_join0
.Lg910_nodma0:
	s_add_u32 s4, s4, 0x80
	s_addc_u32 s5, s5, 0
	v_mfma_f32_32x32x16_bf16 v[114:129], v[174:177], v[192:195], v[114:129]
	ds_read_b128 v[150:153], v205 offset:32768
	v_mfma_f32_32x32x16_bf16 v[98:113], v[174:177], v[200:203], v[98:113]
	ds_read_b128 v[166:169], v209 offset:32768
	v_mfma_f32_32x32x16_bf16 v[82:97], v[180:183], v[192:195], v[82:97]
	ds_read_b128 v[170:173], v209 offset:36864
	v_mfma_f32_32x32x16_bf16 v[66:81], v[180:183], v[200:203], v[66:81]
	ds_read_b128 v[154:157], v205 offset:36864
	v_mfma_f32_32x32x16_bf16 v[50:65], v[184:187], v[192:195], v[50:65]
	ds_read_b128 v[158:161], v205 offset:40960
	v_mfma_f32_32x32x16_bf16 v[34:49], v[184:187], v[200:203], v[34:49]
	ds_read_b128 v[162:165], v205 offset:45056
	v_mfma_f32_32x32x16_bf16 v[18:33], v[188:191], v[192:195], v[18:33]
	v_mfma_f32_32x32x16_bf16 v[2:17], v[188:191], v[200:203], v[2:17]
.Lg910_join0:
	s_waitcnt lgkmcnt(4)
	v_mfma_f32_32x32x16_bf16 v[114:129], v[150:153], v[166:169], v[114:129]
	ds_read_b128 v[174:177], v206 offset:32768
	s_waitcnt lgkmcnt(4)
	v_mfma_f32_32x32x16_bf16 v[98:113], v[150:153], v[170:173], v[98:113]
	ds_read_b128 v[192:195], v210 offset:32768
	s_waitcnt lgkmcnt(4)
	v_mfma_f32_32x32x16_bf16 v[82:97], v[154:157], v[166:169], v[82:97]
	ds_read_b128 v[200:203], v210 offset:36864
	v_mfma_f32_32x32x16_bf16 v[66:81], v[154:157], v[170:173], v[66:81]
	ds_read_b128 v[180:183], v206 offset:36864
	s_waitcnt lgkmcnt(5)
	v_mfma_f32_32x32x16_bf16 v[50:65], v[158:161], v[166:169], v[50:65]
	ds_read_b128 v[184:187], v206 offset:40960
	v_mfma_f32_32x32x16_bf16 v[34:49], v[158:161], v[170:173], v[34:49]
	ds_read_b128 v[188:191], v206 offset:45056
	s_waitcnt lgkmcnt(6)
	v_mfma_f32_32x32x16_bf16 v[18:33], v[162:165], v[166:169], v[18:33]
	v_mfma_f32_32x32x16_bf16 v[2:17], v[162:165], v[170:173], v[2:17]
	s_waitcnt lgkmcnt(4)
	v_mfma_f32_32x32x16_bf16 v[114:129], v[174:177], v[192:195], v[114:129]
	ds_read_b128 v[150:153], v207 offset:32768
	s_waitcnt lgkmcnt(4)
	v_mfma_f32_32x32x16_bf16 v[98:113], v[174:177], v[200:203], v[98:113]
	ds_read_b128 v[166:169], v211 offset:32768
	s_waitcnt lgkmcnt(4)
	v_mfma_f32_32x32x16_bf16 v[82:97], v[180:183], v[192:195], v[82:97]
	ds_read_b128 v[170:173], v211 offset:36864
	v_mfma_f32_32x32x16_bf16 v[66:81], v[180:183], v[200:203], v[66:81]
	ds_read_b128 v[154:157], v207 offset:36864
	s_waitcnt lgkmcnt(5)
	v_mfma_f32_32x32x16_bf16 v[50:65], v[184:187], v[192:195], v[50:65]
	ds_read_b128 v[158:161], v207 offset:40960
	v_mfma_f32_32x32x16_bf16 v[34:49], v[184:187], v[200:203], v[34:49]
	ds_read_b128 v[162:165], v207 offset:45056
	s_waitcnt lgkmcnt(6)
	v_mfma_f32_32x32x16_bf16 v[18:33], v[188:191], v[192:195], v[18:33]
	v_mfma_f32_32x32x16_bf16 v[2:17], v[188:191], v[200:203], v[2:17]
	s_waitcnt lgkmcnt(4)
	v_mfma_f32_32x32x16_bf16 v[114:129], v[150:153], v[166:169], v[114:129]
	ds_read_b128 v[174:177], v208 offset:32768
	ds_read_b128 v[192:195], v212 offset:32768
	s_waitcnt lgkmcnt(5)
	v_mfma_f32_32x32x16_bf16 v[98:113], v[150:153], v[170:173], v[98:113]
	ds_read_b128 v[200:203], v212 offset:36864
	ds_read_b128 v[180:183], v208 offset:36864
	s_waitcnt lgkmcnt(6)
	v_mfma_f32_32x32x16_bf16 v[82:97], v[154:157], v[166:169], v[82:97]
	ds_read_b128 v[184:187], v208 offset:40960
	ds_read_b128 v[188:191], v208 offset:45056
	v_mfma_f32_32x32x16_bf16 v[66:81], v[154:157], v[170:173], v[66:81]
	s_waitcnt lgkmcnt(7)
	v_mfma_f32_32x32x16_bf16 v[50:65], v[158:161], v[166:169], v[50:65]
	v_mfma_f32_32x32x16_bf16 v[34:49], v[158:161], v[170:173], v[34:49]
	s_waitcnt lgkmcnt(6)
	v_mfma_f32_32x32x16_bf16 v[18:33], v[162:165], v[166:169], v[18:33]
	v_mfma_f32_32x32x16_bf16 v[2:17], v[162:165], v[170:173], v[2:17]
	s_waitcnt vmcnt(0) lgkmcnt(0)
	s_barrier
	s_cmp_lt_u32 s4, 0x780
	s_cbranch_scc0 .Lg910_nodma1
	v_mfma_f32_32x32x16_bf16 v[114:129], v[174:177], v[192:195], v[114:129]
	ds_read_b128 v[150:153], v205 offset:0
	s_add_u32 m0, s14, 0x8020
	s_add_u32 s12, s1, s4
	s_addc_u32 s13, s3, s5
	global_load_lds_dwordx4 v149, s[12:13]
	v_mfma_f32_32x32x16_bf16 v[98:113], v[174:177], v[200:203], v[98:113]
	ds_read_b128 v[166:169], v209 offset:0
	s_add_u32 m0, s14, 0xa020
	s_add_u32 s12, s12, 0x20000
	s_addc_u32 s13, s13, 0
	global_load_lds_dwordx4 v149, s[12:13]
	v_mfma_f32_32x32x16_bf16 v[82:97], v[180:183], v[192:195], v[82:97]
	ds_read_b128 v[170:173], v209 offset:4096
	s_add_u32 m0, s14, 0xc020
	s_add_u32 s12, s12, 0x20000
	s_addc_u32 s13, s13, 0
	global_load_lds_dwordx4 v149, s[12:13]
	v_mfma_f32_32x32x16_bf16 v[66:81], v[180:183], v[200:203], v[66:81]
	ds_read_b128 v[154:157], v205 offset:4096
	s_add_u32 m0, s14, 0xe020
	s_add_u32 s12, s12, 0x20000
	s_addc_u32 s13, s13, 0
	global_load_lds_dwordx4 v149, s[12:13]
	v_mfma_f32_32x32x16_bf16 v[50:65], v[184:187], v[192:195], v[50:65]
	ds_read_b128 v[158:161], v205 offset:8192
	s_add_u32 m0, s14, 0x18020
	s_add_u32 s12, s10, s4
	s_addc_u32 s13, s11, s5
	global_load_lds_dwordx4 v149, s[12:13]
	v_mfma_f32_32x32x16_bf16 v[34:49], v[184:187], v[200:203], v[34:49]
	ds_read_b128 v[162:165], v205 offset:12288
	s_add_u32 m0, s14, 0x1a020
	s_add_u32 s12, s12, 0x20000
	s_addc_u32 s13, s13, 0
	global_load_lds_dwordx4 v149, s[12:13]
	v_mfma_f32_32x32x16_bf16 v[18:33], v[188:191], v[192:195], v[18:33]
	s_add_u32 m0, s14, 0x1c020
	s_add_u32 s12, s12, 0x20000
	s_addc_u32 s13, s13, 0
	global_load_lds_dwordx4 v149, s[12:13]
	v_mfma_f32_32x32x16_bf16 v[2:17], v[188:191], v[200:203], v[2:17]
	s_add_u32 m0, s14, 0x1e020
	s_add_u32 s12, s12, 0x20000
	s_addc_u32 s13, s13, 0
	global_load_lds_dwordx4 v149, s[12:13]
	s_add_u32 s4, s4, 0x80
	s_addc_u32 s5, s5, 0
	s_branch .Lg910_join1
.Lg910_nodma1:
	s_add_u32 s4, s4, 0x80
	s_addc_u32 s5, s5, 0
	v_mfma_f32_32x32x16_bf16 v[114:129], v[174:177], v[192:195], v[114:129]
	ds_read_b128 v[150:153], v205 offset:0
	v_mfma_f32_32x32x16_bf16 v[98:113], v[174:177], v[200:203], v[98:113]
	ds_read_b128 v[166:169], v209 offset:0
	v_mfma_f32_32x32x16_bf16 v[82:97], v[180:183], v[192:195], v[82:97]
	ds_read_b128 v[170:173], v209 offset:4096
	v_mfma_f32_32x32x16_bf16 v[66:81], v[180:183], v[200:203], v[66:81]
	ds_read_b128 v[154:157], v205 offset:4096
	v_mfma_f32_32x32x16_bf16 v[50:65], v[184:187], v[192:195], v[50:65]
	ds_read_b128 v[158:161], v205 offset:8192
	v_mfma_f32_32x32x16_bf16 v[34:49], v[184:187], v[200:203], v[34:49]
	ds_read_b128 v[162:165], v205 offset:12288
	v_mfma_f32_32x32x16_bf16 v[18:33], v[188:191], v[192:195], v[18:33]
	v_mfma_f32_32x32x16_bf16 v[2:17], v[188:191], v[200:203], v[2:17]
.Lg910_join1:
	s_cmp_lt_u32 s4, 0x880
	s_cbranch_scc1 .Lg910_loop
	s_waitcnt lgkmcnt(0)
	v_add_u32_e32 v149, s0, v143
	v_or_b32_e32 v130, s2, v144
	s_mov_b32 s2, 0x7e07e07f
	v_mul_hi_i32 v0, v149, s2
	v_lshrrev_b32_e32 v131, 31, v0
	v_ashrrev_i32_e32 v0, 13, v0
	v_add_u32_e32 v0, v0, v131
	v_mul_i32_i24_e32 v131, 0x4100, v0
	v_sub_u32_e32 v131, v149, v131
	s_movk_i32 s3, 0xff
	v_mul_i32_i24_e32 v0, 0xc00, v0
	v_cmp_lt_i32_e32 vcc, s3, v131
	v_mov_b32_e32 v162, 0x1800
	v_mov_b32_e32 v152, v179
	s_waitcnt vmcnt(0)
	s_barrier
	v_cndmask_b32_e32 v150, v162, v0, vcc
	v_readlane_b32 s12, v251, 2
	v_and_b32_e32 v0, 31, v152
	v_bfe_u32 v131, v152, 5, 1
	v_mul_u32_u24_e32 v131, 0x240, v131
	v_lshlrev_b32_e32 v0, 2, v0
	v_add3_u32 v0, v145, v131, v0
	ds_write2_b32 v0, v114, v115 offset1:36
	ds_write2_b32 v0, v116, v117 offset0:72 offset1:108
	v_add_u32_e32 v114, 0x400, v0
	v_ashrrev_i32_e32 v151, 31, v150
	ds_write2_b32 v114, v118, v119 offset0:32 offset1:68
	ds_write2_b32 v114, v120, v121 offset0:104 offset1:140
	v_add_u32_e32 v114, 0x800, v0
	v_add_u32_e32 v0, 0xc00, v0
	v_readlane_b32 s26, v251, 16
	v_readlane_b32 s27, v251, 17
	ds_write2_b32 v114, v122, v123 offset0:64 offset1:100
	ds_write2_b32 v114, v124, v125 offset0:136 offset1:172
	ds_write2_b32 v0, v126, v127 offset0:96 offset1:132
	ds_write2_b32 v0, v128, v129 offset0:168 offset1:204
	v_lshl_add_u64 v[114:115], v[150:151], 2, s[26:27]
	s_mov_b64 s[4:5], 0x1b02000
	v_ashrrev_i32_e32 v131, 31, v130
	v_readlane_b32 s0, v251, 26
	v_lshlrev_b32_e32 v0, 3, v152
	v_lshl_add_u64 v[118:119], v[114:115], 0, s[4:5]
	v_lshlrev_b64 v[116:117], 2, v[130:131]
	v_readlane_b32 s1, v251, 27
	v_and_b32_e32 v122, 24, v0
	v_lshl_add_u64 v[120:121], v[118:119], 0, v[116:117]
	v_lshl_add_u64 v[114:115], v[130:131], 1, s[0:1]
	v_lshlrev_b32_e32 v0, 2, v122
	v_bfe_u32 v131, v152, 2, 4
	v_lshl_add_u64 v[158:159], v[120:121], 0, v[0:1]
	v_lshlrev_b32_e32 v120, 1, v122
	v_mul_u32_u24_e32 v122, 0x90, v131
	s_waitcnt lgkmcnt(0)
	v_add3_u32 v0, v145, v0, v122
	ds_read_b128 v[122:125], v0
	ds_read_b128 v[126:129], v0 offset:16
	global_load_dwordx4 v[150:153], v[158:159], off offset:16
	global_load_dwordx4 v[154:157], v[158:159], off
	v_or_b32_e32 v160, v131, v149
	v_mov_b32_e32 v121, v1
	v_ashrrev_i32_e32 v161, 31, v160
	v_lshl_add_u64 v[120:121], v[114:115], 0, v[120:121]
	v_readlane_b32 s13, v251, 3
	v_readlane_b32 s14, v251, 4
	v_readlane_b32 s15, v251, 5
	v_readlane_b32 s16, v251, 6
	v_readlane_b32 s17, v251, 7
	v_readlane_b32 s18, v251, 8
	v_readlane_b32 s19, v251, 9
	v_readlane_b32 s20, v251, 10
	v_readlane_b32 s21, v251, 11
	v_readlane_b32 s22, v251, 12
	v_readlane_b32 s23, v251, 13
	v_readlane_b32 s24, v251, 14
	v_readlane_b32 s25, v251, 15
	s_waitcnt vmcnt(1) lgkmcnt(0)
	v_pk_mul_f32 v[126:127], v[126:127], v[150:151]
	s_waitcnt vmcnt(0)
	v_pk_mul_f32 v[122:123], v[122:123], v[154:155]
	v_pk_mul_f32 v[124:125], v[124:125], v[156:157]
	v_pk_mul_f32 v[128:129], v[128:129], v[152:153]
	v_cvt_pk_bf16_f32 v122, v122, v123
	v_cvt_pk_bf16_f32 v123, v124, v125
	v_cvt_pk_bf16_f32 v124, v126, v127
	v_lshlrev_b64 v[126:127], 11, v[160:161]
	v_cvt_pk_bf16_f32 v125, v128, v129
	v_lshl_add_u64 v[126:127], v[120:121], 0, v[126:127]
	global_store_dwordx4 v[126:127], v[122:125], off
	ds_read_b128 v[122:125], v0 offset:2304
	ds_read_b128 v[126:129], v0 offset:2320
	global_load_dwordx4 v[150:153], v[158:159], off offset:16
	global_load_dwordx4 v[154:157], v[158:159], off
	s_waitcnt vmcnt(1) lgkmcnt(0)
	v_pk_mul_f32 v[126:127], v[126:127], v[150:151]
	s_waitcnt vmcnt(0)
	v_pk_mul_f32 v[122:123], v[122:123], v[154:155]
	v_pk_mul_f32 v[124:125], v[124:125], v[156:157]
	v_cvt_pk_bf16_f32 v122, v122, v123
	v_cvt_pk_bf16_f32 v123, v124, v125
	v_cvt_pk_bf16_f32 v124, v126, v127
	v_or_b32_e32 v126, 16, v160
	v_ashrrev_i32_e32 v127, 31, v126
	v_pk_mul_f32 v[128:129], v[128:129], v[152:153]
	v_lshlrev_b64 v[126:127], 11, v[126:127]
	v_cvt_pk_bf16_f32 v125, v128, v129
	v_lshl_add_u64 v[120:121], v[120:121], 0, v[126:127]
	global_store_dwordx4 v[120:121], v[122:125], off
	v_mov_b32_e32 v120, v179
	v_or_b32_e32 v126, 32, v130
	v_and_b32_e32 v0, 31, v120
	v_bfe_u32 v121, v120, 5, 1
	v_mul_u32_u24_e32 v121, 0x240, v121
	v_lshlrev_b32_e32 v0, 2, v0
	v_add3_u32 v0, v145, v121, v0
	ds_write2_b32 v0, v98, v99 offset1:36
	ds_write2_b32 v0, v100, v101 offset0:72 offset1:108
	v_add_u32_e32 v98, 0x400, v0
	ds_write2_b32 v98, v102, v103 offset0:32 offset1:68
	ds_write2_b32 v98, v104, v105 offset0:104 offset1:140
	v_add_u32_e32 v98, 0x800, v0
	v_add_u32_e32 v0, 0xc00, v0
	ds_write2_b32 v98, v106, v107 offset0:64 offset1:100
	ds_write2_b32 v98, v108, v109 offset0:136 offset1:172
	ds_write2_b32 v0, v110, v111 offset0:96 offset1:132
	ds_write2_b32 v0, v112, v113 offset0:168 offset1:204
	v_lshlrev_b32_e32 v0, 3, v120
	v_and_b32_e32 v102, 24, v0
	v_ashrrev_i32_e32 v127, 31, v126
	v_lshlrev_b32_e32 v0, 2, v102
	v_lshl_add_u64 v[98:99], v[118:119], 0, v[0:1]
	v_lshlrev_b64 v[100:101], 2, v[126:127]
	v_lshl_add_u64 v[112:113], v[98:99], 0, v[100:101]
	v_lshlrev_b32_e32 v98, 1, v102
	v_mov_b32_e32 v99, v1
	v_bfe_u32 v128, v120, 2, 4
	v_lshl_add_u64 v[102:103], s[0:1], 0, v[98:99]
	v_mul_u32_u24_e32 v98, 0x90, v128
	s_waitcnt lgkmcnt(0)
	v_add3_u32 v0, v145, v0, v98
	ds_read_b128 v[104:107], v0
	ds_read_b128 v[108:111], v0 offset:16
	global_load_dwordx4 v[118:121], v[112:113], off offset:16
	global_load_dwordx4 v[122:125], v[112:113], off
	v_or_b32_e32 v128, v128, v149
	v_ashrrev_i32_e32 v129, 31, v128
	s_waitcnt vmcnt(1) lgkmcnt(0)
	v_pk_mul_f32 v[108:109], v[108:109], v[118:119]
	s_waitcnt vmcnt(0)
	v_pk_mul_f32 v[98:99], v[104:105], v[122:123]
	v_pk_mul_f32 v[106:107], v[106:107], v[124:125]
	v_cvt_pk_bf16_f32 v104, v98, v99
	v_lshlrev_b64 v[98:99], 11, v[128:129]
	v_pk_mul_f32 v[110:111], v[110:111], v[120:121]
	v_cvt_pk_bf16_f32 v105, v106, v107
	v_cvt_pk_bf16_f32 v106, v108, v109
	v_lshl_add_u64 v[108:109], v[102:103], 0, v[98:99]
	v_lshlrev_b64 v[98:99], 1, v[126:127]
	v_cvt_pk_bf16_f32 v107, v110, v111
	v_lshl_add_u64 v[108:109], v[108:109], 0, v[98:99]
	global_store_dwordx4 v[108:109], v[104:107], off
	ds_read_b128 v[104:107], v0 offset:2304
	ds_read_b128 v[108:111], v0 offset:2320
	global_load_dwordx4 v[118:121], v[112:113], off offset:16
	global_load_dwordx4 v[122:125], v[112:113], off
	s_waitcnt vmcnt(1) lgkmcnt(0)
	v_pk_mul_f32 v[108:109], v[108:109], v[118:119]
	s_waitcnt vmcnt(0)
	v_pk_mul_f32 v[104:105], v[104:105], v[122:123]
	v_pk_mul_f32 v[106:107], v[106:107], v[124:125]
	v_cvt_pk_bf16_f32 v104, v104, v105
	v_cvt_pk_bf16_f32 v105, v106, v107
	v_cvt_pk_bf16_f32 v106, v108, v109
	v_or_b32_e32 v108, 16, v128
	v_ashrrev_i32_e32 v109, 31, v108
	v_lshlrev_b64 v[108:109], 11, v[108:109]
	v_pk_mul_f32 v[110:111], v[110:111], v[120:121]
	v_lshl_add_u64 v[102:103], v[102:103], 0, v[108:109]
	v_cvt_pk_bf16_f32 v107, v110, v111
	v_lshl_add_u64 v[102:103], v[102:103], 0, v[98:99]
	global_store_dwordx4 v[102:103], v[104:107], off
	v_or_b32_e32 v110, 32, v149
	v_mul_hi_i32 v0, v110, s2
	v_lshrrev_b32_e32 v102, 31, v0
	v_ashrrev_i32_e32 v0, 13, v0
	v_add_u32_e32 v0, v0, v102
	v_mul_i32_i24_e32 v102, 0x4100, v0
	v_sub_u32_e32 v102, v110, v102
	v_mul_i32_i24_e32 v0, 0xc00, v0
	v_cmp_lt_i32_e32 vcc, s3, v102
	v_mov_b32_e32 v104, v179
	s_nop 0
	v_cndmask_b32_e32 v102, v162, v0, vcc
	v_and_b32_e32 v0, 31, v104
	v_bfe_u32 v105, v104, 5, 1
	v_mul_u32_u24_e32 v105, 0x240, v105
	v_lshlrev_b32_e32 v0, 2, v0
	v_add3_u32 v0, v145, v105, v0
	ds_write2_b32 v0, v82, v83 offset1:36
	ds_write2_b32 v0, v84, v85 offset0:72 offset1:108
	v_add_u32_e32 v82, 0x400, v0
	v_ashrrev_i32_e32 v103, 31, v102
	ds_write2_b32 v82, v86, v87 offset0:32 offset1:68
	ds_write2_b32 v82, v88, v89 offset0:104 offset1:140
	v_add_u32_e32 v82, 0x800, v0
	v_add_u32_e32 v0, 0xc00, v0
	ds_write2_b32 v82, v90, v91 offset0:64 offset1:100
	ds_write2_b32 v82, v92, v93 offset0:136 offset1:172
	ds_write2_b32 v0, v94, v95 offset0:96 offset1:132
	ds_write2_b32 v0, v96, v97 offset0:168 offset1:204
	v_lshl_add_u64 v[82:83], v[102:103], 2, s[26:27]
	v_lshlrev_b32_e32 v0, 3, v104
	v_lshl_add_u64 v[82:83], v[82:83], 0, s[4:5]
	v_and_b32_e32 v86, 24, v0
	v_lshl_add_u64 v[84:85], v[82:83], 0, v[116:117]
	v_lshlrev_b32_e32 v0, 2, v86
	v_bfe_u32 v108, v104, 2, 4
	v_lshl_add_u64 v[106:107], v[84:85], 0, v[0:1]
	v_lshlrev_b32_e32 v84, 1, v86
	v_mul_u32_u24_e32 v86, 0x90, v108
	s_waitcnt lgkmcnt(0)
	v_add3_u32 v0, v145, v0, v86
	ds_read_b128 v[86:89], v0
	ds_read_b128 v[90:93], v0 offset:16
	global_load_dwordx4 v[94:97], v[106:107], off offset:16
	global_load_dwordx4 v[102:105], v[106:107], off
	v_or_b32_e32 v108, v108, v110
	v_mov_b32_e32 v85, v1
	v_ashrrev_i32_e32 v109, 31, v108
	v_lshl_add_u64 v[84:85], v[114:115], 0, v[84:85]
	s_waitcnt vmcnt(1) lgkmcnt(0)
	v_pk_mul_f32 v[90:91], v[90:91], v[94:95]
	s_waitcnt vmcnt(0)
	v_pk_mul_f32 v[86:87], v[86:87], v[102:103]
	v_pk_mul_f32 v[88:89], v[88:89], v[104:105]
	v_pk_mul_f32 v[92:93], v[92:93], v[96:97]
	v_cvt_pk_bf16_f32 v86, v86, v87
	v_cvt_pk_bf16_f32 v87, v88, v89
	v_cvt_pk_bf16_f32 v88, v90, v91
	v_lshlrev_b64 v[90:91], 11, v[108:109]
	v_cvt_pk_bf16_f32 v89, v92, v93
	v_lshl_add_u64 v[90:91], v[84:85], 0, v[90:91]
	global_store_dwordx4 v[90:91], v[86:89], off
	ds_read_b128 v[86:89], v0 offset:2304
	ds_read_b128 v[90:93], v0 offset:2320
	global_load_dwordx4 v[94:97], v[106:107], off offset:16
	global_load_dwordx4 v[102:105], v[106:107], off
	s_waitcnt vmcnt(1) lgkmcnt(0)
	v_pk_mul_f32 v[90:91], v[90:91], v[94:95]
	s_waitcnt vmcnt(0)
	v_pk_mul_f32 v[86:87], v[86:87], v[102:103]
	v_pk_mul_f32 v[88:89], v[88:89], v[104:105]
	v_cvt_pk_bf16_f32 v86, v86, v87
	v_cvt_pk_bf16_f32 v87, v88, v89
	v_cvt_pk_bf16_f32 v88, v90, v91
	v_or_b32_e32 v90, 16, v108
	v_ashrrev_i32_e32 v91, 31, v90
	v_pk_mul_f32 v[92:93], v[92:93], v[96:97]
	v_lshlrev_b64 v[90:91], 11, v[90:91]
	v_cvt_pk_bf16_f32 v89, v92, v93
	v_lshl_add_u64 v[84:85], v[84:85], 0, v[90:91]
	global_store_dwordx4 v[84:85], v[86:89], off
	s_nop 1
	v_mov_b32_e32 v86, v179
	s_nop 0
	v_and_b32_e32 v0, 31, v86
	v_bfe_u32 v84, v86, 5, 1
	v_mul_u32_u24_e32 v84, 0x240, v84
	v_lshlrev_b32_e32 v0, 2, v0
	v_add3_u32 v0, v145, v84, v0
	ds_write2_b32 v0, v66, v67 offset1:36
	ds_write2_b32 v0, v68, v69 offset0:72 offset1:108
	v_add_u32_e32 v66, 0x400, v0
	ds_write2_b32 v66, v70, v71 offset0:32 offset1:68
	ds_write2_b32 v66, v72, v73 offset0:104 offset1:140
	v_add_u32_e32 v66, 0x800, v0
	v_add_u32_e32 v0, 0xc00, v0
	ds_write2_b32 v66, v74, v75 offset0:64 offset1:100
	ds_write2_b32 v66, v76, v77 offset0:136 offset1:172
	ds_write2_b32 v0, v78, v79 offset0:96 offset1:132
	ds_write2_b32 v0, v80, v81 offset0:168 offset1:204
	v_lshlrev_b32_e32 v0, 3, v86
	v_and_b32_e32 v68, 24, v0
	v_lshlrev_b32_e32 v0, 2, v68
	v_lshl_add_u64 v[66:67], v[82:83], 0, v[0:1]
	v_bfe_u32 v86, v86, 2, 4
	v_lshl_add_u64 v[84:85], v[66:67], 0, v[100:101]
	v_lshlrev_b32_e32 v66, 1, v68
	v_mul_u32_u24_e32 v68, 0x90, v86
	s_waitcnt lgkmcnt(0)
	v_add3_u32 v0, v145, v0, v68
	ds_read_b128 v[68:71], v0
	ds_read_b128 v[72:75], v0 offset:16
	global_load_dwordx4 v[76:79], v[84:85], off offset:16
	global_load_dwordx4 v[80:83], v[84:85], off
	v_or_b32_e32 v86, v86, v110
	v_mov_b32_e32 v67, v1
	v_ashrrev_i32_e32 v87, 31, v86
	v_lshl_add_u64 v[66:67], s[0:1], 0, v[66:67]
	s_waitcnt vmcnt(1) lgkmcnt(0)
	v_pk_mul_f32 v[72:73], v[72:73], v[76:77]
	s_waitcnt vmcnt(0)
	v_pk_mul_f32 v[68:69], v[68:69], v[80:81]
	v_pk_mul_f32 v[70:71], v[70:71], v[82:83]
	v_cvt_pk_bf16_f32 v68, v68, v69
	v_cvt_pk_bf16_f32 v69, v70, v71
	v_cvt_pk_bf16_f32 v70, v72, v73
	v_lshlrev_b64 v[72:73], 11, v[86:87]
	v_pk_mul_f32 v[74:75], v[74:75], v[78:79]
	v_lshl_add_u64 v[72:73], v[66:67], 0, v[72:73]
	v_cvt_pk_bf16_f32 v71, v74, v75
	v_lshl_add_u64 v[72:73], v[72:73], 0, v[98:99]
	global_store_dwordx4 v[72:73], v[68:71], off
	ds_read_b128 v[68:71], v0 offset:2304
	ds_read_b128 v[72:75], v0 offset:2320
	global_load_dwordx4 v[76:79], v[84:85], off offset:16
	global_load_dwordx4 v[80:83], v[84:85], off
	s_waitcnt vmcnt(1) lgkmcnt(0)
	v_pk_mul_f32 v[72:73], v[72:73], v[76:77]
	s_waitcnt vmcnt(0)
	v_pk_mul_f32 v[68:69], v[68:69], v[80:81]
	v_pk_mul_f32 v[70:71], v[70:71], v[82:83]
	v_cvt_pk_bf16_f32 v68, v68, v69
	v_cvt_pk_bf16_f32 v69, v70, v71
	v_cvt_pk_bf16_f32 v70, v72, v73
	v_or_b32_e32 v72, 16, v86
	v_ashrrev_i32_e32 v73, 31, v72
	v_lshlrev_b64 v[72:73], 11, v[72:73]
	v_pk_mul_f32 v[74:75], v[74:75], v[78:79]
	v_lshl_add_u64 v[66:67], v[66:67], 0, v[72:73]
	v_cvt_pk_bf16_f32 v71, v74, v75
	v_lshl_add_u64 v[66:67], v[66:67], 0, v[98:99]
	global_store_dwordx4 v[66:67], v[68:71], off
	v_or_b32_e32 v74, 64, v149
	v_mul_hi_i32 v0, v74, s2
	v_lshrrev_b32_e32 v66, 31, v0
	v_ashrrev_i32_e32 v0, 13, v0
	v_add_u32_e32 v0, v0, v66
	v_mul_i32_i24_e32 v66, 0x4100, v0
	v_sub_u32_e32 v66, v74, v66
	v_mul_i32_i24_e32 v0, 0xc00, v0
	v_cmp_lt_i32_e32 vcc, s3, v66
	v_mov_b32_e32 v68, v179
	s_nop 0
	v_cndmask_b32_e32 v66, v162, v0, vcc
	v_and_b32_e32 v0, 31, v68
	v_bfe_u32 v69, v68, 5, 1
	v_mul_u32_u24_e32 v69, 0x240, v69
	v_lshlrev_b32_e32 v0, 2, v0
	v_add3_u32 v0, v145, v69, v0
	ds_write2_b32 v0, v50, v51 offset1:36
	ds_write2_b32 v0, v52, v53 offset0:72 offset1:108
	v_add_u32_e32 v50, 0x400, v0
	v_ashrrev_i32_e32 v67, 31, v66
	ds_write2_b32 v50, v54, v55 offset0:32 offset1:68
	ds_write2_b32 v50, v56, v57 offset0:104 offset1:140
	v_add_u32_e32 v50, 0x800, v0
	v_add_u32_e32 v0, 0xc00, v0
	ds_write2_b32 v50, v58, v59 offset0:64 offset1:100
	ds_write2_b32 v50, v60, v61 offset0:136 offset1:172
	ds_write2_b32 v0, v62, v63 offset0:96 offset1:132
	ds_write2_b32 v0, v64, v65 offset0:168 offset1:204
	v_lshl_add_u64 v[50:51], v[66:67], 2, s[26:27]
	v_lshlrev_b32_e32 v0, 3, v68
	v_lshl_add_u64 v[50:51], v[50:51], 0, s[4:5]
	v_and_b32_e32 v54, 24, v0
	v_lshl_add_u64 v[52:53], v[50:51], 0, v[116:117]
	v_lshlrev_b32_e32 v0, 2, v54
	v_bfe_u32 v72, v68, 2, 4
	v_lshl_add_u64 v[70:71], v[52:53], 0, v[0:1]
	v_lshlrev_b32_e32 v52, 1, v54
	v_mul_u32_u24_e32 v54, 0x90, v72
	s_waitcnt lgkmcnt(0)
	v_add3_u32 v0, v145, v0, v54
	ds_read_b128 v[54:57], v0
	ds_read_b128 v[58:61], v0 offset:16
	global_load_dwordx4 v[62:65], v[70:71], off offset:16
	global_load_dwordx4 v[66:69], v[70:71], off
	v_or_b32_e32 v72, v72, v74
	v_mov_b32_e32 v53, v1
	v_ashrrev_i32_e32 v73, 31, v72
	v_lshl_add_u64 v[52:53], v[114:115], 0, v[52:53]
	s_waitcnt vmcnt(1) lgkmcnt(0)
	v_pk_mul_f32 v[58:59], v[58:59], v[62:63]
	s_waitcnt vmcnt(0)
	v_pk_mul_f32 v[54:55], v[54:55], v[66:67]
	v_pk_mul_f32 v[56:57], v[56:57], v[68:69]
	v_pk_mul_f32 v[60:61], v[60:61], v[64:65]
	v_cvt_pk_bf16_f32 v54, v54, v55
	v_cvt_pk_bf16_f32 v55, v56, v57
	v_cvt_pk_bf16_f32 v56, v58, v59
	v_lshlrev_b64 v[58:59], 11, v[72:73]
	v_cvt_pk_bf16_f32 v57, v60, v61
	v_lshl_add_u64 v[58:59], v[52:53], 0, v[58:59]
	global_store_dwordx4 v[58:59], v[54:57], off
	ds_read_b128 v[54:57], v0 offset:2304
	ds_read_b128 v[58:61], v0 offset:2320
	global_load_dwordx4 v[62:65], v[70:71], off offset:16
	global_load_dwordx4 v[66:69], v[70:71], off
	s_waitcnt vmcnt(1) lgkmcnt(0)
	v_pk_mul_f32 v[58:59], v[58:59], v[62:63]
	s_waitcnt vmcnt(0)
	v_pk_mul_f32 v[54:55], v[54:55], v[66:67]
	v_pk_mul_f32 v[56:57], v[56:57], v[68:69]
	v_cvt_pk_bf16_f32 v54, v54, v55
	v_cvt_pk_bf16_f32 v55, v56, v57
	v_cvt_pk_bf16_f32 v56, v58, v59
	v_or_b32_e32 v58, 16, v72
	v_ashrrev_i32_e32 v59, 31, v58
	v_pk_mul_f32 v[60:61], v[60:61], v[64:65]
	v_lshlrev_b64 v[58:59], 11, v[58:59]
	v_cvt_pk_bf16_f32 v57, v60, v61
	v_lshl_add_u64 v[52:53], v[52:53], 0, v[58:59]
	global_store_dwordx4 v[52:53], v[54:57], off
	s_nop 1
	v_mov_b32_e32 v54, v179
	s_nop 0
	v_and_b32_e32 v0, 31, v54
	v_bfe_u32 v52, v54, 5, 1
	v_mul_u32_u24_e32 v52, 0x240, v52
	v_lshlrev_b32_e32 v0, 2, v0
	v_add3_u32 v0, v145, v52, v0
	ds_write2_b32 v0, v34, v35 offset1:36
	ds_write2_b32 v0, v36, v37 offset0:72 offset1:108
	v_add_u32_e32 v34, 0x400, v0
	ds_write2_b32 v34, v38, v39 offset0:32 offset1:68
	ds_write2_b32 v34, v40, v41 offset0:104 offset1:140
	v_add_u32_e32 v34, 0x800, v0
	v_add_u32_e32 v0, 0xc00, v0
	ds_write2_b32 v34, v42, v43 offset0:64 offset1:100
	ds_write2_b32 v34, v44, v45 offset0:136 offset1:172
	ds_write2_b32 v0, v46, v47 offset0:96 offset1:132
	ds_write2_b32 v0, v48, v49 offset0:168 offset1:204
	v_lshlrev_b32_e32 v0, 3, v54
	v_and_b32_e32 v36, 24, v0
	v_lshlrev_b32_e32 v0, 2, v36
	v_lshl_add_u64 v[34:35], v[50:51], 0, v[0:1]
	v_bfe_u32 v54, v54, 2, 4
	v_lshl_add_u64 v[52:53], v[34:35], 0, v[100:101]
	v_lshlrev_b32_e32 v34, 1, v36
	v_mul_u32_u24_e32 v36, 0x90, v54
	s_waitcnt lgkmcnt(0)
	v_add3_u32 v0, v145, v0, v36
	ds_read_b128 v[36:39], v0
	ds_read_b128 v[40:43], v0 offset:16
	global_load_dwordx4 v[44:47], v[52:53], off offset:16
	global_load_dwordx4 v[48:51], v[52:53], off
	v_or_b32_e32 v54, v54, v74
	v_mov_b32_e32 v35, v1
	v_ashrrev_i32_e32 v55, 31, v54
	v_lshl_add_u64 v[34:35], s[0:1], 0, v[34:35]
	s_waitcnt vmcnt(1) lgkmcnt(0)
	v_pk_mul_f32 v[40:41], v[40:41], v[44:45]
	s_waitcnt vmcnt(0)
	v_pk_mul_f32 v[36:37], v[36:37], v[48:49]
	v_pk_mul_f32 v[38:39], v[38:39], v[50:51]
	v_cvt_pk_bf16_f32 v36, v36, v37
	v_cvt_pk_bf16_f32 v37, v38, v39
	v_cvt_pk_bf16_f32 v38, v40, v41
	v_lshlrev_b64 v[40:41], 11, v[54:55]
	v_pk_mul_f32 v[42:43], v[42:43], v[46:47]
	v_lshl_add_u64 v[40:41], v[34:35], 0, v[40:41]
	v_cvt_pk_bf16_f32 v39, v42, v43
	v_lshl_add_u64 v[40:41], v[40:41], 0, v[98:99]
	global_store_dwordx4 v[40:41], v[36:39], off
	ds_read_b128 v[36:39], v0 offset:2304
	ds_read_b128 v[40:43], v0 offset:2320
	global_load_dwordx4 v[44:47], v[52:53], off offset:16
	global_load_dwordx4 v[48:51], v[52:53], off
	s_waitcnt vmcnt(1) lgkmcnt(0)
	v_pk_mul_f32 v[40:41], v[40:41], v[44:45]
	s_waitcnt vmcnt(0)
	v_pk_mul_f32 v[36:37], v[36:37], v[48:49]
	v_pk_mul_f32 v[38:39], v[38:39], v[50:51]
	v_cvt_pk_bf16_f32 v36, v36, v37
	v_cvt_pk_bf16_f32 v37, v38, v39
	v_cvt_pk_bf16_f32 v38, v40, v41
	v_or_b32_e32 v40, 16, v54
	v_ashrrev_i32_e32 v41, 31, v40
	v_lshlrev_b64 v[40:41], 11, v[40:41]
	v_pk_mul_f32 v[42:43], v[42:43], v[46:47]
	v_lshl_add_u64 v[34:35], v[34:35], 0, v[40:41]
	v_cvt_pk_bf16_f32 v39, v42, v43
	v_lshl_add_u64 v[34:35], v[34:35], 0, v[98:99]
	global_store_dwordx4 v[34:35], v[36:39], off
	v_or_b32_e32 v42, 0x60, v149
	v_mul_hi_i32 v0, v42, s2
	v_lshrrev_b32_e32 v34, 31, v0
	v_ashrrev_i32_e32 v0, 13, v0
	v_add_u32_e32 v0, v0, v34
	v_mul_i32_i24_e32 v34, 0x4100, v0
	v_sub_u32_e32 v34, v42, v34
	v_mul_i32_i24_e32 v0, 0xc00, v0
	v_cmp_lt_i32_e32 vcc, s3, v34
	v_mov_b32_e32 v36, v179
	s_nop 0
	v_cndmask_b32_e32 v34, v162, v0, vcc
	v_and_b32_e32 v0, 31, v36
	v_bfe_u32 v37, v36, 5, 1
	v_mul_u32_u24_e32 v37, 0x240, v37
	v_lshlrev_b32_e32 v0, 2, v0
	v_add3_u32 v0, v145, v37, v0
	ds_write2_b32 v0, v18, v19 offset1:36
	ds_write2_b32 v0, v20, v21 offset0:72 offset1:108
	v_add_u32_e32 v18, 0x400, v0
	v_ashrrev_i32_e32 v35, 31, v34
	ds_write2_b32 v18, v22, v23 offset0:32 offset1:68
	ds_write2_b32 v18, v24, v25 offset0:104 offset1:140
	v_add_u32_e32 v18, 0x800, v0
	v_add_u32_e32 v0, 0xc00, v0
	ds_write2_b32 v18, v26, v27 offset0:64 offset1:100
	ds_write2_b32 v18, v28, v29 offset0:136 offset1:172
	ds_write2_b32 v0, v30, v31 offset0:96 offset1:132
	ds_write2_b32 v0, v32, v33 offset0:168 offset1:204
	v_lshl_add_u64 v[18:19], v[34:35], 2, s[26:27]
	v_lshlrev_b32_e32 v0, 3, v36
	v_lshl_add_u64 v[18:19], v[18:19], 0, s[4:5]
	v_and_b32_e32 v22, 24, v0
	v_lshl_add_u64 v[20:21], v[18:19], 0, v[116:117]
	v_lshlrev_b32_e32 v0, 2, v22
	v_bfe_u32 v40, v36, 2, 4
	v_lshl_add_u64 v[38:39], v[20:21], 0, v[0:1]
	v_lshlrev_b32_e32 v20, 1, v22
	v_mul_u32_u24_e32 v22, 0x90, v40
	s_waitcnt lgkmcnt(0)
	v_add3_u32 v0, v145, v0, v22
	ds_read_b128 v[22:25], v0
	ds_read_b128 v[26:29], v0 offset:16
	global_load_dwordx4 v[30:33], v[38:39], off offset:16
	global_load_dwordx4 v[34:37], v[38:39], off
	v_or_b32_e32 v40, v40, v42
	v_mov_b32_e32 v21, v1
	v_ashrrev_i32_e32 v41, 31, v40
	v_lshl_add_u64 v[20:21], v[114:115], 0, v[20:21]
	s_waitcnt vmcnt(1) lgkmcnt(0)
	v_pk_mul_f32 v[26:27], v[26:27], v[30:31]
	s_waitcnt vmcnt(0)
	v_pk_mul_f32 v[22:23], v[22:23], v[34:35]
	v_pk_mul_f32 v[24:25], v[24:25], v[36:37]
	v_pk_mul_f32 v[28:29], v[28:29], v[32:33]
	v_cvt_pk_bf16_f32 v22, v22, v23
	v_cvt_pk_bf16_f32 v23, v24, v25
	v_cvt_pk_bf16_f32 v24, v26, v27
	v_lshlrev_b64 v[26:27], 11, v[40:41]
	v_cvt_pk_bf16_f32 v25, v28, v29
	v_lshl_add_u64 v[26:27], v[20:21], 0, v[26:27]
	global_store_dwordx4 v[26:27], v[22:25], off
	ds_read_b128 v[22:25], v0 offset:2304
	ds_read_b128 v[26:29], v0 offset:2320
	global_load_dwordx4 v[30:33], v[38:39], off offset:16
	global_load_dwordx4 v[34:37], v[38:39], off
	s_waitcnt vmcnt(1) lgkmcnt(0)
	v_pk_mul_f32 v[26:27], v[26:27], v[30:31]
	s_waitcnt vmcnt(0)
	v_pk_mul_f32 v[22:23], v[22:23], v[34:35]
	v_pk_mul_f32 v[24:25], v[24:25], v[36:37]
	v_cvt_pk_bf16_f32 v22, v22, v23
	v_cvt_pk_bf16_f32 v23, v24, v25
	v_cvt_pk_bf16_f32 v24, v26, v27
	v_or_b32_e32 v26, 16, v40
	v_ashrrev_i32_e32 v27, 31, v26
	v_pk_mul_f32 v[28:29], v[28:29], v[32:33]
	v_lshlrev_b64 v[26:27], 11, v[26:27]
	v_cvt_pk_bf16_f32 v25, v28, v29
	v_lshl_add_u64 v[20:21], v[20:21], 0, v[26:27]
	global_store_dwordx4 v[20:21], v[22:25], off
	s_nop 1
	v_mov_b32_e32 v22, v179
	s_nop 0
	v_and_b32_e32 v0, 31, v22
	v_bfe_u32 v20, v22, 5, 1
	v_mul_u32_u24_e32 v20, 0x240, v20
	v_lshlrev_b32_e32 v0, 2, v0
	v_add3_u32 v0, v145, v20, v0
	ds_write2_b32 v0, v2, v3 offset1:36
	ds_write2_b32 v0, v4, v5 offset0:72 offset1:108
	v_add_u32_e32 v2, 0x400, v0
	ds_write2_b32 v2, v6, v7 offset0:32 offset1:68
	ds_write2_b32 v2, v8, v9 offset0:104 offset1:140
	v_add_u32_e32 v2, 0x800, v0
	v_add_u32_e32 v0, 0xc00, v0
	ds_write2_b32 v2, v10, v11 offset0:64 offset1:100
	ds_write2_b32 v2, v12, v13 offset0:136 offset1:172
	ds_write2_b32 v0, v14, v15 offset0:96 offset1:132
	ds_write2_b32 v0, v16, v17 offset0:168 offset1:204
	v_lshlrev_b32_e32 v0, 3, v22
	v_and_b32_e32 v4, 24, v0
	v_lshlrev_b32_e32 v0, 2, v4
	v_lshl_add_u64 v[2:3], v[18:19], 0, v[0:1]
	v_bfe_u32 v22, v22, 2, 4
	v_lshl_add_u64 v[20:21], v[2:3], 0, v[100:101]
	v_lshlrev_b32_e32 v2, 1, v4
	v_mul_u32_u24_e32 v4, 0x90, v22
	s_waitcnt lgkmcnt(0)
	v_add3_u32 v0, v145, v0, v4
	ds_read_b128 v[4:7], v0
	ds_read_b128 v[8:11], v0 offset:16
	global_load_dwordx4 v[12:15], v[20:21], off offset:16
	global_load_dwordx4 v[16:19], v[20:21], off
	v_or_b32_e32 v22, v22, v42
	v_mov_b32_e32 v3, v1
	v_ashrrev_i32_e32 v23, 31, v22
	v_lshl_add_u64 v[2:3], s[0:1], 0, v[2:3]
	s_waitcnt vmcnt(1) lgkmcnt(0)
	v_pk_mul_f32 v[8:9], v[8:9], v[12:13]
	s_waitcnt vmcnt(0)
	v_pk_mul_f32 v[4:5], v[4:5], v[16:17]
	v_pk_mul_f32 v[6:7], v[6:7], v[18:19]
	v_cvt_pk_bf16_f32 v4, v4, v5
	v_cvt_pk_bf16_f32 v5, v6, v7
	v_cvt_pk_bf16_f32 v6, v8, v9
	v_lshlrev_b64 v[8:9], 11, v[22:23]
	v_pk_mul_f32 v[10:11], v[10:11], v[14:15]
	v_lshl_add_u64 v[8:9], v[2:3], 0, v[8:9]
	v_cvt_pk_bf16_f32 v7, v10, v11
	v_lshl_add_u64 v[8:9], v[8:9], 0, v[98:99]
	global_store_dwordx4 v[8:9], v[4:7], off
	ds_read_b128 v[4:7], v0 offset:2304
	ds_read_b128 v[8:11], v0 offset:2320
	global_load_dwordx4 v[12:15], v[20:21], off offset:16
	global_load_dwordx4 v[16:19], v[20:21], off
	s_waitcnt vmcnt(1) lgkmcnt(0)
	v_pk_mul_f32 v[8:9], v[8:9], v[12:13]
	s_waitcnt vmcnt(0)
	v_pk_mul_f32 v[4:5], v[4:5], v[16:17]
	v_pk_mul_f32 v[6:7], v[6:7], v[18:19]
	v_cvt_pk_bf16_f32 v4, v4, v5
	v_cvt_pk_bf16_f32 v5, v6, v7
	v_cvt_pk_bf16_f32 v6, v8, v9
	v_or_b32_e32 v8, 16, v22
	v_ashrrev_i32_e32 v9, 31, v8
	v_lshlrev_b64 v[8:9], 11, v[8:9]
	v_pk_mul_f32 v[10:11], v[10:11], v[14:15]
	v_lshl_add_u64 v[2:3], v[2:3], 0, v[8:9]
	v_cvt_pk_bf16_f32 v7, v10, v11
	v_lshl_add_u64 v[2:3], v[2:3], 0, v[98:99]
	global_store_dwordx4 v[2:3], v[4:7], off
	s_add_i32 s7, s7, s6
	s_cmpk_gt_i32 s7, 0x207
	s_cselect_b64 s[0:1], -1, 0
	s_branch .LBB0_907

.LBB0_1120:
	s_add_i32 s2, s13, s14
	s_cmpk_gt_i32 s2, 0x81f
	s_mov_b64 s[0:1], -1
	s_cbranch_scc1 .LBB0_1119
	s_ashr_i32 s0, s2, 31
	s_lshr_b32 s0, s0, 25
	s_add_i32 s0, s2, s0
	s_ashr_i32 s1, s0, 7
	s_lshl_b32 s1, s1, 3
	s_sub_i32 s3, 0x82, s1
	s_min_u32 s3, s3, 8
	v_cvt_f32_ubyte0_e32 v0, s3
	v_rcp_iflag_f32_e32 v0, v0
	s_sub_i32 s6, 0, s3
	s_and_b32 s0, s0, 0xffffff80
	s_sub_i32 s0, s2, s0
	v_mul_f32_e32 v0, 0x4f7ffffe, v0
	v_cvt_u32_f32_e32 v0, v0
	s_abs_i32 s4, s0
	s_ashr_i32 s2, s0, 31
	s_waitcnt vmcnt(63) expcnt(7) lgkmcnt(15)
	v_readfirstlane_b32 s7, v0
	s_mul_i32 s6, s6, s7
	s_mul_hi_u32 s6, s7, s6
	s_add_i32 s7, s7, s6
	s_mul_hi_u32 s6, s4, s7
	s_mul_i32 s7, s6, s3
	s_sub_i32 s4, s4, s7
	s_add_i32 s7, s6, 1
	s_sub_i32 s8, s4, s3
	s_cmp_ge_u32 s4, s3
	s_cselect_b32 s6, s7, s6
	s_cselect_b32 s4, s8, s4
	s_add_i32 s7, s6, 1
	s_cmp_ge_u32 s4, s3
	s_cselect_b32 s4, s7, s6
	s_xor_b32 s4, s4, s2
	s_sub_i32 s4, s4, s2
	s_mul_i32 s2, s4, s3
	s_sub_i32 s0, s0, s2
	s_add_i32 s0, s0, s1
	s_lshl_b32 s0, s0, 8
	s_lshl_b32 s6, s4, 8
	s_ashr_i32 s1, s0, 31
	s_ashr_i32 s7, s6, 31
	s_lshl_b64 s[2:3], s[0:1], 11
	s_lshl_b64 s[8:9], s[6:7], 11
	s_add_u32 s10, s64, s2
	v_mov_b32_e32 v0, v143
	s_addc_u32 s11, s65, s3
	s_barrier
	v_readlane_b32 s16, v251, 2
	v_lshl_add_u64 v[2:3], v[0:1], 1, s[10:11]
	v_add_u32_e32 v0, 32, v158
	v_readlane_b32 s30, v251, 16
	v_readfirstlane_b32 s1, v0
	s_mov_b32 m0, s1
	v_mov_b32_e32 v0, v159
	global_load_lds_dwordx4 v[2:3], off
	v_readlane_b32 s17, v251, 3
	v_lshl_add_u64 v[2:3], v[0:1], 1, s[10:11]
	v_add_u32_e32 v0, 32, v160
	v_readlane_b32 s31, v251, 17
	v_readfirstlane_b32 s1, v0
	s_mov_b32 m0, s1
	v_mov_b32_e32 v0, v161
	global_load_lds_dwordx4 v[2:3], off
	s_add_u32 s16, s30, s8
	v_lshl_add_u64 v[2:3], v[0:1], 1, s[10:11]
	v_add_u32_e32 v0, 32, v162
	s_addc_u32 s17, s31, s9
	v_readfirstlane_b32 s1, v0
	s_mov_b32 m0, s1
	v_mov_b32_e32 v0, v163
	global_load_lds_dwordx4 v[2:3], off
	v_readlane_b32 s7, v254, 3
	v_lshl_add_u64 v[2:3], v[0:1], 1, s[10:11]
	v_add_u32_e32 v0, 32, v164
	s_mov_b32 s5, 0
	v_readfirstlane_b32 s1, v0
	s_mov_b32 m0, s1
	v_mov_b32_e32 v0, v143
	global_load_lds_dwordx4 v[2:3], off
	v_readlane_b32 s18, v251, 4
	v_lshl_add_u64 v[2:3], v[0:1], 1, s[16:17]
	v_add_u32_e32 v0, s7, v158
	v_readlane_b32 s19, v251, 5
	v_readfirstlane_b32 s1, v0
	s_mov_b32 m0, s1
	v_mov_b32_e32 v0, v159
	global_load_lds_dwordx4 v[2:3], off
	v_readlane_b32 s20, v251, 6
	v_lshl_add_u64 v[2:3], v[0:1], 1, s[16:17]
	v_add_u32_e32 v0, s7, v160
	v_readlane_b32 s21, v251, 7
	v_readfirstlane_b32 s1, v0
	s_mov_b32 m0, s1
	v_mov_b32_e32 v0, v161
	global_load_lds_dwordx4 v[2:3], off
	v_readlane_b32 s22, v251, 8
	v_lshl_add_u64 v[2:3], v[0:1], 1, s[16:17]
	v_add_u32_e32 v0, s7, v162
	v_readlane_b32 s23, v251, 9
	v_readfirstlane_b32 s1, v0
	s_mov_b32 m0, s1
	v_mov_b32_e32 v0, v163
	global_load_lds_dwordx4 v[2:3], off
	v_readlane_b32 s24, v251, 10
	v_lshl_add_u64 v[2:3], v[0:1], 1, s[16:17]
	v_add_u32_e32 v0, s7, v164
	v_readlane_b32 s25, v251, 11
	v_readfirstlane_b32 s1, v0
	s_mov_b32 m0, s1
	v_readlane_b32 s1, v253, 25
	global_load_lds_dwordx4 v[2:3], off
	s_add_u32 s1, s1, s2
	v_readlane_b32 s2, v253, 26
	s_waitcnt vmcnt(0)
	s_addc_u32 s7, s2, s3
	v_readlane_b32 s2, v253, 45
	s_add_u32 s8, s2, s8
	v_readlane_b32 s2, v253, 46
	v_mov_b32_e32 v2, 0
	s_addc_u32 s9, s2, s9
	s_mov_b64 s[2:3], 0
	v_mov_b32_e32 v3, v2
	v_mov_b32_e32 v4, v2
	v_mov_b32_e32 v5, v2
	v_mov_b32_e32 v6, v2
	v_mov_b32_e32 v7, v2
	v_mov_b32_e32 v8, v2
	v_mov_b32_e32 v9, v2
	v_mov_b32_e32 v10, v2
	v_mov_b32_e32 v11, v2
	v_mov_b32_e32 v12, v2
	v_mov_b32_e32 v13, v2
	s_waitcnt vmcnt(0)
	v_mov_b32_e32 v14, v2
	v_mov_b32_e32 v15, v2
	v_mov_b32_e32 v16, v2
	v_mov_b32_e32 v17, v2
	v_mov_b32_e32 v18, v2
	v_mov_b32_e32 v19, v2
	v_mov_b32_e32 v20, v2
	v_mov_b32_e32 v21, v2
	v_mov_b32_e32 v22, v2
	v_mov_b32_e32 v23, v2
	v_mov_b32_e32 v24, v2
	v_mov_b32_e32 v25, v2
	v_mov_b32_e32 v26, v2
	v_mov_b32_e32 v27, v2
	v_mov_b32_e32 v28, v2
	v_mov_b32_e32 v29, v2
	v_mov_b32_e32 v30, v2
	v_mov_b32_e32 v31, v2
	v_mov_b32_e32 v32, v2
	v_mov_b32_e32 v33, v2
	v_mov_b32_e32 v34, v2
	v_mov_b32_e32 v35, v2
	v_mov_b32_e32 v36, v2
	v_mov_b32_e32 v37, v2
	v_mov_b32_e32 v38, v2
	v_mov_b32_e32 v39, v2
	v_mov_b32_e32 v40, v2
	v_mov_b32_e32 v41, v2
	v_mov_b32_e32 v42, v2
	v_mov_b32_e32 v43, v2
	v_mov_b32_e32 v44, v2
	v_mov_b32_e32 v45, v2
	v_mov_b32_e32 v46, v2
	v_mov_b32_e32 v47, v2
	v_mov_b32_e32 v48, v2
	v_mov_b32_e32 v49, v2
	v_mov_b32_e32 v50, v2
	v_mov_b32_e32 v51, v2
	v_mov_b32_e32 v52, v2
	v_mov_b32_e32 v53, v2
	v_mov_b32_e32 v54, v2
	v_mov_b32_e32 v55, v2
	v_mov_b32_e32 v56, v2
	v_mov_b32_e32 v57, v2
	v_mov_b32_e32 v58, v2
	v_mov_b32_e32 v59, v2
	v_mov_b32_e32 v60, v2
	v_mov_b32_e32 v61, v2
	v_mov_b32_e32 v62, v2
	v_mov_b32_e32 v63, v2
	v_mov_b32_e32 v64, v2
	v_mov_b32_e32 v65, v2
	v_mov_b32_e32 v66, v2
	v_mov_b32_e32 v67, v2
	v_mov_b32_e32 v68, v2
	v_mov_b32_e32 v69, v2
	v_mov_b32_e32 v70, v2
	v_mov_b32_e32 v71, v2
	v_mov_b32_e32 v72, v2
	v_mov_b32_e32 v73, v2
	v_mov_b32_e32 v74, v2
	v_mov_b32_e32 v75, v2
	v_mov_b32_e32 v76, v2
	v_mov_b32_e32 v77, v2
	v_mov_b32_e32 v78, v2
	v_mov_b32_e32 v79, v2
	v_mov_b32_e32 v80, v2
	v_mov_b32_e32 v81, v2
	v_mov_b32_e32 v82, v2
	v_mov_b32_e32 v83, v2
	v_mov_b32_e32 v84, v2
	v_mov_b32_e32 v85, v2
	v_mov_b32_e32 v86, v2
	v_mov_b32_e32 v87, v2
	v_mov_b32_e32 v88, v2
	v_mov_b32_e32 v89, v2
	v_mov_b32_e32 v90, v2
	v_mov_b32_e32 v91, v2
	v_mov_b32_e32 v92, v2
	v_mov_b32_e32 v93, v2
	v_mov_b32_e32 v94, v2
	v_mov_b32_e32 v95, v2
	v_mov_b32_e32 v96, v2
	v_mov_b32_e32 v97, v2
	v_mov_b32_e32 v98, v2
	v_mov_b32_e32 v99, v2
	v_mov_b32_e32 v100, v2
	v_mov_b32_e32 v101, v2
	v_mov_b32_e32 v102, v2
	v_mov_b32_e32 v103, v2
	v_mov_b32_e32 v104, v2
	v_mov_b32_e32 v105, v2
	v_mov_b32_e32 v106, v2
	v_mov_b32_e32 v107, v2
	v_mov_b32_e32 v108, v2
	v_mov_b32_e32 v109, v2
	v_mov_b32_e32 v110, v2
	v_mov_b32_e32 v111, v2
	v_mov_b32_e32 v112, v2
	v_mov_b32_e32 v113, v2
	v_mov_b32_e32 v114, v2
	v_mov_b32_e32 v115, v2
	v_mov_b32_e32 v116, v2
	v_mov_b32_e32 v117, v2
	v_mov_b32_e32 v118, v2
	v_mov_b32_e32 v119, v2
	v_mov_b32_e32 v120, v2
	v_mov_b32_e32 v121, v2
	v_mov_b32_e32 v122, v2
	v_mov_b32_e32 v123, v2
	v_mov_b32_e32 v124, v2
	v_mov_b32_e32 v125, v2
	v_mov_b32_e32 v126, v2
	v_mov_b32_e32 v127, v2
	v_mov_b32_e32 v128, v2
	v_mov_b32_e32 v129, v2
	v_readlane_b32 s26, v251, 12
	v_readlane_b32 s27, v251, 13
	v_readlane_b32 s28, v251, 14
	v_readlane_b32 s29, v251, 15
	s_waitcnt lgkmcnt(0)
	s_barrier
	v_lshlrev_b32_e32 v142, 1, v143
	v_readfirstlane_b32 s15, v158
	v_add_u32_e32 v156, v165, v167
	v_add_u32_e32 v195, v166, v167
	v_add_u32_e32 v157, v165, v172
	v_add_u32_e32 v200, v166, v172
	v_add_u32_e32 v193, v165, v173
	v_add_u32_e32 v201, v166, v173
	v_add_u32_e32 v194, v165, v174
	v_add_u32_e32 v202, v166, v174
	s_nop 1
	s_add_u32 m0, s15, 0x8020
	s_add_u32 s10, s1, s2
	s_addc_u32 s11, s7, s3
	global_load_lds_dwordx4 v142, s[10:11]
	s_add_u32 m0, s15, 0xa020
	s_add_u32 s10, s10, 0x20000
	s_addc_u32 s11, s11, 0
	global_load_lds_dwordx4 v142, s[10:11]
	s_add_u32 m0, s15, 0xc020
	s_add_u32 s10, s10, 0x20000
	s_addc_u32 s11, s11, 0
	global_load_lds_dwordx4 v142, s[10:11]
	s_add_u32 m0, s15, 0xe020
	s_add_u32 s10, s10, 0x20000
	s_addc_u32 s11, s11, 0
	global_load_lds_dwordx4 v142, s[10:11]
	s_add_u32 m0, s15, 0x18020
	s_add_u32 s10, s8, s2
	s_addc_u32 s11, s9, s3
	global_load_lds_dwordx4 v142, s[10:11]
	s_add_u32 m0, s15, 0x1a020
	s_add_u32 s10, s10, 0x20000
	s_addc_u32 s11, s11, 0
	global_load_lds_dwordx4 v142, s[10:11]
	s_add_u32 m0, s15, 0x1c020
	s_add_u32 s10, s10, 0x20000
	s_addc_u32 s11, s11, 0
	global_load_lds_dwordx4 v142, s[10:11]
	s_add_u32 m0, s15, 0x1e020
	s_add_u32 s10, s10, 0x20000
	s_addc_u32 s11, s11, 0
	global_load_lds_dwordx4 v142, s[10:11]
	s_add_u32 s2, s2, 0x80
	s_addc_u32 s3, s3, 0
	ds_read_b128 v[130:133], v156 offset:0
	ds_read_b128 v[148:151], v195 offset:0
	ds_read_b128 v[152:155], v195 offset:4096
	ds_read_b128 v[134:137], v156 offset:4096
	ds_read_b128 v[138:141], v156 offset:8192
	ds_read_b128 v[144:147], v156 offset:12288
.Lg1122_loop:
	s_waitcnt lgkmcnt(4)
	v_mfma_f32_32x32x16_bf16 v[114:129], v[130:133], v[148:151], v[114:129]
	ds_read_b128 v[180:183], v157 offset:0
	s_waitcnt lgkmcnt(4)
	v_mfma_f32_32x32x16_bf16 v[98:113], v[130:133], v[152:155], v[98:113]
	ds_read_b128 v[226:229], v200 offset:0
	s_waitcnt lgkmcnt(4)
	v_mfma_f32_32x32x16_bf16 v[82:97], v[134:137], v[148:151], v[82:97]
	ds_read_b128 v[230:233], v200 offset:4096
	v_mfma_f32_32x32x16_bf16 v[66:81], v[134:137], v[152:155], v[66:81]
	ds_read_b128 v[184:187], v157 offset:4096
	s_waitcnt lgkmcnt(5)
	v_mfma_f32_32x32x16_bf16 v[50:65], v[138:141], v[148:151], v[50:65]
	ds_read_b128 v[188:191], v157 offset:8192
	v_mfma_f32_32x32x16_bf16 v[34:49], v[138:141], v[152:155], v[34:49]
	ds_read_b128 v[222:225], v157 offset:12288
	s_waitcnt lgkmcnt(6)
	v_mfma_f32_32x32x16_bf16 v[18:33], v[144:147], v[148:151], v[18:33]
	v_mfma_f32_32x32x16_bf16 v[2:17], v[144:147], v[152:155], v[2:17]
	s_waitcnt lgkmcnt(4)
	v_mfma_f32_32x32x16_bf16 v[114:129], v[180:183], v[226:229], v[114:129]
	ds_read_b128 v[130:133], v193 offset:0
	s_waitcnt lgkmcnt(4)
	v_mfma_f32_32x32x16_bf16 v[98:113], v[180:183], v[230:233], v[98:113]
	ds_read_b128 v[148:151], v201 offset:0
	s_waitcnt lgkmcnt(4)
	v_mfma_f32_32x32x16_bf16 v[82:97], v[184:187], v[226:229], v[82:97]
	ds_read_b128 v[152:155], v201 offset:4096
	v_mfma_f32_32x32x16_bf16 v[66:81], v[184:187], v[230:233], v[66:81]
	ds_read_b128 v[134:137], v193 offset:4096
	s_waitcnt lgkmcnt(5)
	v_mfma_f32_32x32x16_bf16 v[50:65], v[188:191], v[226:229], v[50:65]
	ds_read_b128 v[138:141], v193 offset:8192
	v_mfma_f32_32x32x16_bf16 v[34:49], v[188:191], v[230:233], v[34:49]
	ds_read_b128 v[144:147], v193 offset:12288
	s_waitcnt lgkmcnt(6)
	v_mfma_f32_32x32x16_bf16 v[18:33], v[222:225], v[226:229], v[18:33]
	v_mfma_f32_32x32x16_bf16 v[2:17], v[222:225], v[230:233], v[2:17]
	s_waitcnt lgkmcnt(4)
	v_mfma_f32_32x32x16_bf16 v[114:129], v[130:133], v[148:151], v[114:129]
	ds_read_b128 v[180:183], v194 offset:0
	ds_read_b128 v[226:229], v202 offset:0
	s_waitcnt lgkmcnt(5)
	v_mfma_f32_32x32x16_bf16 v[98:113], v[130:133], v[152:155], v[98:113]
	ds_read_b128 v[230:233], v202 offset:4096
	ds_read_b128 v[184:187], v194 offset:4096
	s_waitcnt lgkmcnt(6)
	v_mfma_f32_32x32x16_bf16 v[82:97], v[134:137], v[148:151], v[82:97]
	ds_read_b128 v[188:191], v194 offset:8192
	ds_read_b128 v[222:225], v194 offset:12288
	v_mfma_f32_32x32x16_bf16 v[66:81], v[134:137], v[152:155], v[66:81]
	s_waitcnt lgkmcnt(7)
	v_mfma_f32_32x32x16_bf16 v[50:65], v[138:141], v[148:151], v[50:65]
	v_mfma_f32_32x32x16_bf16 v[34:49], v[138:141], v[152:155], v[34:49]
	s_waitcnt lgkmcnt(6)
	v_mfma_f32_32x32x16_bf16 v[18:33], v[144:147], v[148:151], v[18:33]
	v_mfma_f32_32x32x16_bf16 v[2:17], v[144:147], v[152:155], v[2:17]
	s_waitcnt vmcnt(0) lgkmcnt(0)
	s_barrier
	s_cmp_lt_u32 s2, 0x780
	s_cbranch_scc0 .Lg1122_nodma0
	v_mfma_f32_32x32x16_bf16 v[114:129], v[180:183], v[226:229], v[114:129]
	ds_read_b128 v[130:133], v156 offset:32768
	s_add_u32 m0, s15, 0x20
	s_add_u32 s10, s1, s2
	s_addc_u32 s11, s7, s3
	global_load_lds_dwordx4 v142, s[10:11]
	v_mfma_f32_32x32x16_bf16 v[98:113], v[180:183], v[230:233], v[98:113]
	ds_read_b128 v[148:151], v195 offset:32768
	s_add_u32 m0, s15, 0x2020
	s_add_u32 s10, s10, 0x20000
	s_addc_u32 s11, s11, 0
	global_load_lds_dwordx4 v142, s[10:11]
	v_mfma_f32_32x32x16_bf16 v[82:97], v[184:187], v[226:229], v[82:97]
	ds_read_b128 v[152:155], v195 offset:36864
	s_add_u32 m0, s15, 0x4020
	s_add_u32 s10, s10, 0x20000
	s_addc_u32 s11, s11, 0
	global_load_lds_dwordx4 v142, s[10:11]
	v_mfma_f32_32x32x16_bf16 v[66:81], v[184:187], v[230:233], v[66:81]
	ds_read_b128 v[134:137], v156 offset:36864
	s_add_u32 m0, s15, 0x6020
	s_add_u32 s10, s10, 0x20000
	s_addc_u32 s11, s11, 0
	global_load_lds_dwordx4 v142, s[10:11]
	v_mfma_f32_32x32x16_bf16 v[50:65], v[188:191], v[226:229], v[50:65]
	ds_read_b128 v[138:141], v156 offset:40960
	s_add_u32 m0, s15, 0x10020
	s_add_u32 s10, s8, s2
	s_addc_u32 s11, s9, s3
	global_load_lds_dwordx4 v142, s[10:11]
	v_mfma_f32_32x32x16_bf16 v[34:49], v[188:191], v[230:233], v[34:49]
	ds_read_b128 v[144:147], v156 offset:45056
	s_add_u32 m0, s15, 0x12020
	s_add_u32 s10, s10, 0x20000
	s_addc_u32 s11, s11, 0
	global_load_lds_dwordx4 v142, s[10:11]
	v_mfma_f32_32x32x16_bf16 v[18:33], v[222:225], v[226:229], v[18:33]
	s_add_u32 m0, s15, 0x14020
	s_add_u32 s10, s10, 0x20000
	s_addc_u32 s11, s11, 0
	global_load_lds_dwordx4 v142, s[10:11]
	v_mfma_f32_32x32x16_bf16 v[2:17], v[222:225], v[230:233], v[2:17]
	s_add_u32 m0, s15, 0x16020
	s_add_u32 s10, s10, 0x20000
	s_addc_u32 s11, s11, 0
	global_load_lds_dwordx4 v142, s[10:11]
	s_add_u32 s2, s2, 0x80
	s_addc_u32 s3, s3, 0
	s_branch .Lg1122_join0
.Lg1122_nodma0:
	s_add_u32 s2, s2, 0x80
	s_addc_u32 s3, s3, 0
	v_mfma_f32_32x32x16_bf16 v[114:129], v[180:183], v[226:229], v[114:129]
	ds_read_b128 v[130:133], v156 offset:32768
	v_mfma_f32_32x32x16_bf16 v[98:113], v[180:183], v[230:233], v[98:113]
	ds_read_b128 v[148:151], v195 offset:32768
	v_mfma_f32_32x32x16_bf16 v[82:97], v[184:187], v[226:229], v[82:97]
	ds_read_b128 v[152:155], v195 offset:36864
	v_mfma_f32_32x32x16_bf16 v[66:81], v[184:187], v[230:233], v[66:81]
	ds_read_b128 v[134:137], v156 offset:36864
	v_mfma_f32_32x32x16_bf16 v[50:65], v[188:191], v[226:229], v[50:65]
	ds_read_b128 v[138:141], v156 offset:40960
	v_mfma_f32_32x32x16_bf16 v[34:49], v[188:191], v[230:233], v[34:49]
	ds_read_b128 v[144:147], v156 offset:45056
	v_mfma_f32_32x32x16_bf16 v[18:33], v[222:225], v[226:229], v[18:33]
	v_mfma_f32_32x32x16_bf16 v[2:17], v[222:225], v[230:233], v[2:17]
.Lg1122_join0:
	s_waitcnt lgkmcnt(4)
	v_mfma_f32_32x32x16_bf16 v[114:129], v[130:133], v[148:151], v[114:129]
	ds_read_b128 v[180:183], v157 offset:32768
	s_waitcnt lgkmcnt(4)
	v_mfma_f32_32x32x16_bf16 v[98:113], v[130:133], v[152:155], v[98:113]
	ds_read_b128 v[226:229], v200 offset:32768
	s_waitcnt lgkmcnt(4)
	v_mfma_f32_32x32x16_bf16 v[82:97], v[134:137], v[148:151], v[82:97]
	ds_read_b128 v[230:233], v200 offset:36864
	v_mfma_f32_32x32x16_bf16 v[66:81], v[134:137], v[152:155], v[66:81]
	ds_read_b128 v[184:187], v157 offset:36864
	s_waitcnt lgkmcnt(5)
	v_mfma_f32_32x32x16_bf16 v[50:65], v[138:141], v[148:151], v[50:65]
	ds_read_b128 v[188:191], v157 offset:40960
	v_mfma_f32_32x32x16_bf16 v[34:49], v[138:141], v[152:155], v[34:49]
	ds_read_b128 v[222:225], v157 offset:45056
	s_waitcnt lgkmcnt(6)
	v_mfma_f32_32x32x16_bf16 v[18:33], v[144:147], v[148:151], v[18:33]
	v_mfma_f32_32x32x16_bf16 v[2:17], v[144:147], v[152:155], v[2:17]
	s_waitcnt lgkmcnt(4)
	v_mfma_f32_32x32x16_bf16 v[114:129], v[180:183], v[226:229], v[114:129]
	ds_read_b128 v[130:133], v193 offset:32768
	s_waitcnt lgkmcnt(4)
	v_mfma_f32_32x32x16_bf16 v[98:113], v[180:183], v[230:233], v[98:113]
	ds_read_b128 v[148:151], v201 offset:32768
	s_waitcnt lgkmcnt(4)
	v_mfma_f32_32x32x16_bf16 v[82:97], v[184:187], v[226:229], v[82:97]
	ds_read_b128 v[152:155], v201 offset:36864
	v_mfma_f32_32x32x16_bf16 v[66:81], v[184:187], v[230:233], v[66:81]
	ds_read_b128 v[134:137], v193 offset:36864
	s_waitcnt lgkmcnt(5)
	v_mfma_f32_32x32x16_bf16 v[50:65], v[188:191], v[226:229], v[50:65]
	ds_read_b128 v[138:141], v193 offset:40960
	v_mfma_f32_32x32x16_bf16 v[34:49], v[188:191], v[230:233], v[34:49]
	ds_read_b128 v[144:147], v193 offset:45056
	s_waitcnt lgkmcnt(6)
	v_mfma_f32_32x32x16_bf16 v[18:33], v[222:225], v[226:229], v[18:33]
	v_mfma_f32_32x32x16_bf16 v[2:17], v[222:225], v[230:233], v[2:17]
	s_waitcnt lgkmcnt(4)
	v_mfma_f32_32x32x16_bf16 v[114:129], v[130:133], v[148:151], v[114:129]
	ds_read_b128 v[180:183], v194 offset:32768
	ds_read_b128 v[226:229], v202 offset:32768
	s_waitcnt lgkmcnt(5)
	v_mfma_f32_32x32x16_bf16 v[98:113], v[130:133], v[152:155], v[98:113]
	ds_read_b128 v[230:233], v202 offset:36864
	ds_read_b128 v[184:187], v194 offset:36864
	s_waitcnt lgkmcnt(6)
	v_mfma_f32_32x32x16_bf16 v[82:97], v[134:137], v[148:151], v[82:97]
	ds_read_b128 v[188:191], v194 offset:40960
	ds_read_b128 v[222:225], v194 offset:45056
	v_mfma_f32_32x32x16_bf16 v[66:81], v[134:137], v[152:155], v[66:81]
	s_waitcnt lgkmcnt(7)
	v_mfma_f32_32x32x16_bf16 v[50:65], v[138:141], v[148:151], v[50:65]
	v_mfma_f32_32x32x16_bf16 v[34:49], v[138:141], v[152:155], v[34:49]
	s_waitcnt lgkmcnt(6)
	v_mfma_f32_32x32x16_bf16 v[18:33], v[144:147], v[148:151], v[18:33]
	v_mfma_f32_32x32x16_bf16 v[2:17], v[144:147], v[152:155], v[2:17]
	s_waitcnt vmcnt(0) lgkmcnt(0)
	s_barrier
	s_cmp_lt_u32 s2, 0x780
	s_cbranch_scc0 .Lg1122_nodma1
	v_mfma_f32_32x32x16_bf16 v[114:129], v[180:183], v[226:229], v[114:129]
	ds_read_b128 v[130:133], v156 offset:0
	s_add_u32 m0, s15, 0x8020
	s_add_u32 s10, s1, s2
	s_addc_u32 s11, s7, s3
	global_load_lds_dwordx4 v142, s[10:11]
	v_mfma_f32_32x32x16_bf16 v[98:113], v[180:183], v[230:233], v[98:113]
	ds_read_b128 v[148:151], v195 offset:0
	s_add_u32 m0, s15, 0xa020
	s_add_u32 s10, s10, 0x20000
	s_addc_u32 s11, s11, 0
	global_load_lds_dwordx4 v142, s[10:11]
	v_mfma_f32_32x32x16_bf16 v[82:97], v[184:187], v[226:229], v[82:97]
	ds_read_b128 v[152:155], v195 offset:4096
	s_add_u32 m0, s15, 0xc020
	s_add_u32 s10, s10, 0x20000
	s_addc_u32 s11, s11, 0
	global_load_lds_dwordx4 v142, s[10:11]
	v_mfma_f32_32x32x16_bf16 v[66:81], v[184:187], v[230:233], v[66:81]
	ds_read_b128 v[134:137], v156 offset:4096
	s_add_u32 m0, s15, 0xe020
	s_add_u32 s10, s10, 0x20000
	s_addc_u32 s11, s11, 0
	global_load_lds_dwordx4 v142, s[10:11]
	v_mfma_f32_32x32x16_bf16 v[50:65], v[188:191], v[226:229], v[50:65]
	ds_read_b128 v[138:141], v156 offset:8192
	s_add_u32 m0, s15, 0x18020
	s_add_u32 s10, s8, s2
	s_addc_u32 s11, s9, s3
	global_load_lds_dwordx4 v142, s[10:11]
	v_mfma_f32_32x32x16_bf16 v[34:49], v[188:191], v[230:233], v[34:49]
	ds_read_b128 v[144:147], v156 offset:12288
	s_add_u32 m0, s15, 0x1a020
	s_add_u32 s10, s10, 0x20000
	s_addc_u32 s11, s11, 0
	global_load_lds_dwordx4 v142, s[10:11]
	v_mfma_f32_32x32x16_bf16 v[18:33], v[222:225], v[226:229], v[18:33]
	s_add_u32 m0, s15, 0x1c020
	s_add_u32 s10, s10, 0x20000
	s_addc_u32 s11, s11, 0
	global_load_lds_dwordx4 v142, s[10:11]
	v_mfma_f32_32x32x16_bf16 v[2:17], v[222:225], v[230:233], v[2:17]
	s_add_u32 m0, s15, 0x1e020
	s_add_u32 s10, s10, 0x20000
	s_addc_u32 s11, s11, 0
	global_load_lds_dwordx4 v142, s[10:11]
	s_add_u32 s2, s2, 0x80
	s_addc_u32 s3, s3, 0
	s_branch .Lg1122_join1
.Lg1122_nodma1:
	s_add_u32 s2, s2, 0x80
	s_addc_u32 s3, s3, 0
	v_mfma_f32_32x32x16_bf16 v[114:129], v[180:183], v[226:229], v[114:129]
	ds_read_b128 v[130:133], v156 offset:0
	v_mfma_f32_32x32x16_bf16 v[98:113], v[180:183], v[230:233], v[98:113]
	ds_read_b128 v[148:151], v195 offset:0
	v_mfma_f32_32x32x16_bf16 v[82:97], v[184:187], v[226:229], v[82:97]
	ds_read_b128 v[152:155], v195 offset:4096
	v_mfma_f32_32x32x16_bf16 v[66:81], v[184:187], v[230:233], v[66:81]
	ds_read_b128 v[134:137], v156 offset:4096
	v_mfma_f32_32x32x16_bf16 v[50:65], v[188:191], v[226:229], v[50:65]
	ds_read_b128 v[138:141], v156 offset:8192
	v_mfma_f32_32x32x16_bf16 v[34:49], v[188:191], v[230:233], v[34:49]
	ds_read_b128 v[144:147], v156 offset:12288
	v_mfma_f32_32x32x16_bf16 v[18:33], v[222:225], v[226:229], v[18:33]
	v_mfma_f32_32x32x16_bf16 v[2:17], v[222:225], v[230:233], v[2:17]
.Lg1122_join1:
	s_cmp_lt_u32 s2, 0x880
	s_cbranch_scc1 .Lg1122_loop
	s_waitcnt lgkmcnt(0)
	v_add_u32_e32 v180, s0, v168
	s_and_b32 s0, s4, 0x7ffffe
	s_mov_b32 s4, 0x7e07e07f
	v_mul_hi_i32 v0, v180, s4
	v_lshrrev_b32_e32 v130, 31, v0
	v_ashrrev_i32_e32 v0, 13, v0
	s_cmp_eq_u32 s0, 12
	v_add_u32_e32 v182, v0, v130
	s_waitcnt vmcnt(0)
	s_cselect_b64 s[2:3], -1, 0
	s_cmp_lg_u32 s0, 12
	v_mul_i32_i24_e32 v0, 0x4100, v182
	v_or_b32_e32 v138, s6, v169
	s_movk_i32 s4, 0x5ff
	s_cselect_b64 s[0:1], -1, 0
	v_sub_u32_e32 v140, v180, v0
	v_mov_b32_e32 v184, v179
	v_cmp_lt_i32_e64 s[52:53], s4, v138
	s_barrier
	v_lshl_or_b32 v181, v182, 3, v171
	v_ashrrev_i32_e32 v141, 31, v140
	s_and_b64 s[10:11], s[0:1], s[52:53]
	v_and_b32_e32 v183, 63, v184
	v_and_b32_e32 v0, 31, v184
	v_bfe_u32 v133, v184, 5, 1
	s_and_saveexec_b64 s[0:1], s[10:11]
	s_xor_b64 s[8:9], exec, s[0:1]
	s_cbranch_execz .LBB0_1136
	s_add_i32 s4, s6, 0xfffff200
	v_mul_u32_u24_e32 v130, 0x90, v133
	s_mov_b64 s[0:1], -1
	s_cmp_gt_u32 s4, 0xfffff9ff
	v_lshlrev_b32_e32 v139, 2, v0
	v_lshlrev_b32_e32 v185, 2, v130
	s_cbranch_scc0 .LBB0_1134
	v_add3_u32 v0, v170, v185, v139
	ds_write_b32 v0, v114
	v_add3_u32 v0, v170, v139, v185
	v_add_u32_e32 v130, 0x100, v0
	ds_write2_b32 v130, v117, v118 offset0:44 offset1:224
	v_add_u32_e32 v130, 0x400, v0
	ds_write2_b32 v130, v119, v120 offset0:68 offset1:104
	v_add_u32_e32 v130, 0x600, v0
	ds_write2_b32 v130, v121, v122 offset0:12 offset1:192
	v_add_u32_e32 v130, 0x800, v0
	ds_write2_b32 v130, v123, v124 offset0:100 offset1:136
	v_add_u32_e32 v130, 0xa00, v0
	ds_write2_b32 v130, v125, v126 offset0:44 offset1:224
	v_add_u32_e32 v130, 0xc00, v0
	s_cmpk_lt_u32 s6, 0xa00
	ds_write2_b32 v0, v115, v116 offset0:36 offset1:72
	ds_write2_b32 v130, v127, v128 offset0:132 offset1:168
	ds_write_b32 v0, v129 offset:3888
	s_cselect_b64 s[0:1], -1, 0
	v_mov_b32_e32 v0, 0x3e38aa3b
	v_cndmask_b32_e64 v142, 1.0, v0, s[0:1]
	v_lshlrev_b32_e32 v0, 3, v184
	v_lshrrev_b32_e32 v188, 2, v183
	s_movk_i32 s4, 0x90
	v_and_b32_e32 v187, 24, v0
	v_mad_u32_u24 v147, v188, s4, v170
	s_waitcnt lgkmcnt(0)
	v_lshl_add_u32 v130, v187, 2, v147
	ds_read_b128 v[134:137], v130
	ds_read_b128 v[130:133], v130 offset:16
	v_and_b32_e32 v144, 2, v184
	v_or_b32_e32 v150, v188, v140
	s_movk_i32 s4, 0x100
	v_cmp_eq_u32_e32 vcc, 0, v144
	v_cmp_gt_i32_e64 s[4:5], s4, v150
	s_and_saveexec_b64 s[16:17], s[4:5]
	s_xor_b64 s[4:5], exec, s[16:17]
	s_cbranch_execz .LBB0_1127
	s_waitcnt lgkmcnt(1)
	v_pk_mul_f32 v[152:153], v[142:143], v[134:135] op_sel_hi:[0,1]
	v_pk_mul_f32 v[154:155], v[142:143], v[136:137] op_sel_hi:[0,1]
	s_waitcnt lgkmcnt(0)
	v_pk_mul_f32 v[156:157], v[142:143], v[130:131] op_sel_hi:[0,1]
	v_mul_f32_e32 v145, v142, v132
